# removed the adjacent s_setprio 0 / s_setprio 1 pairs between the two 16-MFMA blocks of every GEMM sub-phase (40 sites), on top of pipelined attention + final-norm wait
# baseline (speedup 1.0000x reference)
.LBB0_253:
	s_add_i32 s82, s18, 2
	s_cmp_eq_u32 s70, s18
	s_cselect_b32 s18, s49, s78
	s_cselect_b32 s19, s47, s79
	s_cselect_b32 s56, s73, s80
	s_cselect_b32 s57, s72, s81
	s_add_u32 s26, s18, 0x80
	s_addc_u32 s27, s19, 0
	s_add_i32 s83, 0, 0x10000
	v_add_u32_e32 v0, s83, v213
	s_add_i32 s86, 0, 0x14000
	ds_read_b128 v[130:133], v0
	ds_read_b128 v[134:137], v0 offset:1024
	ds_read_b128 v[138:141], v0 offset:2048
	ds_read_b128 v[142:145], v0 offset:3072
	v_add_u32_e32 v0, s86, v213
	ds_read_b128 v[146:149], v0
	ds_read_b128 v[150:153], v0 offset:1024
	ds_read_b128 v[154:157], v0 offset:2048
	ds_read_b128 v[158:161], v0 offset:3072
	s_add_u32 s84, s78, 0x3ff80
	s_addc_u32 s85, s79, 0
	ds_read_b128 v[162:165], v216
	ds_read_b128 v[166:169], v216 offset:1024
	ds_read_b128 v[194:197], v216 offset:2048
	ds_read_b128 v[198:201], v216 offset:3072
	ds_read_b128 v[202:205], v216 offset:4096
	ds_read_b128 v[206:209], v216 offset:5120
	ds_read_b128 v[218:221], v216 offset:6144
	ds_read_b128 v[222:225], v216 offset:7168
	s_add_i32 m0, s40, 0xc000
	v_lshl_add_u64 v[210:211], s[84:85], 0, v[172:173]
	global_load_lds_dwordx4 v[210:211], off
	v_lshl_add_u64 v[210:211], s[84:85], 0, v[170:171]
	s_add_i32 m0, s40, 0xe000
	s_nop 0
	global_load_lds_dwordx4 v[210:211], off
	s_waitcnt vmcnt(8)
	s_waitcnt lgkmcnt(0)
	s_barrier
	s_setprio 1
	s_waitcnt lgkmcnt(0)
	v_mfma_f32_16x16x32_bf16 v[126:129], v[130:133], v[162:165], v[126:129]
	v_mfma_f32_16x16x32_bf16 v[122:125], v[138:141], v[162:165], v[122:125]
	v_mfma_f32_16x16x32_bf16 v[110:113], v[130:133], v[194:197], v[110:113]
	v_mfma_f32_16x16x32_bf16 v[106:109], v[138:141], v[194:197], v[106:109]
	v_mfma_f32_16x16x32_bf16 v[94:97], v[130:133], v[202:205], v[94:97]
	v_mfma_f32_16x16x32_bf16 v[90:93], v[138:141], v[202:205], v[90:93]
	v_mfma_f32_16x16x32_bf16 v[78:81], v[130:133], v[218:221], v[78:81]
	v_mfma_f32_16x16x32_bf16 v[74:77], v[138:141], v[218:221], v[74:77]
	v_mfma_f32_16x16x32_bf16 v[126:129], v[134:137], v[166:169], v[126:129]
	v_mfma_f32_16x16x32_bf16 v[122:125], v[142:145], v[166:169], v[122:125]
	v_mfma_f32_16x16x32_bf16 v[110:113], v[134:137], v[198:201], v[110:113]
	v_mfma_f32_16x16x32_bf16 v[106:109], v[142:145], v[198:201], v[106:109]
	v_mfma_f32_16x16x32_bf16 v[94:97], v[134:137], v[206:209], v[94:97]
	v_mfma_f32_16x16x32_bf16 v[90:93], v[142:145], v[206:209], v[90:93]
	v_mfma_f32_16x16x32_bf16 v[78:81], v[134:137], v[222:225], v[78:81]
	v_mfma_f32_16x16x32_bf16 v[74:77], v[142:145], v[222:225], v[74:77]
	v_mfma_f32_16x16x32_bf16 v[118:121], v[146:149], v[162:165], v[118:121]
	v_mfma_f32_16x16x32_bf16 v[114:117], v[154:157], v[162:165], v[114:117]
	v_mfma_f32_16x16x32_bf16 v[102:105], v[146:149], v[194:197], v[102:105]
	v_mfma_f32_16x16x32_bf16 v[98:101], v[154:157], v[194:197], v[98:101]
	v_mfma_f32_16x16x32_bf16 v[86:89], v[146:149], v[202:205], v[86:89]
	v_mfma_f32_16x16x32_bf16 v[82:85], v[154:157], v[202:205], v[82:85]
	v_mfma_f32_16x16x32_bf16 v[70:73], v[146:149], v[218:221], v[70:73]
	v_mfma_f32_16x16x32_bf16 v[66:69], v[154:157], v[218:221], v[66:69]
	v_mfma_f32_16x16x32_bf16 v[118:121], v[150:153], v[166:169], v[118:121]
	v_mfma_f32_16x16x32_bf16 v[114:117], v[158:161], v[166:169], v[114:117]
	v_mfma_f32_16x16x32_bf16 v[102:105], v[150:153], v[198:201], v[102:105]
	v_mfma_f32_16x16x32_bf16 v[98:101], v[158:161], v[198:201], v[98:101]
	v_mfma_f32_16x16x32_bf16 v[86:89], v[150:153], v[206:209], v[86:89]
	v_mfma_f32_16x16x32_bf16 v[82:85], v[158:161], v[206:209], v[82:85]
	v_mfma_f32_16x16x32_bf16 v[70:73], v[150:153], v[222:225], v[70:73]
	v_mfma_f32_16x16x32_bf16 v[66:69], v[158:161], v[222:225], v[66:69]
	s_setprio 0
	s_barrier
	s_mov_b64 s[84:85], s[56:57]
	s_add_i32 s83, s83, s25
	ds_read_b128 v[162:165], v216 offset:16384
	ds_read_b128 v[166:169], v216 offset:17408
	ds_read_b128 v[194:197], v216 offset:18432
	ds_read_b128 v[198:201], v216 offset:19456
	ds_read_b128 v[202:205], v216 offset:20480
	ds_read_b128 v[206:209], v216 offset:21504
	ds_read_b128 v[218:221], v216 offset:22528
	ds_read_b128 v[222:225], v216 offset:23552
	s_mov_b32 m0, s83
	v_lshl_add_u64 v[210:211], s[84:85], 0, v[172:173]
	global_load_lds_dwordx4 v[210:211], off
	s_add_i32 m0, s83, 0x2000
	v_lshl_add_u64 v[210:211], s[84:85], 0, v[170:171]
	s_add_u32 s84, s56, 0x40000
	s_addc_u32 s85, s57, 0
	s_add_i32 s83, s86, s25
	global_load_lds_dwordx4 v[210:211], off
	s_mov_b32 m0, s83
	v_lshl_add_u64 v[210:211], s[84:85], 0, v[172:173]
	global_load_lds_dwordx4 v[210:211], off
	v_lshl_add_u64 v[210:211], s[84:85], 0, v[170:171]
	s_add_i32 m0, s83, 0x2000
	s_mov_b64 s[84:85], s[18:19]
	global_load_lds_dwordx4 v[210:211], off
	s_mov_b32 m0, s40
	v_lshl_add_u64 v[210:211], s[84:85], 0, v[172:173]
	global_load_lds_dwordx4 v[210:211], off
	v_lshl_add_u64 v[210:211], s[84:85], 0, v[170:171]
	s_mov_b32 m0, s41
	s_nop 0
	global_load_lds_dwordx4 v[210:211], off
	s_waitcnt vmcnt(8)
	s_waitcnt lgkmcnt(0)
	s_barrier
	s_setprio 1
	s_waitcnt lgkmcnt(0)
	v_mfma_f32_16x16x32_bf16 v[62:65], v[130:133], v[162:165], v[62:65]
	v_mfma_f32_16x16x32_bf16 v[58:61], v[138:141], v[162:165], v[58:61]
	v_mfma_f32_16x16x32_bf16 v[46:49], v[130:133], v[194:197], v[46:49]
	v_mfma_f32_16x16x32_bf16 v[42:45], v[138:141], v[194:197], v[42:45]
	v_mfma_f32_16x16x32_bf16 v[30:33], v[130:133], v[202:205], v[30:33]
	v_mfma_f32_16x16x32_bf16 v[26:29], v[138:141], v[202:205], v[26:29]
	v_mfma_f32_16x16x32_bf16 v[14:17], v[130:133], v[218:221], v[14:17]
	v_mfma_f32_16x16x32_bf16 v[10:13], v[138:141], v[218:221], v[10:13]
	v_mfma_f32_16x16x32_bf16 v[62:65], v[134:137], v[166:169], v[62:65]
	v_mfma_f32_16x16x32_bf16 v[58:61], v[142:145], v[166:169], v[58:61]
	v_mfma_f32_16x16x32_bf16 v[46:49], v[134:137], v[198:201], v[46:49]
	v_mfma_f32_16x16x32_bf16 v[42:45], v[142:145], v[198:201], v[42:45]
	v_mfma_f32_16x16x32_bf16 v[30:33], v[134:137], v[206:209], v[30:33]
	v_mfma_f32_16x16x32_bf16 v[26:29], v[142:145], v[206:209], v[26:29]
	v_mfma_f32_16x16x32_bf16 v[14:17], v[134:137], v[222:225], v[14:17]
	v_mfma_f32_16x16x32_bf16 v[10:13], v[142:145], v[222:225], v[10:13]
	v_mfma_f32_16x16x32_bf16 v[54:57], v[146:149], v[162:165], v[54:57]
	v_mfma_f32_16x16x32_bf16 v[50:53], v[154:157], v[162:165], v[50:53]
	v_mfma_f32_16x16x32_bf16 v[38:41], v[146:149], v[194:197], v[38:41]
	v_mfma_f32_16x16x32_bf16 v[34:37], v[154:157], v[194:197], v[34:37]
	v_mfma_f32_16x16x32_bf16 v[22:25], v[146:149], v[202:205], v[22:25]
	v_mfma_f32_16x16x32_bf16 v[18:21], v[154:157], v[202:205], v[18:21]
	v_mfma_f32_16x16x32_bf16 v[6:9], v[146:149], v[218:221], v[6:9]
	v_mfma_f32_16x16x32_bf16 v[2:5], v[154:157], v[218:221], v[2:5]
	v_mfma_f32_16x16x32_bf16 v[54:57], v[150:153], v[166:169], v[54:57]
	v_mfma_f32_16x16x32_bf16 v[50:53], v[158:161], v[166:169], v[50:53]
	v_mfma_f32_16x16x32_bf16 v[38:41], v[150:153], v[198:201], v[38:41]
	v_mfma_f32_16x16x32_bf16 v[34:37], v[158:161], v[198:201], v[34:37]
	v_mfma_f32_16x16x32_bf16 v[22:25], v[150:153], v[206:209], v[22:25]
	v_mfma_f32_16x16x32_bf16 v[18:21], v[158:161], v[206:209], v[18:21]
	v_mfma_f32_16x16x32_bf16 v[6:9], v[150:153], v[222:225], v[6:9]
	v_mfma_f32_16x16x32_bf16 v[2:5], v[158:161], v[222:225], v[2:5]
	s_setprio 0
	s_barrier
	s_add_i32 s83, 0, 0x18000
	v_add_u32_e32 v0, s83, v213
	s_add_i32 s84, 0, 0x1c000
	ds_read_b128 v[130:133], v0
	ds_read_b128 v[134:137], v0 offset:1024
	ds_read_b128 v[138:141], v0 offset:2048
	ds_read_b128 v[142:145], v0 offset:3072
	v_add_u32_e32 v0, s84, v213
	ds_read_b128 v[146:149], v0
	ds_read_b128 v[150:153], v0 offset:1024
	ds_read_b128 v[154:157], v0 offset:2048
	ds_read_b128 v[158:161], v0 offset:3072
	s_add_u32 s18, s18, 0x40000
	s_addc_u32 s19, s19, 0
	s_mov_b32 m0, s60
	ds_read_b128 v[162:165], v216 offset:32768
	ds_read_b128 v[166:169], v216 offset:33792
	ds_read_b128 v[194:197], v216 offset:34816
	ds_read_b128 v[198:201], v216 offset:35840
	ds_read_b128 v[202:205], v216 offset:36864
	ds_read_b128 v[206:209], v216 offset:37888
	ds_read_b128 v[218:221], v216 offset:38912
	ds_read_b128 v[222:225], v216 offset:39936
	s_nop 0
	v_lshl_add_u64 v[210:211], s[18:19], 0, v[172:173]
	global_load_lds_dwordx4 v[210:211], off
	v_lshl_add_u64 v[210:211], s[18:19], 0, v[170:171]
	s_mov_b32 m0, s61
	s_nop 0
	global_load_lds_dwordx4 v[210:211], off
	s_waitcnt vmcnt(8)
	s_waitcnt lgkmcnt(0)
	s_barrier
	s_setprio 1
	s_waitcnt lgkmcnt(0)
	v_mfma_f32_16x16x32_bf16 v[126:129], v[130:133], v[162:165], v[126:129]
	v_mfma_f32_16x16x32_bf16 v[122:125], v[138:141], v[162:165], v[122:125]
	v_mfma_f32_16x16x32_bf16 v[110:113], v[130:133], v[194:197], v[110:113]
	v_mfma_f32_16x16x32_bf16 v[106:109], v[138:141], v[194:197], v[106:109]
	v_mfma_f32_16x16x32_bf16 v[94:97], v[130:133], v[202:205], v[94:97]
	v_mfma_f32_16x16x32_bf16 v[90:93], v[138:141], v[202:205], v[90:93]
	v_mfma_f32_16x16x32_bf16 v[78:81], v[130:133], v[218:221], v[78:81]
	v_mfma_f32_16x16x32_bf16 v[74:77], v[138:141], v[218:221], v[74:77]
	v_mfma_f32_16x16x32_bf16 v[126:129], v[134:137], v[166:169], v[126:129]
	v_mfma_f32_16x16x32_bf16 v[122:125], v[142:145], v[166:169], v[122:125]
	v_mfma_f32_16x16x32_bf16 v[110:113], v[134:137], v[198:201], v[110:113]
	v_mfma_f32_16x16x32_bf16 v[106:109], v[142:145], v[198:201], v[106:109]
	v_mfma_f32_16x16x32_bf16 v[94:97], v[134:137], v[206:209], v[94:97]
	v_mfma_f32_16x16x32_bf16 v[90:93], v[142:145], v[206:209], v[90:93]
	v_mfma_f32_16x16x32_bf16 v[78:81], v[134:137], v[222:225], v[78:81]
	v_mfma_f32_16x16x32_bf16 v[74:77], v[142:145], v[222:225], v[74:77]
	v_mfma_f32_16x16x32_bf16 v[118:121], v[146:149], v[162:165], v[118:121]
	v_mfma_f32_16x16x32_bf16 v[114:117], v[154:157], v[162:165], v[114:117]
	v_mfma_f32_16x16x32_bf16 v[102:105], v[146:149], v[194:197], v[102:105]
	v_mfma_f32_16x16x32_bf16 v[98:101], v[154:157], v[194:197], v[98:101]
	v_mfma_f32_16x16x32_bf16 v[86:89], v[146:149], v[202:205], v[86:89]
	v_mfma_f32_16x16x32_bf16 v[82:85], v[154:157], v[202:205], v[82:85]
	v_mfma_f32_16x16x32_bf16 v[70:73], v[146:149], v[218:221], v[70:73]
	v_mfma_f32_16x16x32_bf16 v[66:69], v[154:157], v[218:221], v[66:69]
	v_mfma_f32_16x16x32_bf16 v[118:121], v[150:153], v[166:169], v[118:121]
	v_mfma_f32_16x16x32_bf16 v[114:117], v[158:161], v[166:169], v[114:117]
	v_mfma_f32_16x16x32_bf16 v[102:105], v[150:153], v[198:201], v[102:105]
	v_mfma_f32_16x16x32_bf16 v[98:101], v[158:161], v[198:201], v[98:101]
	v_mfma_f32_16x16x32_bf16 v[86:89], v[150:153], v[206:209], v[86:89]
	v_mfma_f32_16x16x32_bf16 v[82:85], v[158:161], v[206:209], v[82:85]
	v_mfma_f32_16x16x32_bf16 v[70:73], v[150:153], v[222:225], v[70:73]
	v_mfma_f32_16x16x32_bf16 v[66:69], v[158:161], v[222:225], v[66:69]
	s_setprio 0
	s_barrier
	s_add_u32 s18, s56, 0x80
	s_addc_u32 s19, s57, 0
	s_add_i32 s83, s83, s25
	ds_read_b128 v[162:165], v216 offset:49152
	ds_read_b128 v[166:169], v216 offset:50176
	ds_read_b128 v[194:197], v216 offset:51200
	ds_read_b128 v[198:201], v216 offset:52224
	ds_read_b128 v[202:205], v216 offset:53248
	ds_read_b128 v[206:209], v216 offset:54272
	ds_read_b128 v[218:221], v216 offset:55296
	ds_read_b128 v[222:225], v216 offset:56320
	s_mov_b32 m0, s83
	v_lshl_add_u64 v[210:211], s[18:19], 0, v[172:173]
	global_load_lds_dwordx4 v[210:211], off
	s_add_i32 m0, s83, 0x2000
	v_lshl_add_u64 v[210:211], s[18:19], 0, v[170:171]
	s_add_u32 s18, s56, 0x40080
	s_addc_u32 s19, s57, 0
	s_add_i32 s56, s84, s25
	global_load_lds_dwordx4 v[210:211], off
	s_mov_b32 m0, s56
	v_lshl_add_u64 v[210:211], s[18:19], 0, v[172:173]
	global_load_lds_dwordx4 v[210:211], off
	v_lshl_add_u64 v[210:211], s[18:19], 0, v[170:171]
	s_add_i32 m0, s56, 0x2000
	s_nop 0
	global_load_lds_dwordx4 v[210:211], off
	s_mov_b32 m0, s68
	v_lshl_add_u64 v[210:211], s[26:27], 0, v[172:173]
	global_load_lds_dwordx4 v[210:211], off
	v_lshl_add_u64 v[210:211], s[26:27], 0, v[170:171]
	s_mov_b32 m0, s69
	s_nop 0
	global_load_lds_dwordx4 v[210:211], off
	s_waitcnt vmcnt(8)
	s_waitcnt lgkmcnt(0)
	s_barrier
	s_setprio 1
	s_waitcnt lgkmcnt(0)
	v_mfma_f32_16x16x32_bf16 v[62:65], v[130:133], v[162:165], v[62:65]
	v_mfma_f32_16x16x32_bf16 v[58:61], v[138:141], v[162:165], v[58:61]
	v_mfma_f32_16x16x32_bf16 v[46:49], v[130:133], v[194:197], v[46:49]
	v_mfma_f32_16x16x32_bf16 v[42:45], v[138:141], v[194:197], v[42:45]
	v_mfma_f32_16x16x32_bf16 v[30:33], v[130:133], v[202:205], v[30:33]
	v_mfma_f32_16x16x32_bf16 v[26:29], v[138:141], v[202:205], v[26:29]
	v_mfma_f32_16x16x32_bf16 v[14:17], v[130:133], v[218:221], v[14:17]
	v_mfma_f32_16x16x32_bf16 v[10:13], v[138:141], v[218:221], v[10:13]
	v_mfma_f32_16x16x32_bf16 v[62:65], v[134:137], v[166:169], v[62:65]
	v_mfma_f32_16x16x32_bf16 v[58:61], v[142:145], v[166:169], v[58:61]
	v_mfma_f32_16x16x32_bf16 v[46:49], v[134:137], v[198:201], v[46:49]
	v_mfma_f32_16x16x32_bf16 v[42:45], v[142:145], v[198:201], v[42:45]
	v_mfma_f32_16x16x32_bf16 v[30:33], v[134:137], v[206:209], v[30:33]
	v_mfma_f32_16x16x32_bf16 v[26:29], v[142:145], v[206:209], v[26:29]
	v_mfma_f32_16x16x32_bf16 v[14:17], v[134:137], v[222:225], v[14:17]
	v_mfma_f32_16x16x32_bf16 v[10:13], v[142:145], v[222:225], v[10:13]
	v_mfma_f32_16x16x32_bf16 v[54:57], v[146:149], v[162:165], v[54:57]
	v_mfma_f32_16x16x32_bf16 v[50:53], v[154:157], v[162:165], v[50:53]
	v_mfma_f32_16x16x32_bf16 v[38:41], v[146:149], v[194:197], v[38:41]
	v_mfma_f32_16x16x32_bf16 v[34:37], v[154:157], v[194:197], v[34:37]
	v_mfma_f32_16x16x32_bf16 v[22:25], v[146:149], v[202:205], v[22:25]
	v_mfma_f32_16x16x32_bf16 v[18:21], v[154:157], v[202:205], v[18:21]
	v_mfma_f32_16x16x32_bf16 v[6:9], v[146:149], v[218:221], v[6:9]
	v_mfma_f32_16x16x32_bf16 v[2:5], v[154:157], v[218:221], v[2:5]
	v_mfma_f32_16x16x32_bf16 v[54:57], v[150:153], v[166:169], v[54:57]
	v_mfma_f32_16x16x32_bf16 v[50:53], v[158:161], v[166:169], v[50:53]
	v_mfma_f32_16x16x32_bf16 v[38:41], v[150:153], v[198:201], v[38:41]
	v_mfma_f32_16x16x32_bf16 v[34:37], v[158:161], v[198:201], v[34:37]
	v_mfma_f32_16x16x32_bf16 v[22:25], v[150:153], v[206:209], v[22:25]
	v_mfma_f32_16x16x32_bf16 v[18:21], v[158:161], v[206:209], v[18:21]
	v_mfma_f32_16x16x32_bf16 v[6:9], v[150:153], v[222:225], v[6:9]
	v_mfma_f32_16x16x32_bf16 v[2:5], v[158:161], v[222:225], v[2:5]
	s_setprio 0
	s_barrier
	s_add_u32 s78, s78, 0x100
	s_addc_u32 s79, s79, 0
	s_add_u32 s80, s80, 0x100
	s_addc_u32 s81, s81, 0
	s_cmp_ge_i32 s82, s67
	s_mov_b32 s18, s82
	s_cbranch_scc0 .LBB0_253
	s_mov_b32 s72, 0x18000
	s_mov_b32 s78, 0x1a000
	s_mov_b32 s79, 0x8000
	s_mov_b32 s80, 0x1e000
	s_mov_b32 s81, 0xc000
	s_mov_b32 s82, 0xe000
	s_mov_b32 s83, 0xb000
	s_mov_b32 s84, 0x4ffff
	s_mov_b32 s85, 0x66666667
	s_mov_b32 s86, 0x1f000

.LBB0_440:
	s_add_i32 s82, s18, 2
	s_cmp_eq_u32 s73, s18
	s_cselect_b32 s18, s3, s55
	s_cselect_b32 s19, s1, s61
	s_cselect_b32 s44, s41, s80
	s_cselect_b32 s45, s40, s81
	s_add_u32 s26, s18, 0x80
	s_addc_u32 s27, s19, 0
	s_add_i32 s83, 0, 0x10000
	v_add_u32_e32 v0, s83, v144
	s_add_i32 s86, 0, 0x14000
	ds_read_b128 v[138:141], v0
	ds_read_b128 v[146:149], v0 offset:1024
	ds_read_b128 v[150:153], v0 offset:2048
	ds_read_b128 v[154:157], v0 offset:3072
	v_add_u32_e32 v0, s86, v144
	ds_read_b128 v[158:161], v0
	ds_read_b128 v[162:165], v0 offset:1024
	ds_read_b128 v[166:169], v0 offset:2048
	ds_read_b128 v[170:173], v0 offset:3072
	s_add_u32 s84, s55, 0x1ff80
	s_addc_u32 s85, s61, 0
	ds_read_b128 v[194:197], v145
	ds_read_b128 v[198:201], v145 offset:1024
	ds_read_b128 v[202:205], v145 offset:2048
	ds_read_b128 v[206:209], v145 offset:3072
	ds_read_b128 v[210:213], v145 offset:4096
	ds_read_b128 v[214:217], v145 offset:5120
	ds_read_b128 v[218:221], v145 offset:6144
	ds_read_b128 v[222:225], v145 offset:7168
	s_add_i32 m0, s39, 0xc000
	v_lshl_add_u64 v[142:143], s[84:85], 0, v[130:131]
	global_load_lds_dwordx4 v[142:143], off
	v_lshl_add_u64 v[142:143], s[84:85], 0, v[134:135]
	s_add_i32 m0, s39, 0xe000
	s_nop 0
	global_load_lds_dwordx4 v[142:143], off
	s_waitcnt vmcnt(8)
	s_waitcnt lgkmcnt(0)
	s_barrier
	s_setprio 1
	s_waitcnt lgkmcnt(0)
	v_mfma_f32_16x16x32_bf16 v[126:129], v[138:141], v[194:197], v[126:129]
	v_mfma_f32_16x16x32_bf16 v[122:125], v[150:153], v[194:197], v[122:125]
	v_mfma_f32_16x16x32_bf16 v[118:121], v[138:141], v[202:205], v[118:121]
	v_mfma_f32_16x16x32_bf16 v[114:117], v[150:153], v[202:205], v[114:117]
	v_mfma_f32_16x16x32_bf16 v[110:113], v[138:141], v[210:213], v[110:113]
	v_mfma_f32_16x16x32_bf16 v[106:109], v[150:153], v[210:213], v[106:109]
	v_mfma_f32_16x16x32_bf16 v[102:105], v[138:141], v[218:221], v[102:105]
	v_mfma_f32_16x16x32_bf16 v[98:101], v[150:153], v[218:221], v[98:101]
	v_mfma_f32_16x16x32_bf16 v[126:129], v[146:149], v[198:201], v[126:129]
	v_mfma_f32_16x16x32_bf16 v[122:125], v[154:157], v[198:201], v[122:125]
	v_mfma_f32_16x16x32_bf16 v[118:121], v[146:149], v[206:209], v[118:121]
	v_mfma_f32_16x16x32_bf16 v[114:117], v[154:157], v[206:209], v[114:117]
	v_mfma_f32_16x16x32_bf16 v[110:113], v[146:149], v[214:217], v[110:113]
	v_mfma_f32_16x16x32_bf16 v[106:109], v[154:157], v[214:217], v[106:109]
	v_mfma_f32_16x16x32_bf16 v[102:105], v[146:149], v[222:225], v[102:105]
	v_mfma_f32_16x16x32_bf16 v[98:101], v[154:157], v[222:225], v[98:101]
	v_mfma_f32_16x16x32_bf16 v[62:65], v[158:161], v[194:197], v[62:65]
	v_mfma_f32_16x16x32_bf16 v[58:61], v[166:169], v[194:197], v[58:61]
	v_mfma_f32_16x16x32_bf16 v[54:57], v[158:161], v[202:205], v[54:57]
	v_mfma_f32_16x16x32_bf16 v[50:53], v[166:169], v[202:205], v[50:53]
	v_mfma_f32_16x16x32_bf16 v[46:49], v[158:161], v[210:213], v[46:49]
	v_mfma_f32_16x16x32_bf16 v[42:45], v[166:169], v[210:213], v[42:45]
	v_mfma_f32_16x16x32_bf16 v[38:41], v[158:161], v[218:221], v[38:41]
	v_mfma_f32_16x16x32_bf16 v[34:37], v[166:169], v[218:221], v[34:37]
	v_mfma_f32_16x16x32_bf16 v[62:65], v[162:165], v[198:201], v[62:65]
	v_mfma_f32_16x16x32_bf16 v[58:61], v[170:173], v[198:201], v[58:61]
	v_mfma_f32_16x16x32_bf16 v[54:57], v[162:165], v[206:209], v[54:57]
	v_mfma_f32_16x16x32_bf16 v[50:53], v[170:173], v[206:209], v[50:53]
	v_mfma_f32_16x16x32_bf16 v[46:49], v[162:165], v[214:217], v[46:49]
	v_mfma_f32_16x16x32_bf16 v[42:45], v[170:173], v[214:217], v[42:45]
	v_mfma_f32_16x16x32_bf16 v[38:41], v[162:165], v[222:225], v[38:41]
	v_mfma_f32_16x16x32_bf16 v[34:37], v[170:173], v[222:225], v[34:37]
	s_setprio 0
	s_barrier
	s_mov_b64 s[84:85], s[44:45]
	s_add_i32 s83, s83, s25
	ds_read_b128 v[194:197], v145 offset:16384
	ds_read_b128 v[198:201], v145 offset:17408
	ds_read_b128 v[202:205], v145 offset:18432
	ds_read_b128 v[206:209], v145 offset:19456
	ds_read_b128 v[210:213], v145 offset:20480
	ds_read_b128 v[214:217], v145 offset:21504
	ds_read_b128 v[218:221], v145 offset:22528
	ds_read_b128 v[222:225], v145 offset:23552
	s_mov_b32 m0, s83
	v_lshl_add_u64 v[142:143], s[84:85], 0, v[132:133]
	global_load_lds_dwordx4 v[142:143], off
	s_add_i32 m0, s83, 0x2000
	v_lshl_add_u64 v[142:143], s[84:85], 0, v[136:137]
	s_add_u32 s84, s44, 0x20000
	s_addc_u32 s85, s45, 0
	s_add_i32 s83, s86, s25
	global_load_lds_dwordx4 v[142:143], off
	s_mov_b32 m0, s83
	v_lshl_add_u64 v[142:143], s[84:85], 0, v[132:133]
	global_load_lds_dwordx4 v[142:143], off
	v_lshl_add_u64 v[142:143], s[84:85], 0, v[136:137]
	s_add_i32 m0, s83, 0x2000
	s_mov_b64 s[84:85], s[18:19]
	global_load_lds_dwordx4 v[142:143], off
	s_mov_b32 m0, s39
	v_lshl_add_u64 v[142:143], s[84:85], 0, v[130:131]
	global_load_lds_dwordx4 v[142:143], off
	v_lshl_add_u64 v[142:143], s[84:85], 0, v[134:135]
	s_mov_b32 m0, s67
	s_nop 0
	global_load_lds_dwordx4 v[142:143], off
	s_waitcnt vmcnt(8)
	s_waitcnt lgkmcnt(0)
	s_barrier
	s_setprio 1
	s_waitcnt lgkmcnt(0)
	v_mfma_f32_16x16x32_bf16 v[94:97], v[138:141], v[194:197], v[94:97]
	v_mfma_f32_16x16x32_bf16 v[90:93], v[150:153], v[194:197], v[90:93]
	v_mfma_f32_16x16x32_bf16 v[86:89], v[138:141], v[202:205], v[86:89]
	v_mfma_f32_16x16x32_bf16 v[82:85], v[150:153], v[202:205], v[82:85]
	v_mfma_f32_16x16x32_bf16 v[78:81], v[138:141], v[210:213], v[78:81]
	v_mfma_f32_16x16x32_bf16 v[74:77], v[150:153], v[210:213], v[74:77]
	v_mfma_f32_16x16x32_bf16 v[70:73], v[138:141], v[218:221], v[70:73]
	v_mfma_f32_16x16x32_bf16 v[66:69], v[150:153], v[218:221], v[66:69]
	v_mfma_f32_16x16x32_bf16 v[94:97], v[146:149], v[198:201], v[94:97]
	v_mfma_f32_16x16x32_bf16 v[90:93], v[154:157], v[198:201], v[90:93]
	v_mfma_f32_16x16x32_bf16 v[86:89], v[146:149], v[206:209], v[86:89]
	v_mfma_f32_16x16x32_bf16 v[82:85], v[154:157], v[206:209], v[82:85]
	v_mfma_f32_16x16x32_bf16 v[78:81], v[146:149], v[214:217], v[78:81]
	v_mfma_f32_16x16x32_bf16 v[74:77], v[154:157], v[214:217], v[74:77]
	v_mfma_f32_16x16x32_bf16 v[70:73], v[146:149], v[222:225], v[70:73]
	v_mfma_f32_16x16x32_bf16 v[66:69], v[154:157], v[222:225], v[66:69]
	v_mfma_f32_16x16x32_bf16 v[30:33], v[158:161], v[194:197], v[30:33]
	v_mfma_f32_16x16x32_bf16 v[26:29], v[166:169], v[194:197], v[26:29]
	v_mfma_f32_16x16x32_bf16 v[22:25], v[158:161], v[202:205], v[22:25]
	v_mfma_f32_16x16x32_bf16 v[18:21], v[166:169], v[202:205], v[18:21]
	v_mfma_f32_16x16x32_bf16 v[14:17], v[158:161], v[210:213], v[14:17]
	v_mfma_f32_16x16x32_bf16 v[10:13], v[166:169], v[210:213], v[10:13]
	v_mfma_f32_16x16x32_bf16 v[6:9], v[158:161], v[218:221], v[6:9]
	v_mfma_f32_16x16x32_bf16 v[2:5], v[166:169], v[218:221], v[2:5]
	v_mfma_f32_16x16x32_bf16 v[30:33], v[162:165], v[198:201], v[30:33]
	v_mfma_f32_16x16x32_bf16 v[26:29], v[170:173], v[198:201], v[26:29]
	v_mfma_f32_16x16x32_bf16 v[22:25], v[162:165], v[206:209], v[22:25]
	v_mfma_f32_16x16x32_bf16 v[18:21], v[170:173], v[206:209], v[18:21]
	v_mfma_f32_16x16x32_bf16 v[14:17], v[162:165], v[214:217], v[14:17]
	v_mfma_f32_16x16x32_bf16 v[10:13], v[170:173], v[214:217], v[10:13]
	v_mfma_f32_16x16x32_bf16 v[6:9], v[162:165], v[222:225], v[6:9]
	v_mfma_f32_16x16x32_bf16 v[2:5], v[170:173], v[222:225], v[2:5]
	s_setprio 0
	s_barrier
	s_add_i32 s83, 0, 0x18000
	v_add_u32_e32 v0, s83, v144
	s_add_i32 s84, 0, 0x1c000
	ds_read_b128 v[138:141], v0
	ds_read_b128 v[146:149], v0 offset:1024
	ds_read_b128 v[150:153], v0 offset:2048
	ds_read_b128 v[154:157], v0 offset:3072
	v_add_u32_e32 v0, s84, v144
	ds_read_b128 v[158:161], v0
	ds_read_b128 v[162:165], v0 offset:1024
	ds_read_b128 v[166:169], v0 offset:2048
	ds_read_b128 v[170:173], v0 offset:3072
	s_add_u32 s18, s18, 0x20000
	s_addc_u32 s19, s19, 0
	s_mov_b32 m0, s68
	ds_read_b128 v[194:197], v145 offset:32768
	ds_read_b128 v[198:201], v145 offset:33792
	ds_read_b128 v[202:205], v145 offset:34816
	ds_read_b128 v[206:209], v145 offset:35840
	ds_read_b128 v[210:213], v145 offset:36864
	ds_read_b128 v[214:217], v145 offset:37888
	ds_read_b128 v[218:221], v145 offset:38912
	ds_read_b128 v[222:225], v145 offset:39936
	s_nop 0
	v_lshl_add_u64 v[142:143], s[18:19], 0, v[130:131]
	global_load_lds_dwordx4 v[142:143], off
	v_lshl_add_u64 v[142:143], s[18:19], 0, v[134:135]
	s_mov_b32 m0, s69
	s_nop 0
	global_load_lds_dwordx4 v[142:143], off
	s_waitcnt vmcnt(8)
	s_waitcnt lgkmcnt(0)
	s_barrier
	s_setprio 1
	s_waitcnt lgkmcnt(0)
	v_mfma_f32_16x16x32_bf16 v[126:129], v[138:141], v[194:197], v[126:129]
	v_mfma_f32_16x16x32_bf16 v[122:125], v[150:153], v[194:197], v[122:125]
	v_mfma_f32_16x16x32_bf16 v[118:121], v[138:141], v[202:205], v[118:121]
	v_mfma_f32_16x16x32_bf16 v[114:117], v[150:153], v[202:205], v[114:117]
	v_mfma_f32_16x16x32_bf16 v[110:113], v[138:141], v[210:213], v[110:113]
	v_mfma_f32_16x16x32_bf16 v[106:109], v[150:153], v[210:213], v[106:109]
	v_mfma_f32_16x16x32_bf16 v[102:105], v[138:141], v[218:221], v[102:105]
	v_mfma_f32_16x16x32_bf16 v[98:101], v[150:153], v[218:221], v[98:101]
	v_mfma_f32_16x16x32_bf16 v[126:129], v[146:149], v[198:201], v[126:129]
	v_mfma_f32_16x16x32_bf16 v[122:125], v[154:157], v[198:201], v[122:125]
	v_mfma_f32_16x16x32_bf16 v[118:121], v[146:149], v[206:209], v[118:121]
	v_mfma_f32_16x16x32_bf16 v[114:117], v[154:157], v[206:209], v[114:117]
	v_mfma_f32_16x16x32_bf16 v[110:113], v[146:149], v[214:217], v[110:113]
	v_mfma_f32_16x16x32_bf16 v[106:109], v[154:157], v[214:217], v[106:109]
	v_mfma_f32_16x16x32_bf16 v[102:105], v[146:149], v[222:225], v[102:105]
	v_mfma_f32_16x16x32_bf16 v[98:101], v[154:157], v[222:225], v[98:101]
	v_mfma_f32_16x16x32_bf16 v[62:65], v[158:161], v[194:197], v[62:65]
	v_mfma_f32_16x16x32_bf16 v[58:61], v[166:169], v[194:197], v[58:61]
	v_mfma_f32_16x16x32_bf16 v[54:57], v[158:161], v[202:205], v[54:57]
	v_mfma_f32_16x16x32_bf16 v[50:53], v[166:169], v[202:205], v[50:53]
	v_mfma_f32_16x16x32_bf16 v[46:49], v[158:161], v[210:213], v[46:49]
	v_mfma_f32_16x16x32_bf16 v[42:45], v[166:169], v[210:213], v[42:45]
	v_mfma_f32_16x16x32_bf16 v[38:41], v[158:161], v[218:221], v[38:41]
	v_mfma_f32_16x16x32_bf16 v[34:37], v[166:169], v[218:221], v[34:37]
	v_mfma_f32_16x16x32_bf16 v[62:65], v[162:165], v[198:201], v[62:65]
	v_mfma_f32_16x16x32_bf16 v[58:61], v[170:173], v[198:201], v[58:61]
	v_mfma_f32_16x16x32_bf16 v[54:57], v[162:165], v[206:209], v[54:57]
	v_mfma_f32_16x16x32_bf16 v[50:53], v[170:173], v[206:209], v[50:53]
	v_mfma_f32_16x16x32_bf16 v[46:49], v[162:165], v[214:217], v[46:49]
	v_mfma_f32_16x16x32_bf16 v[42:45], v[170:173], v[214:217], v[42:45]
	v_mfma_f32_16x16x32_bf16 v[38:41], v[162:165], v[222:225], v[38:41]
	v_mfma_f32_16x16x32_bf16 v[34:37], v[170:173], v[222:225], v[34:37]
	s_setprio 0
	s_barrier
	s_add_u32 s18, s44, 0x80
	s_addc_u32 s19, s45, 0
	s_add_i32 s83, s83, s25
	ds_read_b128 v[194:197], v145 offset:49152
	ds_read_b128 v[198:201], v145 offset:50176
	ds_read_b128 v[202:205], v145 offset:51200
	ds_read_b128 v[206:209], v145 offset:52224
	ds_read_b128 v[210:213], v145 offset:53248
	ds_read_b128 v[214:217], v145 offset:54272
	ds_read_b128 v[218:221], v145 offset:55296
	ds_read_b128 v[222:225], v145 offset:56320
	s_mov_b32 m0, s83
	v_lshl_add_u64 v[142:143], s[18:19], 0, v[132:133]
	global_load_lds_dwordx4 v[142:143], off
	s_add_i32 m0, s83, 0x2000
	v_lshl_add_u64 v[142:143], s[18:19], 0, v[136:137]
	s_add_u32 s18, s44, 0x20080
	s_addc_u32 s19, s45, 0
	s_add_i32 s44, s84, s25
	global_load_lds_dwordx4 v[142:143], off
	s_mov_b32 m0, s44
	v_lshl_add_u64 v[142:143], s[18:19], 0, v[132:133]
	global_load_lds_dwordx4 v[142:143], off
	v_lshl_add_u64 v[142:143], s[18:19], 0, v[136:137]
	s_add_i32 m0, s44, 0x2000
	s_nop 0
	global_load_lds_dwordx4 v[142:143], off
	s_mov_b32 m0, s71
	v_lshl_add_u64 v[142:143], s[26:27], 0, v[130:131]
	global_load_lds_dwordx4 v[142:143], off
	v_lshl_add_u64 v[142:143], s[26:27], 0, v[134:135]
	s_mov_b32 m0, s72
	s_nop 0
	global_load_lds_dwordx4 v[142:143], off
	s_waitcnt vmcnt(8)
	s_waitcnt lgkmcnt(0)
	s_barrier
	s_setprio 1
	s_waitcnt lgkmcnt(0)
	v_mfma_f32_16x16x32_bf16 v[94:97], v[138:141], v[194:197], v[94:97]
	v_mfma_f32_16x16x32_bf16 v[90:93], v[150:153], v[194:197], v[90:93]
	v_mfma_f32_16x16x32_bf16 v[86:89], v[138:141], v[202:205], v[86:89]
	v_mfma_f32_16x16x32_bf16 v[82:85], v[150:153], v[202:205], v[82:85]
	v_mfma_f32_16x16x32_bf16 v[78:81], v[138:141], v[210:213], v[78:81]
	v_mfma_f32_16x16x32_bf16 v[74:77], v[150:153], v[210:213], v[74:77]
	v_mfma_f32_16x16x32_bf16 v[70:73], v[138:141], v[218:221], v[70:73]
	v_mfma_f32_16x16x32_bf16 v[66:69], v[150:153], v[218:221], v[66:69]
	v_mfma_f32_16x16x32_bf16 v[94:97], v[146:149], v[198:201], v[94:97]
	v_mfma_f32_16x16x32_bf16 v[90:93], v[154:157], v[198:201], v[90:93]
	v_mfma_f32_16x16x32_bf16 v[86:89], v[146:149], v[206:209], v[86:89]
	v_mfma_f32_16x16x32_bf16 v[82:85], v[154:157], v[206:209], v[82:85]
	v_mfma_f32_16x16x32_bf16 v[78:81], v[146:149], v[214:217], v[78:81]
	v_mfma_f32_16x16x32_bf16 v[74:77], v[154:157], v[214:217], v[74:77]
	v_mfma_f32_16x16x32_bf16 v[70:73], v[146:149], v[222:225], v[70:73]
	v_mfma_f32_16x16x32_bf16 v[66:69], v[154:157], v[222:225], v[66:69]
	v_mfma_f32_16x16x32_bf16 v[30:33], v[158:161], v[194:197], v[30:33]
	v_mfma_f32_16x16x32_bf16 v[26:29], v[166:169], v[194:197], v[26:29]
	v_mfma_f32_16x16x32_bf16 v[22:25], v[158:161], v[202:205], v[22:25]
	v_mfma_f32_16x16x32_bf16 v[18:21], v[166:169], v[202:205], v[18:21]
	v_mfma_f32_16x16x32_bf16 v[14:17], v[158:161], v[210:213], v[14:17]
	v_mfma_f32_16x16x32_bf16 v[10:13], v[166:169], v[210:213], v[10:13]
	v_mfma_f32_16x16x32_bf16 v[6:9], v[158:161], v[218:221], v[6:9]
	v_mfma_f32_16x16x32_bf16 v[2:5], v[166:169], v[218:221], v[2:5]
	v_mfma_f32_16x16x32_bf16 v[30:33], v[162:165], v[198:201], v[30:33]
	v_mfma_f32_16x16x32_bf16 v[26:29], v[170:173], v[198:201], v[26:29]
	v_mfma_f32_16x16x32_bf16 v[22:25], v[162:165], v[206:209], v[22:25]
	v_mfma_f32_16x16x32_bf16 v[18:21], v[170:173], v[206:209], v[18:21]
	v_mfma_f32_16x16x32_bf16 v[14:17], v[162:165], v[214:217], v[14:17]
	v_mfma_f32_16x16x32_bf16 v[10:13], v[170:173], v[214:217], v[10:13]
	v_mfma_f32_16x16x32_bf16 v[6:9], v[162:165], v[222:225], v[6:9]
	v_mfma_f32_16x16x32_bf16 v[2:5], v[170:173], v[222:225], v[2:5]
	s_setprio 0
	s_barrier
	s_add_u32 s55, s55, 0x100
	s_addc_u32 s61, s61, 0
	s_add_u32 s80, s80, 0x100
	s_addc_u32 s81, s81, 0
	s_cmp_ge_i32 s82, s70
	s_mov_b32 s18, s82
	s_cbranch_scc0 .LBB0_440
	s_mov_b32 s80, 0x1e000
	s_mov_b32 s81, 0xc000
	s_mov_b32 s82, 0xe000
	s_mov_b32 s83, 0xb000
	s_mov_b32 s84, 0x4ffff
	s_mov_b32 s85, 0x66666667
	s_mov_b32 s86, 0x1f000

.LBB0_512:
	s_add_i32 s82, s18, 2
	s_cmp_eq_u32 s22, s18
	s_cselect_b32 s18, s55, s78
	s_cselect_b32 s19, s51, s79
	s_cselect_b32 s62, s73, s80
	s_cselect_b32 s63, s72, s81
	s_add_u32 s26, s18, 0x80
	s_addc_u32 s27, s19, 0
	s_add_i32 s83, 0, 0x10000
	s_add_i32 s86, 0, 0x14000
	v_add_u32_e32 v150, s83, v136
	v_add_u32_e32 v166, s86, v136
	ds_read_b128 v[138:141], v150
	ds_read_b128 v[142:145], v150 offset:1024
	ds_read_b128 v[146:149], v150 offset:2048
	ds_read_b128 v[150:153], v150 offset:3072
	ds_read_b128 v[154:157], v166
	ds_read_b128 v[158:161], v166 offset:1024
	ds_read_b128 v[162:165], v166 offset:2048
	ds_read_b128 v[166:169], v166 offset:3072
	s_add_u32 s84, s78, 0xff80
	s_addc_u32 s85, s79, 0
	ds_read_b128 v[170:173], v137
	ds_read_b128 v[194:197], v137 offset:1024
	ds_read_b128 v[198:201], v137 offset:2048
	ds_read_b128 v[202:205], v137 offset:3072
	ds_read_b128 v[206:209], v137 offset:4096
	ds_read_b128 v[210:213], v137 offset:5120
	ds_read_b128 v[214:217], v137 offset:6144
	ds_read_b128 v[218:221], v137 offset:7168
	s_add_i32 m0, s21, 0xc000
	v_lshl_add_u64 v[222:223], s[84:85], 0, v[130:131]
	global_load_lds_dwordx4 v[222:223], off
	v_lshl_add_u64 v[222:223], s[84:85], 0, v[132:133]
	s_add_i32 m0, s21, 0xe000
	s_nop 0
	global_load_lds_dwordx4 v[222:223], off
	s_waitcnt vmcnt(8)
	s_waitcnt lgkmcnt(0)
	s_barrier
	s_setprio 1
	s_waitcnt lgkmcnt(0)
	v_mfma_f32_16x16x32_bf16 v[122:125], v[138:141], v[170:173], v[122:125]
	v_mfma_f32_16x16x32_bf16 v[126:129], v[146:149], v[170:173], v[126:129]
	v_mfma_f32_16x16x32_bf16 v[110:113], v[138:141], v[198:201], v[110:113]
	v_mfma_f32_16x16x32_bf16 v[106:109], v[146:149], v[198:201], v[106:109]
	v_mfma_f32_16x16x32_bf16 v[94:97], v[138:141], v[206:209], v[94:97]
	v_mfma_f32_16x16x32_bf16 v[90:93], v[146:149], v[206:209], v[90:93]
	v_mfma_f32_16x16x32_bf16 v[78:81], v[138:141], v[214:217], v[78:81]
	v_mfma_f32_16x16x32_bf16 v[74:77], v[146:149], v[214:217], v[74:77]
	v_mfma_f32_16x16x32_bf16 v[122:125], v[142:145], v[194:197], v[122:125]
	v_mfma_f32_16x16x32_bf16 v[126:129], v[150:153], v[194:197], v[126:129]
	v_mfma_f32_16x16x32_bf16 v[110:113], v[142:145], v[202:205], v[110:113]
	v_mfma_f32_16x16x32_bf16 v[106:109], v[150:153], v[202:205], v[106:109]
	v_mfma_f32_16x16x32_bf16 v[94:97], v[142:145], v[210:213], v[94:97]
	v_mfma_f32_16x16x32_bf16 v[90:93], v[150:153], v[210:213], v[90:93]
	v_mfma_f32_16x16x32_bf16 v[78:81], v[142:145], v[218:221], v[78:81]
	v_mfma_f32_16x16x32_bf16 v[74:77], v[150:153], v[218:221], v[74:77]
	v_mfma_f32_16x16x32_bf16 v[118:121], v[154:157], v[170:173], v[118:121]
	v_mfma_f32_16x16x32_bf16 v[114:117], v[162:165], v[170:173], v[114:117]
	v_mfma_f32_16x16x32_bf16 v[102:105], v[154:157], v[198:201], v[102:105]
	v_mfma_f32_16x16x32_bf16 v[98:101], v[162:165], v[198:201], v[98:101]
	v_mfma_f32_16x16x32_bf16 v[86:89], v[154:157], v[206:209], v[86:89]
	v_mfma_f32_16x16x32_bf16 v[82:85], v[162:165], v[206:209], v[82:85]
	v_mfma_f32_16x16x32_bf16 v[70:73], v[154:157], v[214:217], v[70:73]
	v_mfma_f32_16x16x32_bf16 v[66:69], v[162:165], v[214:217], v[66:69]
	v_mfma_f32_16x16x32_bf16 v[118:121], v[158:161], v[194:197], v[118:121]
	v_mfma_f32_16x16x32_bf16 v[114:117], v[166:169], v[194:197], v[114:117]
	v_mfma_f32_16x16x32_bf16 v[102:105], v[158:161], v[202:205], v[102:105]
	v_mfma_f32_16x16x32_bf16 v[98:101], v[166:169], v[202:205], v[98:101]
	v_mfma_f32_16x16x32_bf16 v[86:89], v[158:161], v[210:213], v[86:89]
	v_mfma_f32_16x16x32_bf16 v[82:85], v[166:169], v[210:213], v[82:85]
	v_mfma_f32_16x16x32_bf16 v[70:73], v[158:161], v[218:221], v[70:73]
	v_mfma_f32_16x16x32_bf16 v[66:69], v[166:169], v[218:221], v[66:69]
	s_setprio 0
	s_barrier
	s_mov_b64 s[84:85], s[62:63]
	s_add_i32 s83, s83, s17
	ds_read_b128 v[170:173], v137 offset:16384
	ds_read_b128 v[194:197], v137 offset:17408
	ds_read_b128 v[198:201], v137 offset:18432
	ds_read_b128 v[202:205], v137 offset:19456
	ds_read_b128 v[206:209], v137 offset:20480
	ds_read_b128 v[210:213], v137 offset:21504
	ds_read_b128 v[214:217], v137 offset:22528
	ds_read_b128 v[218:221], v137 offset:23552
	s_mov_b32 m0, s83
	v_lshl_add_u64 v[222:223], s[84:85], 0, v[0:1]
	global_load_lds_dwordx4 v[222:223], off
	s_add_i32 m0, s83, 0x2000
	v_lshl_add_u64 v[222:223], s[84:85], 0, v[134:135]
	s_add_u32 s84, s62, 0x10000
	s_addc_u32 s85, s63, 0
	s_add_i32 s83, s86, s17
	global_load_lds_dwordx4 v[222:223], off
	s_mov_b32 m0, s83
	v_lshl_add_u64 v[222:223], s[84:85], 0, v[0:1]
	global_load_lds_dwordx4 v[222:223], off
	v_lshl_add_u64 v[222:223], s[84:85], 0, v[134:135]
	s_add_i32 m0, s83, 0x2000
	s_mov_b64 s[84:85], s[18:19]
	global_load_lds_dwordx4 v[222:223], off
	s_mov_b32 m0, s21
	v_lshl_add_u64 v[222:223], s[84:85], 0, v[130:131]
	global_load_lds_dwordx4 v[222:223], off
	v_lshl_add_u64 v[222:223], s[84:85], 0, v[132:133]
	s_mov_b32 m0, s23
	s_nop 0
	global_load_lds_dwordx4 v[222:223], off
	s_waitcnt vmcnt(8)
	s_waitcnt lgkmcnt(0)
	s_barrier
	s_setprio 1
	s_waitcnt lgkmcnt(0)
	v_mfma_f32_16x16x32_bf16 v[62:65], v[138:141], v[170:173], v[62:65]
	v_mfma_f32_16x16x32_bf16 v[58:61], v[146:149], v[170:173], v[58:61]
	v_mfma_f32_16x16x32_bf16 v[46:49], v[138:141], v[198:201], v[46:49]
	v_mfma_f32_16x16x32_bf16 v[42:45], v[146:149], v[198:201], v[42:45]
	v_mfma_f32_16x16x32_bf16 v[30:33], v[138:141], v[206:209], v[30:33]
	v_mfma_f32_16x16x32_bf16 v[26:29], v[146:149], v[206:209], v[26:29]
	v_mfma_f32_16x16x32_bf16 v[14:17], v[138:141], v[214:217], v[14:17]
	v_mfma_f32_16x16x32_bf16 v[10:13], v[146:149], v[214:217], v[10:13]
	v_mfma_f32_16x16x32_bf16 v[62:65], v[142:145], v[194:197], v[62:65]
	v_mfma_f32_16x16x32_bf16 v[58:61], v[150:153], v[194:197], v[58:61]
	v_mfma_f32_16x16x32_bf16 v[46:49], v[142:145], v[202:205], v[46:49]
	v_mfma_f32_16x16x32_bf16 v[42:45], v[150:153], v[202:205], v[42:45]
	v_mfma_f32_16x16x32_bf16 v[30:33], v[142:145], v[210:213], v[30:33]
	v_mfma_f32_16x16x32_bf16 v[26:29], v[150:153], v[210:213], v[26:29]
	v_mfma_f32_16x16x32_bf16 v[14:17], v[142:145], v[218:221], v[14:17]
	v_mfma_f32_16x16x32_bf16 v[10:13], v[150:153], v[218:221], v[10:13]
	v_mfma_f32_16x16x32_bf16 v[54:57], v[154:157], v[170:173], v[54:57]
	v_mfma_f32_16x16x32_bf16 v[50:53], v[162:165], v[170:173], v[50:53]
	v_mfma_f32_16x16x32_bf16 v[38:41], v[154:157], v[198:201], v[38:41]
	v_mfma_f32_16x16x32_bf16 v[34:37], v[162:165], v[198:201], v[34:37]
	v_mfma_f32_16x16x32_bf16 v[22:25], v[154:157], v[206:209], v[22:25]
	v_mfma_f32_16x16x32_bf16 v[18:21], v[162:165], v[206:209], v[18:21]
	v_mfma_f32_16x16x32_bf16 v[6:9], v[154:157], v[214:217], v[6:9]
	v_mfma_f32_16x16x32_bf16 v[2:5], v[162:165], v[214:217], v[2:5]
	v_mfma_f32_16x16x32_bf16 v[54:57], v[158:161], v[194:197], v[54:57]
	v_mfma_f32_16x16x32_bf16 v[50:53], v[166:169], v[194:197], v[50:53]
	v_mfma_f32_16x16x32_bf16 v[38:41], v[158:161], v[202:205], v[38:41]
	v_mfma_f32_16x16x32_bf16 v[34:37], v[166:169], v[202:205], v[34:37]
	v_mfma_f32_16x16x32_bf16 v[22:25], v[158:161], v[210:213], v[22:25]
	v_mfma_f32_16x16x32_bf16 v[18:21], v[166:169], v[210:213], v[18:21]
	v_mfma_f32_16x16x32_bf16 v[6:9], v[158:161], v[218:221], v[6:9]
	v_mfma_f32_16x16x32_bf16 v[2:5], v[166:169], v[218:221], v[2:5]
	s_setprio 0
	s_barrier
	s_add_i32 s83, 0, 0x18000
	s_add_i32 s84, 0, 0x1c000
	v_add_u32_e32 v150, s83, v136
	v_add_u32_e32 v166, s84, v136
	ds_read_b128 v[138:141], v150
	ds_read_b128 v[142:145], v150 offset:1024
	ds_read_b128 v[146:149], v150 offset:2048
	ds_read_b128 v[150:153], v150 offset:3072
	ds_read_b128 v[154:157], v166
	ds_read_b128 v[158:161], v166 offset:1024
	ds_read_b128 v[162:165], v166 offset:2048
	ds_read_b128 v[166:169], v166 offset:3072
	s_add_u32 s18, s18, 0x10000
	s_addc_u32 s19, s19, 0
	s_mov_b32 m0, s25
	ds_read_b128 v[170:173], v137 offset:32768
	ds_read_b128 v[194:197], v137 offset:33792
	ds_read_b128 v[198:201], v137 offset:34816
	ds_read_b128 v[202:205], v137 offset:35840
	ds_read_b128 v[206:209], v137 offset:36864
	ds_read_b128 v[210:213], v137 offset:37888
	ds_read_b128 v[214:217], v137 offset:38912
	ds_read_b128 v[218:221], v137 offset:39936
	s_nop 0
	v_lshl_add_u64 v[222:223], s[18:19], 0, v[130:131]
	global_load_lds_dwordx4 v[222:223], off
	v_lshl_add_u64 v[222:223], s[18:19], 0, v[132:133]
	s_mov_b32 m0, s39
	s_nop 0
	global_load_lds_dwordx4 v[222:223], off
	s_waitcnt vmcnt(8)
	s_waitcnt lgkmcnt(0)
	s_barrier
	s_setprio 1
	s_waitcnt lgkmcnt(0)
	v_mfma_f32_16x16x32_bf16 v[122:125], v[138:141], v[170:173], v[122:125]
	v_mfma_f32_16x16x32_bf16 v[126:129], v[146:149], v[170:173], v[126:129]
	v_mfma_f32_16x16x32_bf16 v[110:113], v[138:141], v[198:201], v[110:113]
	v_mfma_f32_16x16x32_bf16 v[106:109], v[146:149], v[198:201], v[106:109]
	v_mfma_f32_16x16x32_bf16 v[94:97], v[138:141], v[206:209], v[94:97]
	v_mfma_f32_16x16x32_bf16 v[90:93], v[146:149], v[206:209], v[90:93]
	v_mfma_f32_16x16x32_bf16 v[78:81], v[138:141], v[214:217], v[78:81]
	v_mfma_f32_16x16x32_bf16 v[74:77], v[146:149], v[214:217], v[74:77]
	v_mfma_f32_16x16x32_bf16 v[122:125], v[142:145], v[194:197], v[122:125]
	v_mfma_f32_16x16x32_bf16 v[126:129], v[150:153], v[194:197], v[126:129]
	v_mfma_f32_16x16x32_bf16 v[110:113], v[142:145], v[202:205], v[110:113]
	v_mfma_f32_16x16x32_bf16 v[106:109], v[150:153], v[202:205], v[106:109]
	v_mfma_f32_16x16x32_bf16 v[94:97], v[142:145], v[210:213], v[94:97]
	v_mfma_f32_16x16x32_bf16 v[90:93], v[150:153], v[210:213], v[90:93]
	v_mfma_f32_16x16x32_bf16 v[78:81], v[142:145], v[218:221], v[78:81]
	v_mfma_f32_16x16x32_bf16 v[74:77], v[150:153], v[218:221], v[74:77]
	v_mfma_f32_16x16x32_bf16 v[118:121], v[154:157], v[170:173], v[118:121]
	v_mfma_f32_16x16x32_bf16 v[114:117], v[162:165], v[170:173], v[114:117]
	v_mfma_f32_16x16x32_bf16 v[102:105], v[154:157], v[198:201], v[102:105]
	v_mfma_f32_16x16x32_bf16 v[98:101], v[162:165], v[198:201], v[98:101]
	v_mfma_f32_16x16x32_bf16 v[86:89], v[154:157], v[206:209], v[86:89]
	v_mfma_f32_16x16x32_bf16 v[82:85], v[162:165], v[206:209], v[82:85]
	v_mfma_f32_16x16x32_bf16 v[70:73], v[154:157], v[214:217], v[70:73]
	v_mfma_f32_16x16x32_bf16 v[66:69], v[162:165], v[214:217], v[66:69]
	v_mfma_f32_16x16x32_bf16 v[118:121], v[158:161], v[194:197], v[118:121]
	v_mfma_f32_16x16x32_bf16 v[114:117], v[166:169], v[194:197], v[114:117]
	v_mfma_f32_16x16x32_bf16 v[102:105], v[158:161], v[202:205], v[102:105]
	v_mfma_f32_16x16x32_bf16 v[98:101], v[166:169], v[202:205], v[98:101]
	v_mfma_f32_16x16x32_bf16 v[86:89], v[158:161], v[210:213], v[86:89]
	v_mfma_f32_16x16x32_bf16 v[82:85], v[166:169], v[210:213], v[82:85]
	v_mfma_f32_16x16x32_bf16 v[70:73], v[158:161], v[218:221], v[70:73]
	v_mfma_f32_16x16x32_bf16 v[66:69], v[166:169], v[218:221], v[66:69]
	s_setprio 0
	s_barrier
	s_add_u32 s18, s62, 0x80
	s_addc_u32 s19, s63, 0
	s_add_i32 s83, s83, s17
	ds_read_b128 v[170:173], v137 offset:49152
	ds_read_b128 v[194:197], v137 offset:50176
	ds_read_b128 v[198:201], v137 offset:51200
	ds_read_b128 v[202:205], v137 offset:52224
	ds_read_b128 v[206:209], v137 offset:53248
	ds_read_b128 v[210:213], v137 offset:54272
	ds_read_b128 v[214:217], v137 offset:55296
	ds_read_b128 v[218:221], v137 offset:56320
	s_mov_b32 m0, s83
	v_lshl_add_u64 v[222:223], s[18:19], 0, v[0:1]
	global_load_lds_dwordx4 v[222:223], off
	s_add_i32 m0, s83, 0x2000
	v_lshl_add_u64 v[222:223], s[18:19], 0, v[134:135]
	s_add_u32 s18, s62, 0x10080
	s_addc_u32 s19, s63, 0
	s_add_i32 s62, s84, s17
	global_load_lds_dwordx4 v[222:223], off
	s_mov_b32 m0, s62
	v_lshl_add_u64 v[222:223], s[18:19], 0, v[0:1]
	global_load_lds_dwordx4 v[222:223], off
	v_lshl_add_u64 v[222:223], s[18:19], 0, v[134:135]
	s_add_i32 m0, s62, 0x2000
	s_nop 0
	global_load_lds_dwordx4 v[222:223], off
	s_mov_b32 m0, s49
	v_lshl_add_u64 v[222:223], s[26:27], 0, v[130:131]
	global_load_lds_dwordx4 v[222:223], off
	v_lshl_add_u64 v[222:223], s[26:27], 0, v[132:133]
	s_mov_b32 m0, s67
	s_nop 0
	global_load_lds_dwordx4 v[222:223], off
	s_waitcnt vmcnt(8)
	s_waitcnt lgkmcnt(0)
	s_barrier
	s_setprio 1
	s_waitcnt lgkmcnt(0)
	v_mfma_f32_16x16x32_bf16 v[62:65], v[138:141], v[170:173], v[62:65]
	v_mfma_f32_16x16x32_bf16 v[58:61], v[146:149], v[170:173], v[58:61]
	v_mfma_f32_16x16x32_bf16 v[46:49], v[138:141], v[198:201], v[46:49]
	v_mfma_f32_16x16x32_bf16 v[42:45], v[146:149], v[198:201], v[42:45]
	v_mfma_f32_16x16x32_bf16 v[30:33], v[138:141], v[206:209], v[30:33]
	v_mfma_f32_16x16x32_bf16 v[26:29], v[146:149], v[206:209], v[26:29]
	v_mfma_f32_16x16x32_bf16 v[14:17], v[138:141], v[214:217], v[14:17]
	v_mfma_f32_16x16x32_bf16 v[10:13], v[146:149], v[214:217], v[10:13]
	v_mfma_f32_16x16x32_bf16 v[62:65], v[142:145], v[194:197], v[62:65]
	v_mfma_f32_16x16x32_bf16 v[58:61], v[150:153], v[194:197], v[58:61]
	v_mfma_f32_16x16x32_bf16 v[46:49], v[142:145], v[202:205], v[46:49]
	v_mfma_f32_16x16x32_bf16 v[42:45], v[150:153], v[202:205], v[42:45]
	v_mfma_f32_16x16x32_bf16 v[30:33], v[142:145], v[210:213], v[30:33]
	v_mfma_f32_16x16x32_bf16 v[26:29], v[150:153], v[210:213], v[26:29]
	v_mfma_f32_16x16x32_bf16 v[14:17], v[142:145], v[218:221], v[14:17]
	v_mfma_f32_16x16x32_bf16 v[10:13], v[150:153], v[218:221], v[10:13]
	v_mfma_f32_16x16x32_bf16 v[54:57], v[154:157], v[170:173], v[54:57]
	v_mfma_f32_16x16x32_bf16 v[50:53], v[162:165], v[170:173], v[50:53]
	v_mfma_f32_16x16x32_bf16 v[38:41], v[154:157], v[198:201], v[38:41]
	v_mfma_f32_16x16x32_bf16 v[34:37], v[162:165], v[198:201], v[34:37]
	v_mfma_f32_16x16x32_bf16 v[22:25], v[154:157], v[206:209], v[22:25]
	v_mfma_f32_16x16x32_bf16 v[18:21], v[162:165], v[206:209], v[18:21]
	v_mfma_f32_16x16x32_bf16 v[6:9], v[154:157], v[214:217], v[6:9]
	v_mfma_f32_16x16x32_bf16 v[2:5], v[162:165], v[214:217], v[2:5]
	v_mfma_f32_16x16x32_bf16 v[54:57], v[158:161], v[194:197], v[54:57]
	v_mfma_f32_16x16x32_bf16 v[50:53], v[166:169], v[194:197], v[50:53]
	v_mfma_f32_16x16x32_bf16 v[38:41], v[158:161], v[202:205], v[38:41]
	v_mfma_f32_16x16x32_bf16 v[34:37], v[166:169], v[202:205], v[34:37]
	v_mfma_f32_16x16x32_bf16 v[22:25], v[158:161], v[210:213], v[22:25]
	v_mfma_f32_16x16x32_bf16 v[18:21], v[166:169], v[210:213], v[18:21]
	v_mfma_f32_16x16x32_bf16 v[6:9], v[158:161], v[218:221], v[6:9]
	v_mfma_f32_16x16x32_bf16 v[2:5], v[166:169], v[218:221], v[2:5]
	s_setprio 0
	s_barrier
	s_add_u32 s78, s78, 0x100
	s_addc_u32 s79, s79, 0
	s_add_u32 s80, s80, 0x100
	s_addc_u32 s81, s81, 0
	s_cmp_ge_i32 s82, s41
	s_mov_b32 s18, s82
	s_cbranch_scc0 .LBB0_512
	s_mov_b32 s72, 0x18000
	s_mov_b32 s78, 0x1a000
	s_mov_b32 s79, 0x8000
	s_mov_b32 s80, 0x1e000
	s_mov_b32 s81, 0xc000
	s_mov_b32 s82, 0xe000
	s_mov_b32 s83, 0xb000
	s_mov_b32 s84, 0x4ffff
	s_mov_b32 s85, 0x66666667
	s_mov_b32 s86, 0x1f000

.LBB0_691:
	s_add_i32 s92, s18, 2
	s_cmp_eq_u32 s84, s18
	s_cselect_b32 s18, s37, vcc_lo
	s_cselect_b32 s19, s1, vcc_hi
	s_cselect_b32 s72, s89, s90
	s_cselect_b32 s73, s57, s91
	s_add_u32 s26, s18, 0x80
	s_addc_u32 s27, s19, 0
	s_add_i32 s93, 0, 0x10000
	v_add_u32_e32 v0, s93, v222
	s_add_i32 s96, 0, 0x14000
	ds_read_b128 v[66:69], v0
	ds_read_b128 v[70:73], v0 offset:1024
	ds_read_b128 v[74:77], v0 offset:2048
	ds_read_b128 v[78:81], v0 offset:3072
	v_add_u32_e32 v0, s96, v222
	ds_read_b128 v[146:149], v0
	ds_read_b128 v[150:153], v0 offset:1024
	ds_read_b128 v[154:157], v0 offset:2048
	ds_read_b128 v[158:161], v0 offset:3072
	s_mov_b64 s[94:95], s[2:3]
	ds_read_b128 v[162:165], v223
	ds_read_b128 v[166:169], v223 offset:1024
	ds_read_b128 v[198:201], v223 offset:2048
	ds_read_b128 v[202:205], v223 offset:3072
	ds_read_b128 v[206:209], v223 offset:4096
	ds_read_b128 v[210:213], v223 offset:5120
	ds_read_b128 v[214:217], v223 offset:6144
	ds_read_b128 v[218:221], v223 offset:7168
	s_add_i32 m0, s67, 0xc000
	v_lshl_add_u64 v[224:225], s[94:95], 0, v[196:197]
	global_load_lds_dwordx4 v[224:225], off
	v_lshl_add_u64 v[224:225], s[94:95], 0, v[172:173]
	s_add_i32 m0, s67, 0xe000
	s_nop 0
	global_load_lds_dwordx4 v[224:225], off
	s_waitcnt vmcnt(8)
	s_waitcnt lgkmcnt(0)
	s_barrier
	s_setprio 1
	s_waitcnt lgkmcnt(0)
	v_mfma_f32_16x16x32_bf16 v[138:141], v[66:69], v[162:165], v[138:141]
	v_mfma_f32_16x16x32_bf16 v[142:145], v[74:77], v[162:165], v[142:145]
	v_mfma_f32_16x16x32_bf16 v[126:129], v[66:69], v[198:201], v[126:129]
	v_mfma_f32_16x16x32_bf16 v[122:125], v[74:77], v[198:201], v[122:125]
	v_mfma_f32_16x16x32_bf16 v[110:113], v[66:69], v[206:209], v[110:113]
	v_mfma_f32_16x16x32_bf16 v[106:109], v[74:77], v[206:209], v[106:109]
	v_mfma_f32_16x16x32_bf16 v[94:97], v[66:69], v[214:217], v[94:97]
	v_mfma_f32_16x16x32_bf16 v[90:93], v[74:77], v[214:217], v[90:93]
	v_mfma_f32_16x16x32_bf16 v[138:141], v[70:73], v[166:169], v[138:141]
	v_mfma_f32_16x16x32_bf16 v[142:145], v[78:81], v[166:169], v[142:145]
	v_mfma_f32_16x16x32_bf16 v[126:129], v[70:73], v[202:205], v[126:129]
	v_mfma_f32_16x16x32_bf16 v[122:125], v[78:81], v[202:205], v[122:125]
	v_mfma_f32_16x16x32_bf16 v[110:113], v[70:73], v[210:213], v[110:113]
	v_mfma_f32_16x16x32_bf16 v[106:109], v[78:81], v[210:213], v[106:109]
	v_mfma_f32_16x16x32_bf16 v[94:97], v[70:73], v[218:221], v[94:97]
	v_mfma_f32_16x16x32_bf16 v[90:93], v[78:81], v[218:221], v[90:93]
	v_mfma_f32_16x16x32_bf16 v[134:137], v[146:149], v[162:165], v[134:137]
	v_mfma_f32_16x16x32_bf16 v[130:133], v[154:157], v[162:165], v[130:133]
	v_mfma_f32_16x16x32_bf16 v[118:121], v[146:149], v[198:201], v[118:121]
	v_mfma_f32_16x16x32_bf16 v[114:117], v[154:157], v[198:201], v[114:117]
	v_mfma_f32_16x16x32_bf16 v[102:105], v[146:149], v[206:209], v[102:105]
	v_mfma_f32_16x16x32_bf16 v[98:101], v[154:157], v[206:209], v[98:101]
	v_mfma_f32_16x16x32_bf16 v[86:89], v[146:149], v[214:217], v[86:89]
	v_mfma_f32_16x16x32_bf16 v[82:85], v[154:157], v[214:217], v[82:85]
	v_mfma_f32_16x16x32_bf16 v[134:137], v[150:153], v[166:169], v[134:137]
	v_mfma_f32_16x16x32_bf16 v[130:133], v[158:161], v[166:169], v[130:133]
	v_mfma_f32_16x16x32_bf16 v[118:121], v[150:153], v[202:205], v[118:121]
	v_mfma_f32_16x16x32_bf16 v[114:117], v[158:161], v[202:205], v[114:117]
	v_mfma_f32_16x16x32_bf16 v[102:105], v[150:153], v[210:213], v[102:105]
	v_mfma_f32_16x16x32_bf16 v[98:101], v[158:161], v[210:213], v[98:101]
	v_mfma_f32_16x16x32_bf16 v[86:89], v[150:153], v[218:221], v[86:89]
	v_mfma_f32_16x16x32_bf16 v[82:85], v[158:161], v[218:221], v[82:85]
	s_setprio 0
	s_barrier
	s_mov_b64 s[94:95], s[72:73]
	s_add_i32 s93, s93, s25
	ds_read_b128 v[162:165], v223 offset:16384
	ds_read_b128 v[166:169], v223 offset:17408
	ds_read_b128 v[198:201], v223 offset:18432
	ds_read_b128 v[202:205], v223 offset:19456
	ds_read_b128 v[206:209], v223 offset:20480
	ds_read_b128 v[210:213], v223 offset:21504
	ds_read_b128 v[214:217], v223 offset:22528
	ds_read_b128 v[218:221], v223 offset:23552
	s_mov_b32 m0, s93
	v_lshl_add_u64 v[224:225], s[94:95], 0, v[194:195]
	global_load_lds_dwordx4 v[224:225], off
	s_add_i32 m0, s93, 0x2000
	v_lshl_add_u64 v[224:225], s[94:95], 0, v[170:171]
	s_add_u32 s94, s72, 0x40000
	s_addc_u32 s95, s73, 0
	s_add_i32 s93, s96, s25
	global_load_lds_dwordx4 v[224:225], off
	s_mov_b32 m0, s93
	v_lshl_add_u64 v[224:225], s[94:95], 0, v[194:195]
	global_load_lds_dwordx4 v[224:225], off
	v_lshl_add_u64 v[224:225], s[94:95], 0, v[170:171]
	s_add_i32 m0, s93, 0x2000
	s_mov_b64 s[94:95], s[18:19]
	global_load_lds_dwordx4 v[224:225], off
	s_mov_b32 m0, s67
	v_lshl_add_u64 v[224:225], s[94:95], 0, v[196:197]
	global_load_lds_dwordx4 v[224:225], off
	v_lshl_add_u64 v[224:225], s[94:95], 0, v[172:173]
	s_mov_b32 m0, s68
	s_nop 0
	global_load_lds_dwordx4 v[224:225], off
	s_waitcnt vmcnt(8)
	s_waitcnt lgkmcnt(0)
	s_barrier
	s_setprio 1
	s_waitcnt lgkmcnt(0)
	v_mfma_f32_16x16x32_bf16 v[62:65], v[66:69], v[162:165], v[62:65]
	v_mfma_f32_16x16x32_bf16 v[58:61], v[74:77], v[162:165], v[58:61]
	v_mfma_f32_16x16x32_bf16 v[46:49], v[66:69], v[198:201], v[46:49]
	v_mfma_f32_16x16x32_bf16 v[42:45], v[74:77], v[198:201], v[42:45]
	v_mfma_f32_16x16x32_bf16 v[30:33], v[66:69], v[206:209], v[30:33]
	v_mfma_f32_16x16x32_bf16 v[26:29], v[74:77], v[206:209], v[26:29]
	v_mfma_f32_16x16x32_bf16 v[14:17], v[66:69], v[214:217], v[14:17]
	v_mfma_f32_16x16x32_bf16 v[10:13], v[74:77], v[214:217], v[10:13]
	v_mfma_f32_16x16x32_bf16 v[62:65], v[70:73], v[166:169], v[62:65]
	v_mfma_f32_16x16x32_bf16 v[58:61], v[78:81], v[166:169], v[58:61]
	v_mfma_f32_16x16x32_bf16 v[46:49], v[70:73], v[202:205], v[46:49]
	v_mfma_f32_16x16x32_bf16 v[42:45], v[78:81], v[202:205], v[42:45]
	v_mfma_f32_16x16x32_bf16 v[30:33], v[70:73], v[210:213], v[30:33]
	v_mfma_f32_16x16x32_bf16 v[26:29], v[78:81], v[210:213], v[26:29]
	v_mfma_f32_16x16x32_bf16 v[14:17], v[70:73], v[218:221], v[14:17]
	v_mfma_f32_16x16x32_bf16 v[10:13], v[78:81], v[218:221], v[10:13]
	v_mfma_f32_16x16x32_bf16 v[54:57], v[146:149], v[162:165], v[54:57]
	v_mfma_f32_16x16x32_bf16 v[50:53], v[154:157], v[162:165], v[50:53]
	v_mfma_f32_16x16x32_bf16 v[38:41], v[146:149], v[198:201], v[38:41]
	v_mfma_f32_16x16x32_bf16 v[34:37], v[154:157], v[198:201], v[34:37]
	v_mfma_f32_16x16x32_bf16 v[22:25], v[146:149], v[206:209], v[22:25]
	v_mfma_f32_16x16x32_bf16 v[18:21], v[154:157], v[206:209], v[18:21]
	v_mfma_f32_16x16x32_bf16 v[6:9], v[146:149], v[214:217], v[6:9]
	v_mfma_f32_16x16x32_bf16 v[2:5], v[154:157], v[214:217], v[2:5]
	v_mfma_f32_16x16x32_bf16 v[54:57], v[150:153], v[166:169], v[54:57]
	v_mfma_f32_16x16x32_bf16 v[50:53], v[158:161], v[166:169], v[50:53]
	v_mfma_f32_16x16x32_bf16 v[38:41], v[150:153], v[202:205], v[38:41]
	v_mfma_f32_16x16x32_bf16 v[34:37], v[158:161], v[202:205], v[34:37]
	v_mfma_f32_16x16x32_bf16 v[22:25], v[150:153], v[210:213], v[22:25]
	v_mfma_f32_16x16x32_bf16 v[18:21], v[158:161], v[210:213], v[18:21]
	v_mfma_f32_16x16x32_bf16 v[6:9], v[150:153], v[218:221], v[6:9]
	v_mfma_f32_16x16x32_bf16 v[2:5], v[158:161], v[218:221], v[2:5]
	s_setprio 0
	s_barrier
	s_add_i32 s93, 0, 0x18000
	v_add_u32_e32 v0, s93, v222
	s_add_i32 s94, 0, 0x1c000
	ds_read_b128 v[66:69], v0
	ds_read_b128 v[70:73], v0 offset:1024
	ds_read_b128 v[74:77], v0 offset:2048
	ds_read_b128 v[78:81], v0 offset:3072
	v_add_u32_e32 v0, s94, v222
	ds_read_b128 v[146:149], v0
	ds_read_b128 v[150:153], v0 offset:1024
	ds_read_b128 v[154:157], v0 offset:2048
	ds_read_b128 v[158:161], v0 offset:3072
	s_add_u32 s18, s18, 0x40000
	s_addc_u32 s19, s19, 0
	s_mov_b32 m0, s69
	ds_read_b128 v[162:165], v223 offset:32768
	ds_read_b128 v[166:169], v223 offset:33792
	ds_read_b128 v[198:201], v223 offset:34816
	ds_read_b128 v[202:205], v223 offset:35840
	ds_read_b128 v[206:209], v223 offset:36864
	ds_read_b128 v[210:213], v223 offset:37888
	ds_read_b128 v[214:217], v223 offset:38912
	ds_read_b128 v[218:221], v223 offset:39936
	s_nop 0
	v_lshl_add_u64 v[224:225], s[18:19], 0, v[196:197]
	global_load_lds_dwordx4 v[224:225], off
	v_lshl_add_u64 v[224:225], s[18:19], 0, v[172:173]
	s_mov_b32 m0, s70
	s_nop 0
	global_load_lds_dwordx4 v[224:225], off
	s_waitcnt vmcnt(8)
	s_waitcnt lgkmcnt(0)
	s_barrier
	s_setprio 1
	s_waitcnt lgkmcnt(0)
	v_mfma_f32_16x16x32_bf16 v[138:141], v[66:69], v[162:165], v[138:141]
	v_mfma_f32_16x16x32_bf16 v[142:145], v[74:77], v[162:165], v[142:145]
	v_mfma_f32_16x16x32_bf16 v[126:129], v[66:69], v[198:201], v[126:129]
	v_mfma_f32_16x16x32_bf16 v[122:125], v[74:77], v[198:201], v[122:125]
	v_mfma_f32_16x16x32_bf16 v[110:113], v[66:69], v[206:209], v[110:113]
	v_mfma_f32_16x16x32_bf16 v[106:109], v[74:77], v[206:209], v[106:109]
	v_mfma_f32_16x16x32_bf16 v[94:97], v[66:69], v[214:217], v[94:97]
	v_mfma_f32_16x16x32_bf16 v[90:93], v[74:77], v[214:217], v[90:93]
	v_mfma_f32_16x16x32_bf16 v[138:141], v[70:73], v[166:169], v[138:141]
	v_mfma_f32_16x16x32_bf16 v[142:145], v[78:81], v[166:169], v[142:145]
	v_mfma_f32_16x16x32_bf16 v[126:129], v[70:73], v[202:205], v[126:129]
	v_mfma_f32_16x16x32_bf16 v[122:125], v[78:81], v[202:205], v[122:125]
	v_mfma_f32_16x16x32_bf16 v[110:113], v[70:73], v[210:213], v[110:113]
	v_mfma_f32_16x16x32_bf16 v[106:109], v[78:81], v[210:213], v[106:109]
	v_mfma_f32_16x16x32_bf16 v[94:97], v[70:73], v[218:221], v[94:97]
	v_mfma_f32_16x16x32_bf16 v[90:93], v[78:81], v[218:221], v[90:93]
	v_mfma_f32_16x16x32_bf16 v[134:137], v[146:149], v[162:165], v[134:137]
	v_mfma_f32_16x16x32_bf16 v[130:133], v[154:157], v[162:165], v[130:133]
	v_mfma_f32_16x16x32_bf16 v[118:121], v[146:149], v[198:201], v[118:121]
	v_mfma_f32_16x16x32_bf16 v[114:117], v[154:157], v[198:201], v[114:117]
	v_mfma_f32_16x16x32_bf16 v[102:105], v[146:149], v[206:209], v[102:105]
	v_mfma_f32_16x16x32_bf16 v[98:101], v[154:157], v[206:209], v[98:101]
	v_mfma_f32_16x16x32_bf16 v[86:89], v[146:149], v[214:217], v[86:89]
	v_mfma_f32_16x16x32_bf16 v[82:85], v[154:157], v[214:217], v[82:85]
	v_mfma_f32_16x16x32_bf16 v[134:137], v[150:153], v[166:169], v[134:137]
	v_mfma_f32_16x16x32_bf16 v[130:133], v[158:161], v[166:169], v[130:133]
	v_mfma_f32_16x16x32_bf16 v[118:121], v[150:153], v[202:205], v[118:121]
	v_mfma_f32_16x16x32_bf16 v[114:117], v[158:161], v[202:205], v[114:117]
	v_mfma_f32_16x16x32_bf16 v[102:105], v[150:153], v[210:213], v[102:105]
	v_mfma_f32_16x16x32_bf16 v[98:101], v[158:161], v[210:213], v[98:101]
	v_mfma_f32_16x16x32_bf16 v[86:89], v[150:153], v[218:221], v[86:89]
	v_mfma_f32_16x16x32_bf16 v[82:85], v[158:161], v[218:221], v[82:85]
	s_setprio 0
	s_barrier
	s_add_u32 s18, s72, 0x80
	s_addc_u32 s19, s73, 0
	s_add_i32 s93, s93, s25
	ds_read_b128 v[162:165], v223 offset:49152
	ds_read_b128 v[166:169], v223 offset:50176
	ds_read_b128 v[198:201], v223 offset:51200
	ds_read_b128 v[202:205], v223 offset:52224
	ds_read_b128 v[206:209], v223 offset:53248
	ds_read_b128 v[210:213], v223 offset:54272
	ds_read_b128 v[214:217], v223 offset:55296
	ds_read_b128 v[218:221], v223 offset:56320
	s_mov_b32 m0, s93
	v_lshl_add_u64 v[224:225], s[18:19], 0, v[194:195]
	global_load_lds_dwordx4 v[224:225], off
	s_add_i32 m0, s93, 0x2000
	v_lshl_add_u64 v[224:225], s[18:19], 0, v[170:171]
	s_add_u32 s18, s72, 0x40080
	s_addc_u32 s19, s73, 0
	s_add_i32 s72, s94, s25
	global_load_lds_dwordx4 v[224:225], off
	s_mov_b32 m0, s72
	v_lshl_add_u64 v[224:225], s[18:19], 0, v[194:195]
	global_load_lds_dwordx4 v[224:225], off
	v_lshl_add_u64 v[224:225], s[18:19], 0, v[170:171]
	s_add_i32 m0, s72, 0x2000
	s_nop 0
	global_load_lds_dwordx4 v[224:225], off
	s_mov_b32 m0, s82
	v_lshl_add_u64 v[224:225], s[26:27], 0, v[196:197]
	global_load_lds_dwordx4 v[224:225], off
	v_lshl_add_u64 v[224:225], s[26:27], 0, v[172:173]
	s_mov_b32 m0, s83
	s_nop 0
	global_load_lds_dwordx4 v[224:225], off
	s_waitcnt vmcnt(8)
	s_waitcnt lgkmcnt(0)
	s_barrier
	s_setprio 1
	s_waitcnt lgkmcnt(0)
	v_mfma_f32_16x16x32_bf16 v[62:65], v[66:69], v[162:165], v[62:65]
	v_mfma_f32_16x16x32_bf16 v[58:61], v[74:77], v[162:165], v[58:61]
	v_mfma_f32_16x16x32_bf16 v[46:49], v[66:69], v[198:201], v[46:49]
	v_mfma_f32_16x16x32_bf16 v[42:45], v[74:77], v[198:201], v[42:45]
	v_mfma_f32_16x16x32_bf16 v[30:33], v[66:69], v[206:209], v[30:33]
	v_mfma_f32_16x16x32_bf16 v[26:29], v[74:77], v[206:209], v[26:29]
	v_mfma_f32_16x16x32_bf16 v[14:17], v[66:69], v[214:217], v[14:17]
	v_mfma_f32_16x16x32_bf16 v[10:13], v[74:77], v[214:217], v[10:13]
	v_mfma_f32_16x16x32_bf16 v[62:65], v[70:73], v[166:169], v[62:65]
	v_mfma_f32_16x16x32_bf16 v[58:61], v[78:81], v[166:169], v[58:61]
	v_mfma_f32_16x16x32_bf16 v[46:49], v[70:73], v[202:205], v[46:49]
	v_mfma_f32_16x16x32_bf16 v[42:45], v[78:81], v[202:205], v[42:45]
	v_mfma_f32_16x16x32_bf16 v[30:33], v[70:73], v[210:213], v[30:33]
	v_mfma_f32_16x16x32_bf16 v[26:29], v[78:81], v[210:213], v[26:29]
	v_mfma_f32_16x16x32_bf16 v[14:17], v[70:73], v[218:221], v[14:17]
	v_mfma_f32_16x16x32_bf16 v[10:13], v[78:81], v[218:221], v[10:13]
	v_mfma_f32_16x16x32_bf16 v[54:57], v[146:149], v[162:165], v[54:57]
	v_mfma_f32_16x16x32_bf16 v[50:53], v[154:157], v[162:165], v[50:53]
	v_mfma_f32_16x16x32_bf16 v[38:41], v[146:149], v[198:201], v[38:41]
	v_mfma_f32_16x16x32_bf16 v[34:37], v[154:157], v[198:201], v[34:37]
	v_mfma_f32_16x16x32_bf16 v[22:25], v[146:149], v[206:209], v[22:25]
	v_mfma_f32_16x16x32_bf16 v[18:21], v[154:157], v[206:209], v[18:21]
	v_mfma_f32_16x16x32_bf16 v[6:9], v[146:149], v[214:217], v[6:9]
	v_mfma_f32_16x16x32_bf16 v[2:5], v[154:157], v[214:217], v[2:5]
	v_mfma_f32_16x16x32_bf16 v[54:57], v[150:153], v[166:169], v[54:57]
	v_mfma_f32_16x16x32_bf16 v[50:53], v[158:161], v[166:169], v[50:53]
	v_mfma_f32_16x16x32_bf16 v[38:41], v[150:153], v[202:205], v[38:41]
	v_mfma_f32_16x16x32_bf16 v[34:37], v[158:161], v[202:205], v[34:37]
	v_mfma_f32_16x16x32_bf16 v[22:25], v[150:153], v[210:213], v[22:25]
	v_mfma_f32_16x16x32_bf16 v[18:21], v[158:161], v[210:213], v[18:21]
	v_mfma_f32_16x16x32_bf16 v[6:9], v[150:153], v[218:221], v[6:9]
	v_mfma_f32_16x16x32_bf16 v[2:5], v[158:161], v[218:221], v[2:5]
	s_setprio 0
	s_barrier
	s_add_u32 vcc_lo, vcc_lo, 0x100
	s_addc_u32 vcc_hi, vcc_hi, 0
	s_add_u32 s90, s90, 0x100
	s_addc_u32 s91, s91, 0
	s_add_u32 s2, s2, 0x100
	s_addc_u32 s3, s3, 0
	s_cmp_ge_i32 s92, s41
	s_mov_b32 s18, s92
	s_cbranch_scc0 .LBB0_691
	s_movk_i32 s90, 0x80
	s_mov_b32 s91, 0x10000
	s_mov_b32 s92, 0x12000
	s_mov_b32 s93, 0x14000
	s_mov_b32 s94, 0x16000
	s_movk_i32 s95, 0x4000
	s_movk_i32 s96, 0x3000
	s_mov_b32 s72, 0x18000

.LBB0_786:
	s_add_i32 s82, s18, 2
	s_cmp_eq_u32 s71, s18
	s_cselect_b32 s18, s42, s45
	s_cselect_b32 s19, s1, s55
	s_cselect_b32 s36, s44, s63
	s_cselect_b32 s37, s43, s81
	s_add_u32 s26, s18, 0x80
	s_addc_u32 s27, s19, 0
	s_add_i32 s83, 0, 0x10000
	v_add_u32_e32 v0, s83, v214
	s_add_i32 s86, 0, 0x14000
	ds_read_b128 v[58:61], v0
	ds_read_b128 v[66:69], v0 offset:1024
	ds_read_b128 v[74:77], v0 offset:2048
	ds_read_b128 v[78:81], v0 offset:3072
	v_add_u32_e32 v0, s86, v214
	ds_read_b128 v[146:149], v0
	ds_read_b128 v[150:153], v0 offset:1024
	ds_read_b128 v[154:157], v0 offset:2048
	ds_read_b128 v[158:161], v0 offset:3072
	s_add_u32 s84, s45, 0x3ff80
	s_addc_u32 s85, s55, 0
	ds_read_b128 v[162:165], v215
	ds_read_b128 v[194:197], v215 offset:1024
	ds_read_b128 v[198:201], v215 offset:2048
	ds_read_b128 v[202:205], v215 offset:3072
	ds_read_b128 v[206:209], v215 offset:4096
	ds_read_b128 v[210:213], v215 offset:5120
	ds_read_b128 v[216:219], v215 offset:6144
	ds_read_b128 v[220:223], v215 offset:7168
	s_add_i32 m0, s3, 0xc000
	v_lshl_add_u64 v[224:225], s[84:85], 0, v[166:167]
	global_load_lds_dwordx4 v[224:225], off
	v_lshl_add_u64 v[224:225], s[84:85], 0, v[170:171]
	s_add_i32 m0, s3, 0xe000
	s_nop 0
	global_load_lds_dwordx4 v[224:225], off
	s_waitcnt vmcnt(8)
	s_waitcnt lgkmcnt(0)
	s_barrier
	s_setprio 1
	s_waitcnt lgkmcnt(0)
	v_mfma_f32_16x16x32_bf16 v[142:145], v[58:61], v[162:165], v[142:145]
	v_mfma_f32_16x16x32_bf16 v[138:141], v[74:77], v[162:165], v[138:141]
	v_mfma_f32_16x16x32_bf16 v[126:129], v[58:61], v[198:201], v[126:129]
	v_mfma_f32_16x16x32_bf16 v[122:125], v[74:77], v[198:201], v[122:125]
	v_mfma_f32_16x16x32_bf16 v[110:113], v[58:61], v[206:209], v[110:113]
	v_mfma_f32_16x16x32_bf16 v[106:109], v[74:77], v[206:209], v[106:109]
	v_mfma_f32_16x16x32_bf16 v[94:97], v[58:61], v[216:219], v[94:97]
	v_mfma_f32_16x16x32_bf16 v[90:93], v[74:77], v[216:219], v[90:93]
	v_mfma_f32_16x16x32_bf16 v[142:145], v[66:69], v[194:197], v[142:145]
	v_mfma_f32_16x16x32_bf16 v[138:141], v[78:81], v[194:197], v[138:141]
	v_mfma_f32_16x16x32_bf16 v[126:129], v[66:69], v[202:205], v[126:129]
	v_mfma_f32_16x16x32_bf16 v[122:125], v[78:81], v[202:205], v[122:125]
	v_mfma_f32_16x16x32_bf16 v[110:113], v[66:69], v[210:213], v[110:113]
	v_mfma_f32_16x16x32_bf16 v[106:109], v[78:81], v[210:213], v[106:109]
	v_mfma_f32_16x16x32_bf16 v[94:97], v[66:69], v[220:223], v[94:97]
	v_mfma_f32_16x16x32_bf16 v[90:93], v[78:81], v[220:223], v[90:93]
	v_mfma_f32_16x16x32_bf16 v[134:137], v[146:149], v[162:165], v[134:137]
	v_mfma_f32_16x16x32_bf16 v[130:133], v[154:157], v[162:165], v[130:133]
	v_mfma_f32_16x16x32_bf16 v[118:121], v[146:149], v[198:201], v[118:121]
	v_mfma_f32_16x16x32_bf16 v[114:117], v[154:157], v[198:201], v[114:117]
	v_mfma_f32_16x16x32_bf16 v[102:105], v[146:149], v[206:209], v[102:105]
	v_mfma_f32_16x16x32_bf16 v[98:101], v[154:157], v[206:209], v[98:101]
	v_mfma_f32_16x16x32_bf16 v[86:89], v[146:149], v[216:219], v[86:89]
	v_mfma_f32_16x16x32_bf16 v[82:85], v[154:157], v[216:219], v[82:85]
	v_mfma_f32_16x16x32_bf16 v[134:137], v[150:153], v[194:197], v[134:137]
	v_mfma_f32_16x16x32_bf16 v[130:133], v[158:161], v[194:197], v[130:133]
	v_mfma_f32_16x16x32_bf16 v[118:121], v[150:153], v[202:205], v[118:121]
	v_mfma_f32_16x16x32_bf16 v[114:117], v[158:161], v[202:205], v[114:117]
	v_mfma_f32_16x16x32_bf16 v[102:105], v[150:153], v[210:213], v[102:105]
	v_mfma_f32_16x16x32_bf16 v[98:101], v[158:161], v[210:213], v[98:101]
	v_mfma_f32_16x16x32_bf16 v[86:89], v[150:153], v[220:223], v[86:89]
	v_mfma_f32_16x16x32_bf16 v[82:85], v[158:161], v[220:223], v[82:85]
	s_setprio 0
	s_barrier
	s_mov_b64 s[84:85], s[36:37]
	s_add_i32 s83, s83, s25
	ds_read_b128 v[162:165], v215 offset:16384
	ds_read_b128 v[194:197], v215 offset:17408
	ds_read_b128 v[198:201], v215 offset:18432
	ds_read_b128 v[202:205], v215 offset:19456
	ds_read_b128 v[206:209], v215 offset:20480
	ds_read_b128 v[210:213], v215 offset:21504
	ds_read_b128 v[216:219], v215 offset:22528
	ds_read_b128 v[220:223], v215 offset:23552
	s_mov_b32 m0, s83
	v_lshl_add_u64 v[224:225], s[84:85], 0, v[168:169]
	global_load_lds_dwordx4 v[224:225], off
	s_add_i32 m0, s83, 0x2000
	v_lshl_add_u64 v[224:225], s[84:85], 0, v[172:173]
	s_add_u32 s84, s36, 0x40000
	s_addc_u32 s85, s37, 0
	s_add_i32 s83, s86, s25
	global_load_lds_dwordx4 v[224:225], off
	s_mov_b32 m0, s83
	v_lshl_add_u64 v[224:225], s[84:85], 0, v[168:169]
	global_load_lds_dwordx4 v[224:225], off
	v_lshl_add_u64 v[224:225], s[84:85], 0, v[172:173]
	s_add_i32 m0, s83, 0x2000
	s_mov_b64 s[84:85], s[18:19]
	global_load_lds_dwordx4 v[224:225], off
	s_mov_b32 m0, s3
	v_lshl_add_u64 v[224:225], s[84:85], 0, v[166:167]
	global_load_lds_dwordx4 v[224:225], off
	v_lshl_add_u64 v[224:225], s[84:85], 0, v[170:171]
	s_mov_b32 m0, s39
	s_nop 0
	global_load_lds_dwordx4 v[224:225], off
	s_waitcnt vmcnt(8)
	s_waitcnt lgkmcnt(0)
	s_barrier
	s_setprio 1
	s_waitcnt lgkmcnt(0)
	v_mfma_f32_16x16x32_bf16 v[70:73], v[58:61], v[162:165], v[70:73]
	v_mfma_f32_16x16x32_bf16 v[62:65], v[74:77], v[162:165], v[62:65]
	v_mfma_f32_16x16x32_bf16 v[46:49], v[58:61], v[198:201], v[46:49]
	v_mfma_f32_16x16x32_bf16 v[42:45], v[74:77], v[198:201], v[42:45]
	v_mfma_f32_16x16x32_bf16 v[30:33], v[58:61], v[206:209], v[30:33]
	v_mfma_f32_16x16x32_bf16 v[26:29], v[74:77], v[206:209], v[26:29]
	v_mfma_f32_16x16x32_bf16 v[14:17], v[58:61], v[216:219], v[14:17]
	v_mfma_f32_16x16x32_bf16 v[10:13], v[74:77], v[216:219], v[10:13]
	v_mfma_f32_16x16x32_bf16 v[70:73], v[66:69], v[194:197], v[70:73]
	v_mfma_f32_16x16x32_bf16 v[62:65], v[78:81], v[194:197], v[62:65]
	v_mfma_f32_16x16x32_bf16 v[46:49], v[66:69], v[202:205], v[46:49]
	v_mfma_f32_16x16x32_bf16 v[42:45], v[78:81], v[202:205], v[42:45]
	v_mfma_f32_16x16x32_bf16 v[30:33], v[66:69], v[210:213], v[30:33]
	v_mfma_f32_16x16x32_bf16 v[26:29], v[78:81], v[210:213], v[26:29]
	v_mfma_f32_16x16x32_bf16 v[14:17], v[66:69], v[220:223], v[14:17]
	v_mfma_f32_16x16x32_bf16 v[10:13], v[78:81], v[220:223], v[10:13]
	v_mfma_f32_16x16x32_bf16 v[54:57], v[146:149], v[162:165], v[54:57]
	v_mfma_f32_16x16x32_bf16 v[50:53], v[154:157], v[162:165], v[50:53]
	v_mfma_f32_16x16x32_bf16 v[38:41], v[146:149], v[198:201], v[38:41]
	v_mfma_f32_16x16x32_bf16 v[34:37], v[154:157], v[198:201], v[34:37]
	v_mfma_f32_16x16x32_bf16 v[22:25], v[146:149], v[206:209], v[22:25]
	v_mfma_f32_16x16x32_bf16 v[18:21], v[154:157], v[206:209], v[18:21]
	v_mfma_f32_16x16x32_bf16 v[6:9], v[146:149], v[216:219], v[6:9]
	v_mfma_f32_16x16x32_bf16 v[2:5], v[154:157], v[216:219], v[2:5]
	v_mfma_f32_16x16x32_bf16 v[54:57], v[150:153], v[194:197], v[54:57]
	v_mfma_f32_16x16x32_bf16 v[50:53], v[158:161], v[194:197], v[50:53]
	v_mfma_f32_16x16x32_bf16 v[38:41], v[150:153], v[202:205], v[38:41]
	v_mfma_f32_16x16x32_bf16 v[34:37], v[158:161], v[202:205], v[34:37]
	v_mfma_f32_16x16x32_bf16 v[22:25], v[150:153], v[210:213], v[22:25]
	v_mfma_f32_16x16x32_bf16 v[18:21], v[158:161], v[210:213], v[18:21]
	v_mfma_f32_16x16x32_bf16 v[6:9], v[150:153], v[220:223], v[6:9]
	v_mfma_f32_16x16x32_bf16 v[2:5], v[158:161], v[220:223], v[2:5]
	s_setprio 0
	s_barrier
	s_add_i32 s83, 0, 0x18000
	v_add_u32_e32 v0, s83, v214
	s_add_i32 s84, 0, 0x1c000
	ds_read_b128 v[58:61], v0
	ds_read_b128 v[66:69], v0 offset:1024
	ds_read_b128 v[74:77], v0 offset:2048
	ds_read_b128 v[78:81], v0 offset:3072
	v_add_u32_e32 v0, s84, v214
	ds_read_b128 v[146:149], v0
	ds_read_b128 v[150:153], v0 offset:1024
	ds_read_b128 v[154:157], v0 offset:2048
	ds_read_b128 v[158:161], v0 offset:3072
	s_add_u32 s18, s18, 0x40000
	s_addc_u32 s19, s19, 0
	s_mov_b32 m0, s67
	ds_read_b128 v[162:165], v215 offset:32768
	ds_read_b128 v[194:197], v215 offset:33792
	ds_read_b128 v[198:201], v215 offset:34816
	ds_read_b128 v[202:205], v215 offset:35840
	ds_read_b128 v[206:209], v215 offset:36864
	ds_read_b128 v[210:213], v215 offset:37888
	ds_read_b128 v[216:219], v215 offset:38912
	ds_read_b128 v[220:223], v215 offset:39936
	s_nop 0
	v_lshl_add_u64 v[224:225], s[18:19], 0, v[166:167]
	global_load_lds_dwordx4 v[224:225], off
	v_lshl_add_u64 v[224:225], s[18:19], 0, v[170:171]
	s_mov_b32 m0, s68
	s_nop 0
	global_load_lds_dwordx4 v[224:225], off
	s_waitcnt vmcnt(8)
	s_waitcnt lgkmcnt(0)
	s_barrier
	s_setprio 1
	s_waitcnt lgkmcnt(0)
	v_mfma_f32_16x16x32_bf16 v[142:145], v[58:61], v[162:165], v[142:145]
	v_mfma_f32_16x16x32_bf16 v[138:141], v[74:77], v[162:165], v[138:141]
	v_mfma_f32_16x16x32_bf16 v[126:129], v[58:61], v[198:201], v[126:129]
	v_mfma_f32_16x16x32_bf16 v[122:125], v[74:77], v[198:201], v[122:125]
	v_mfma_f32_16x16x32_bf16 v[110:113], v[58:61], v[206:209], v[110:113]
	v_mfma_f32_16x16x32_bf16 v[106:109], v[74:77], v[206:209], v[106:109]
	v_mfma_f32_16x16x32_bf16 v[94:97], v[58:61], v[216:219], v[94:97]
	v_mfma_f32_16x16x32_bf16 v[90:93], v[74:77], v[216:219], v[90:93]
	v_mfma_f32_16x16x32_bf16 v[142:145], v[66:69], v[194:197], v[142:145]
	v_mfma_f32_16x16x32_bf16 v[138:141], v[78:81], v[194:197], v[138:141]
	v_mfma_f32_16x16x32_bf16 v[126:129], v[66:69], v[202:205], v[126:129]
	v_mfma_f32_16x16x32_bf16 v[122:125], v[78:81], v[202:205], v[122:125]
	v_mfma_f32_16x16x32_bf16 v[110:113], v[66:69], v[210:213], v[110:113]
	v_mfma_f32_16x16x32_bf16 v[106:109], v[78:81], v[210:213], v[106:109]
	v_mfma_f32_16x16x32_bf16 v[94:97], v[66:69], v[220:223], v[94:97]
	v_mfma_f32_16x16x32_bf16 v[90:93], v[78:81], v[220:223], v[90:93]
	v_mfma_f32_16x16x32_bf16 v[134:137], v[146:149], v[162:165], v[134:137]
	v_mfma_f32_16x16x32_bf16 v[130:133], v[154:157], v[162:165], v[130:133]
	v_mfma_f32_16x16x32_bf16 v[118:121], v[146:149], v[198:201], v[118:121]
	v_mfma_f32_16x16x32_bf16 v[114:117], v[154:157], v[198:201], v[114:117]
	v_mfma_f32_16x16x32_bf16 v[102:105], v[146:149], v[206:209], v[102:105]
	v_mfma_f32_16x16x32_bf16 v[98:101], v[154:157], v[206:209], v[98:101]
	v_mfma_f32_16x16x32_bf16 v[86:89], v[146:149], v[216:219], v[86:89]
	v_mfma_f32_16x16x32_bf16 v[82:85], v[154:157], v[216:219], v[82:85]
	v_mfma_f32_16x16x32_bf16 v[134:137], v[150:153], v[194:197], v[134:137]
	v_mfma_f32_16x16x32_bf16 v[130:133], v[158:161], v[194:197], v[130:133]
	v_mfma_f32_16x16x32_bf16 v[118:121], v[150:153], v[202:205], v[118:121]
	v_mfma_f32_16x16x32_bf16 v[114:117], v[158:161], v[202:205], v[114:117]
	v_mfma_f32_16x16x32_bf16 v[102:105], v[150:153], v[210:213], v[102:105]
	v_mfma_f32_16x16x32_bf16 v[98:101], v[158:161], v[210:213], v[98:101]
	v_mfma_f32_16x16x32_bf16 v[86:89], v[150:153], v[220:223], v[86:89]
	v_mfma_f32_16x16x32_bf16 v[82:85], v[158:161], v[220:223], v[82:85]
	s_setprio 0
	s_barrier
	s_add_u32 s18, s36, 0x80
	s_addc_u32 s19, s37, 0
	s_add_i32 s83, s83, s25
	ds_read_b128 v[162:165], v215 offset:49152
	ds_read_b128 v[194:197], v215 offset:50176
	ds_read_b128 v[198:201], v215 offset:51200
	ds_read_b128 v[202:205], v215 offset:52224
	ds_read_b128 v[206:209], v215 offset:53248
	ds_read_b128 v[210:213], v215 offset:54272
	ds_read_b128 v[216:219], v215 offset:55296
	ds_read_b128 v[220:223], v215 offset:56320
	s_mov_b32 m0, s83
	v_lshl_add_u64 v[224:225], s[18:19], 0, v[168:169]
	global_load_lds_dwordx4 v[224:225], off
	s_add_i32 m0, s83, 0x2000
	v_lshl_add_u64 v[224:225], s[18:19], 0, v[172:173]
	s_add_u32 s18, s36, 0x40080
	s_addc_u32 s19, s37, 0
	s_add_i32 s36, s84, s25
	global_load_lds_dwordx4 v[224:225], off
	s_mov_b32 m0, s36
	v_lshl_add_u64 v[224:225], s[18:19], 0, v[168:169]
	global_load_lds_dwordx4 v[224:225], off
	v_lshl_add_u64 v[224:225], s[18:19], 0, v[172:173]
	s_add_i32 m0, s36, 0x2000
	s_nop 0
	global_load_lds_dwordx4 v[224:225], off
	s_mov_b32 m0, s72
	v_lshl_add_u64 v[224:225], s[26:27], 0, v[166:167]
	global_load_lds_dwordx4 v[224:225], off
	v_lshl_add_u64 v[224:225], s[26:27], 0, v[170:171]
	s_mov_b32 m0, s73
	s_nop 0
	global_load_lds_dwordx4 v[224:225], off
	s_waitcnt vmcnt(8)
	s_waitcnt lgkmcnt(0)
	s_barrier
	s_setprio 1
	s_waitcnt lgkmcnt(0)
	v_mfma_f32_16x16x32_bf16 v[70:73], v[58:61], v[162:165], v[70:73]
	v_mfma_f32_16x16x32_bf16 v[62:65], v[74:77], v[162:165], v[62:65]
	v_mfma_f32_16x16x32_bf16 v[46:49], v[58:61], v[198:201], v[46:49]
	v_mfma_f32_16x16x32_bf16 v[42:45], v[74:77], v[198:201], v[42:45]
	v_mfma_f32_16x16x32_bf16 v[30:33], v[58:61], v[206:209], v[30:33]
	v_mfma_f32_16x16x32_bf16 v[26:29], v[74:77], v[206:209], v[26:29]
	v_mfma_f32_16x16x32_bf16 v[14:17], v[58:61], v[216:219], v[14:17]
	v_mfma_f32_16x16x32_bf16 v[10:13], v[74:77], v[216:219], v[10:13]
	v_mfma_f32_16x16x32_bf16 v[70:73], v[66:69], v[194:197], v[70:73]
	v_mfma_f32_16x16x32_bf16 v[62:65], v[78:81], v[194:197], v[62:65]
	v_mfma_f32_16x16x32_bf16 v[46:49], v[66:69], v[202:205], v[46:49]
	v_mfma_f32_16x16x32_bf16 v[42:45], v[78:81], v[202:205], v[42:45]
	v_mfma_f32_16x16x32_bf16 v[30:33], v[66:69], v[210:213], v[30:33]
	v_mfma_f32_16x16x32_bf16 v[26:29], v[78:81], v[210:213], v[26:29]
	v_mfma_f32_16x16x32_bf16 v[14:17], v[66:69], v[220:223], v[14:17]
	v_mfma_f32_16x16x32_bf16 v[10:13], v[78:81], v[220:223], v[10:13]
	v_mfma_f32_16x16x32_bf16 v[54:57], v[146:149], v[162:165], v[54:57]
	v_mfma_f32_16x16x32_bf16 v[50:53], v[154:157], v[162:165], v[50:53]
	v_mfma_f32_16x16x32_bf16 v[38:41], v[146:149], v[198:201], v[38:41]
	v_mfma_f32_16x16x32_bf16 v[34:37], v[154:157], v[198:201], v[34:37]
	v_mfma_f32_16x16x32_bf16 v[22:25], v[146:149], v[206:209], v[22:25]
	v_mfma_f32_16x16x32_bf16 v[18:21], v[154:157], v[206:209], v[18:21]
	v_mfma_f32_16x16x32_bf16 v[6:9], v[146:149], v[216:219], v[6:9]
	v_mfma_f32_16x16x32_bf16 v[2:5], v[154:157], v[216:219], v[2:5]
	v_mfma_f32_16x16x32_bf16 v[54:57], v[150:153], v[194:197], v[54:57]
	v_mfma_f32_16x16x32_bf16 v[50:53], v[158:161], v[194:197], v[50:53]
	v_mfma_f32_16x16x32_bf16 v[38:41], v[150:153], v[202:205], v[38:41]
	v_mfma_f32_16x16x32_bf16 v[34:37], v[158:161], v[202:205], v[34:37]
	v_mfma_f32_16x16x32_bf16 v[22:25], v[150:153], v[210:213], v[22:25]
	v_mfma_f32_16x16x32_bf16 v[18:21], v[158:161], v[210:213], v[18:21]
	v_mfma_f32_16x16x32_bf16 v[6:9], v[150:153], v[220:223], v[6:9]
	v_mfma_f32_16x16x32_bf16 v[2:5], v[158:161], v[220:223], v[2:5]
	s_setprio 0
	s_barrier
	s_add_u32 s45, s45, 0x100
	s_addc_u32 s55, s55, 0
	s_add_u32 s63, s63, 0x100
	s_addc_u32 s81, s81, 0
	s_cmp_ge_i32 s82, s78
	s_mov_b32 s18, s82
	s_cbranch_scc0 .LBB0_786
	s_mov_b32 s81, 0xc000
	s_mov_b32 s82, 0xe000
	s_mov_b32 s83, 0xb000
	s_mov_b32 s84, 0x4ffff
	s_mov_b32 s85, 0x66666667
	s_mov_b32 s86, 0x1f000

.LBB0_998:
	s_add_i32 s84, s2, 2
	s_cmp_eq_u32 s68, s2
	s_cselect_b32 s18, s63, s80
	s_cselect_b32 s19, s51, s81
	s_cselect_b32 s26, s79, s82
	s_cselect_b32 s27, s78, s83
	s_add_u32 s2, s18, 0x80
	s_addc_u32 s3, s19, 0
	s_add_i32 s85, 0, 0x10000
	s_add_i32 s88, 0, 0x14000
	v_add_u32_e32 v86, s85, v224
	v_add_u32_e32 v158, s88, v224
	ds_read_b128 v[66:69], v86
	ds_read_b128 v[70:73], v86 offset:1024
	ds_read_b128 v[74:77], v86 offset:2048
	ds_read_b128 v[86:89], v86 offset:3072
	ds_read_b128 v[98:101], v158
	ds_read_b128 v[110:113], v158 offset:1024
	ds_read_b128 v[122:125], v158 offset:2048
	ds_read_b128 v[158:161], v158 offset:3072
	s_add_u32 s86, s80, 0x3ff80
	s_addc_u32 s87, s81, 0
	ds_read_b128 v[162:165], v225
	ds_read_b128 v[166:169], v225 offset:1024
	ds_read_b128 v[170:173], v225 offset:2048
	ds_read_b128 v[200:203], v225 offset:3072
	ds_read_b128 v[204:207], v225 offset:4096
	ds_read_b128 v[208:211], v225 offset:5120
	ds_read_b128 v[212:215], v225 offset:6144
	ds_read_b128 v[216:219], v225 offset:7168
	s_add_i32 m0, s55, 0xc000
	v_lshl_add_u64 v[220:221], s[86:87], 0, v[198:199]
	global_load_lds_dwordx4 v[220:221], off
	v_lshl_add_u64 v[220:221], s[86:87], 0, v[196:197]
	s_add_i32 m0, s55, 0xe000
	s_nop 0
	global_load_lds_dwordx4 v[220:221], off
	s_waitcnt vmcnt(8)
	s_waitcnt lgkmcnt(0)
	s_barrier
	s_setprio 1
	s_waitcnt lgkmcnt(0)
	v_mfma_f32_16x16x32_bf16 v[154:157], v[66:69], v[162:165], v[154:157]
	v_mfma_f32_16x16x32_bf16 v[62:65], v[74:77], v[162:165], v[62:65]
	v_mfma_f32_16x16x32_bf16 v[146:149], v[66:69], v[170:173], v[146:149]
	v_mfma_f32_16x16x32_bf16 v[54:57], v[74:77], v[170:173], v[54:57]
	v_mfma_f32_16x16x32_bf16 v[138:141], v[66:69], v[204:207], v[138:141]
	v_mfma_f32_16x16x32_bf16 v[46:49], v[74:77], v[204:207], v[46:49]
	v_mfma_f32_16x16x32_bf16 v[130:133], v[66:69], v[212:215], v[130:133]
	v_mfma_f32_16x16x32_bf16 v[38:41], v[74:77], v[212:215], v[38:41]
	v_mfma_f32_16x16x32_bf16 v[154:157], v[70:73], v[166:169], v[154:157]
	v_mfma_f32_16x16x32_bf16 v[62:65], v[86:89], v[166:169], v[62:65]
	v_mfma_f32_16x16x32_bf16 v[146:149], v[70:73], v[200:203], v[146:149]
	v_mfma_f32_16x16x32_bf16 v[54:57], v[86:89], v[200:203], v[54:57]
	v_mfma_f32_16x16x32_bf16 v[138:141], v[70:73], v[208:211], v[138:141]
	v_mfma_f32_16x16x32_bf16 v[46:49], v[86:89], v[208:211], v[46:49]
	v_mfma_f32_16x16x32_bf16 v[130:133], v[70:73], v[216:219], v[130:133]
	v_mfma_f32_16x16x32_bf16 v[38:41], v[86:89], v[216:219], v[38:41]
	v_mfma_f32_16x16x32_bf16 v[150:153], v[98:101], v[162:165], v[150:153]
	v_mfma_f32_16x16x32_bf16 v[58:61], v[122:125], v[162:165], v[58:61]
	v_mfma_f32_16x16x32_bf16 v[142:145], v[98:101], v[170:173], v[142:145]
	v_mfma_f32_16x16x32_bf16 v[50:53], v[122:125], v[170:173], v[50:53]
	v_mfma_f32_16x16x32_bf16 v[134:137], v[98:101], v[204:207], v[134:137]
	v_mfma_f32_16x16x32_bf16 v[42:45], v[122:125], v[204:207], v[42:45]
	v_mfma_f32_16x16x32_bf16 v[126:129], v[98:101], v[212:215], v[126:129]
	v_mfma_f32_16x16x32_bf16 v[34:37], v[122:125], v[212:215], v[34:37]
	v_mfma_f32_16x16x32_bf16 v[150:153], v[110:113], v[166:169], v[150:153]
	v_mfma_f32_16x16x32_bf16 v[58:61], v[158:161], v[166:169], v[58:61]
	v_mfma_f32_16x16x32_bf16 v[142:145], v[110:113], v[200:203], v[142:145]
	v_mfma_f32_16x16x32_bf16 v[50:53], v[158:161], v[200:203], v[50:53]
	v_mfma_f32_16x16x32_bf16 v[134:137], v[110:113], v[208:211], v[134:137]
	v_mfma_f32_16x16x32_bf16 v[42:45], v[158:161], v[208:211], v[42:45]
	v_mfma_f32_16x16x32_bf16 v[126:129], v[110:113], v[216:219], v[126:129]
	v_mfma_f32_16x16x32_bf16 v[34:37], v[158:161], v[216:219], v[34:37]
	s_setprio 0
	s_barrier
	s_mov_b64 s[86:87], s[26:27]
	s_add_i32 s85, s85, s37
	ds_read_b128 v[162:165], v225 offset:16384
	ds_read_b128 v[166:169], v225 offset:17408
	ds_read_b128 v[170:173], v225 offset:18432
	ds_read_b128 v[200:203], v225 offset:19456
	ds_read_b128 v[204:207], v225 offset:20480
	ds_read_b128 v[208:211], v225 offset:21504
	ds_read_b128 v[212:215], v225 offset:22528
	ds_read_b128 v[216:219], v225 offset:23552
	s_mov_b32 m0, s85
	v_lshl_add_u64 v[220:221], s[86:87], 0, v[0:1]
	global_load_lds_dwordx4 v[220:221], off
	s_add_i32 m0, s85, 0x2000
	v_lshl_add_u64 v[220:221], s[86:87], 0, v[194:195]
	s_add_u32 s86, s26, 0x8000
	s_addc_u32 s87, s27, 0
	s_add_i32 s85, s88, s37
	global_load_lds_dwordx4 v[220:221], off
	s_mov_b32 m0, s85
	v_lshl_add_u64 v[220:221], s[86:87], 0, v[0:1]
	global_load_lds_dwordx4 v[220:221], off
	v_lshl_add_u64 v[220:221], s[86:87], 0, v[194:195]
	s_add_i32 m0, s85, 0x2000
	s_mov_b64 s[86:87], s[18:19]
	global_load_lds_dwordx4 v[220:221], off
	s_mov_b32 m0, s55
	v_lshl_add_u64 v[220:221], s[86:87], 0, v[198:199]
	global_load_lds_dwordx4 v[220:221], off
	v_lshl_add_u64 v[220:221], s[86:87], 0, v[196:197]
	s_mov_b32 m0, s70
	s_nop 0
	global_load_lds_dwordx4 v[220:221], off
	s_waitcnt vmcnt(8)
	s_waitcnt lgkmcnt(0)
	s_barrier
	s_setprio 1
	s_waitcnt lgkmcnt(0)
	v_mfma_f32_16x16x32_bf16 v[118:121], v[66:69], v[162:165], v[118:121]
	v_mfma_f32_16x16x32_bf16 v[30:33], v[74:77], v[162:165], v[30:33]
	v_mfma_f32_16x16x32_bf16 v[106:109], v[66:69], v[170:173], v[106:109]
	v_mfma_f32_16x16x32_bf16 v[22:25], v[74:77], v[170:173], v[22:25]
	v_mfma_f32_16x16x32_bf16 v[94:97], v[66:69], v[204:207], v[94:97]
	v_mfma_f32_16x16x32_bf16 v[14:17], v[74:77], v[204:207], v[14:17]
	v_mfma_f32_16x16x32_bf16 v[6:9], v[74:77], v[212:215], v[6:9]
	v_mfma_f32_16x16x32_bf16 v[118:121], v[70:73], v[166:169], v[118:121]
	v_mfma_f32_16x16x32_bf16 v[30:33], v[86:89], v[166:169], v[30:33]
	v_mfma_f32_16x16x32_bf16 v[106:109], v[70:73], v[200:203], v[106:109]
	v_mfma_f32_16x16x32_bf16 v[22:25], v[86:89], v[200:203], v[22:25]
	v_mfma_f32_16x16x32_bf16 v[94:97], v[70:73], v[208:211], v[94:97]
	v_mfma_f32_16x16x32_bf16 v[14:17], v[86:89], v[208:211], v[14:17]
	v_mfma_f32_16x16x32_bf16 v[66:69], v[66:69], v[212:215], v[82:85]
	v_mfma_f32_16x16x32_bf16 v[6:9], v[86:89], v[216:219], v[6:9]
	v_mfma_f32_16x16x32_bf16 v[66:69], v[70:73], v[216:219], v[66:69]
	v_mfma_f32_16x16x32_bf16 v[26:29], v[122:125], v[162:165], v[26:29]
	v_mfma_f32_16x16x32_bf16 v[18:21], v[122:125], v[170:173], v[18:21]
	v_mfma_f32_16x16x32_bf16 v[10:13], v[122:125], v[204:207], v[10:13]
	v_mfma_f32_16x16x32_bf16 v[78:81], v[98:101], v[212:215], v[78:81]
	v_mfma_f32_16x16x32_bf16 v[2:5], v[122:125], v[212:215], v[2:5]
	v_mfma_f32_16x16x32_bf16 v[70:73], v[98:101], v[162:165], v[114:117]
	v_mfma_f32_16x16x32_bf16 v[26:29], v[158:161], v[166:169], v[26:29]
	v_mfma_f32_16x16x32_bf16 v[74:77], v[98:101], v[170:173], v[102:105]
	v_mfma_f32_16x16x32_bf16 v[18:21], v[158:161], v[200:203], v[18:21]
	v_mfma_f32_16x16x32_bf16 v[82:85], v[98:101], v[204:207], v[90:93]
	v_mfma_f32_16x16x32_bf16 v[10:13], v[158:161], v[208:211], v[10:13]
	v_mfma_f32_16x16x32_bf16 v[78:81], v[110:113], v[216:219], v[78:81]
	v_mfma_f32_16x16x32_bf16 v[2:5], v[158:161], v[216:219], v[2:5]
	v_mfma_f32_16x16x32_bf16 v[70:73], v[110:113], v[166:169], v[70:73]
	v_mfma_f32_16x16x32_bf16 v[74:77], v[110:113], v[200:203], v[74:77]
	v_mfma_f32_16x16x32_bf16 v[86:89], v[110:113], v[208:211], v[82:85]
	s_setprio 0
	s_barrier
	s_add_i32 s85, 0, 0x18000
	s_add_i32 s86, 0, 0x1c000
	v_add_u32_e32 v102, s85, v224
	v_add_u32_e32 v114, s86, v224
	ds_read_b128 v[82:85], v102
	ds_read_b128 v[90:93], v102 offset:1024
	ds_read_b128 v[98:101], v102 offset:2048
	ds_read_b128 v[102:105], v102 offset:3072
	ds_read_b128 v[110:113], v114
	ds_read_b128 v[122:125], v114 offset:1024
	ds_read_b128 v[158:161], v114 offset:2048
	ds_read_b128 v[162:165], v114 offset:3072
	s_add_u32 s18, s18, 0x40000
	s_addc_u32 s19, s19, 0
	s_mov_b32 m0, s71
	ds_read_b128 v[114:117], v225 offset:32768
	ds_read_b128 v[166:169], v225 offset:33792
	ds_read_b128 v[170:173], v225 offset:34816
	ds_read_b128 v[200:203], v225 offset:35840
	ds_read_b128 v[204:207], v225 offset:36864
	ds_read_b128 v[208:211], v225 offset:37888
	ds_read_b128 v[212:215], v225 offset:38912
	ds_read_b128 v[216:219], v225 offset:39936
	s_nop 0
	v_lshl_add_u64 v[220:221], s[18:19], 0, v[198:199]
	global_load_lds_dwordx4 v[220:221], off
	v_lshl_add_u64 v[220:221], s[18:19], 0, v[196:197]
	s_mov_b32 m0, s72
	s_nop 0
	global_load_lds_dwordx4 v[220:221], off
	s_waitcnt vmcnt(8)
	s_waitcnt lgkmcnt(0)
	s_barrier
	s_setprio 1
	s_waitcnt lgkmcnt(0)
	v_mfma_f32_16x16x32_bf16 v[154:157], v[82:85], v[114:117], v[154:157]
	v_mfma_f32_16x16x32_bf16 v[62:65], v[98:101], v[114:117], v[62:65]
	v_mfma_f32_16x16x32_bf16 v[146:149], v[82:85], v[170:173], v[146:149]
	v_mfma_f32_16x16x32_bf16 v[54:57], v[98:101], v[170:173], v[54:57]
	v_mfma_f32_16x16x32_bf16 v[138:141], v[82:85], v[204:207], v[138:141]
	v_mfma_f32_16x16x32_bf16 v[46:49], v[98:101], v[204:207], v[46:49]
	v_mfma_f32_16x16x32_bf16 v[130:133], v[82:85], v[212:215], v[130:133]
	v_mfma_f32_16x16x32_bf16 v[38:41], v[98:101], v[212:215], v[38:41]
	v_mfma_f32_16x16x32_bf16 v[154:157], v[90:93], v[166:169], v[154:157]
	v_mfma_f32_16x16x32_bf16 v[62:65], v[102:105], v[166:169], v[62:65]
	v_mfma_f32_16x16x32_bf16 v[146:149], v[90:93], v[200:203], v[146:149]
	v_mfma_f32_16x16x32_bf16 v[54:57], v[102:105], v[200:203], v[54:57]
	v_mfma_f32_16x16x32_bf16 v[138:141], v[90:93], v[208:211], v[138:141]
	v_mfma_f32_16x16x32_bf16 v[46:49], v[102:105], v[208:211], v[46:49]
	v_mfma_f32_16x16x32_bf16 v[130:133], v[90:93], v[216:219], v[130:133]
	v_mfma_f32_16x16x32_bf16 v[38:41], v[102:105], v[216:219], v[38:41]
	v_mfma_f32_16x16x32_bf16 v[150:153], v[110:113], v[114:117], v[150:153]
	v_mfma_f32_16x16x32_bf16 v[58:61], v[158:161], v[114:117], v[58:61]
	v_mfma_f32_16x16x32_bf16 v[114:117], v[110:113], v[170:173], v[142:145]
	v_mfma_f32_16x16x32_bf16 v[142:145], v[122:125], v[200:203], v[114:117]
	v_mfma_f32_16x16x32_bf16 v[114:117], v[110:113], v[204:207], v[134:137]
	v_mfma_f32_16x16x32_bf16 v[50:53], v[158:161], v[170:173], v[50:53]
	v_mfma_f32_16x16x32_bf16 v[134:137], v[122:125], v[208:211], v[114:117]
	v_mfma_f32_16x16x32_bf16 v[42:45], v[158:161], v[204:207], v[42:45]
	v_mfma_f32_16x16x32_bf16 v[114:117], v[110:113], v[212:215], v[126:129]
	v_mfma_f32_16x16x32_bf16 v[34:37], v[158:161], v[212:215], v[34:37]
	v_mfma_f32_16x16x32_bf16 v[150:153], v[122:125], v[166:169], v[150:153]
	v_mfma_f32_16x16x32_bf16 v[58:61], v[162:165], v[166:169], v[58:61]
	v_mfma_f32_16x16x32_bf16 v[50:53], v[162:165], v[200:203], v[50:53]
	v_mfma_f32_16x16x32_bf16 v[42:45], v[162:165], v[208:211], v[42:45]
	v_mfma_f32_16x16x32_bf16 v[126:129], v[122:125], v[216:219], v[114:117]
	v_mfma_f32_16x16x32_bf16 v[34:37], v[162:165], v[216:219], v[34:37]
	s_setprio 0
	s_barrier
	s_add_u32 s18, s26, 0x80
	s_addc_u32 s19, s27, 0
	s_add_i32 s85, s85, s37
	ds_read_b128 v[166:169], v225 offset:49152
	ds_read_b128 v[170:173], v225 offset:50176
	ds_read_b128 v[200:203], v225 offset:51200
	ds_read_b128 v[204:207], v225 offset:52224
	ds_read_b128 v[208:211], v225 offset:53248
	ds_read_b128 v[212:215], v225 offset:54272
	ds_read_b128 v[216:219], v225 offset:55296
	ds_read_b128 v[220:223], v225 offset:56320
	s_mov_b32 m0, s85
	v_lshl_add_u64 v[114:115], s[18:19], 0, v[0:1]
	global_load_lds_dwordx4 v[114:115], off
	s_add_i32 m0, s85, 0x2000
	v_lshl_add_u64 v[114:115], s[18:19], 0, v[194:195]
	s_add_u32 s18, s26, 0x8080
	s_addc_u32 s19, s27, 0
	s_add_i32 s26, s86, s37
	global_load_lds_dwordx4 v[114:115], off
	s_mov_b32 m0, s26
	v_lshl_add_u64 v[114:115], s[18:19], 0, v[0:1]
	global_load_lds_dwordx4 v[114:115], off
	v_lshl_add_u64 v[114:115], s[18:19], 0, v[194:195]
	s_add_i32 m0, s26, 0x2000
	s_nop 0
	global_load_lds_dwordx4 v[114:115], off
	s_mov_b32 m0, s69
	v_lshl_add_u64 v[114:115], s[2:3], 0, v[198:199]
	global_load_lds_dwordx4 v[114:115], off
	v_lshl_add_u64 v[114:115], s[2:3], 0, v[196:197]
	s_mov_b32 m0, s25
	s_nop 0
	global_load_lds_dwordx4 v[114:115], off
	s_waitcnt vmcnt(8)
	s_waitcnt lgkmcnt(0)
	s_barrier
	s_setprio 1
	s_waitcnt lgkmcnt(0)
	v_mfma_f32_16x16x32_bf16 v[114:117], v[82:85], v[166:169], v[118:121]
	v_mfma_f32_16x16x32_bf16 v[30:33], v[98:101], v[166:169], v[30:33]
	v_mfma_f32_16x16x32_bf16 v[106:109], v[82:85], v[200:203], v[106:109]
	v_mfma_f32_16x16x32_bf16 v[22:25], v[98:101], v[200:203], v[22:25]
	v_mfma_f32_16x16x32_bf16 v[94:97], v[82:85], v[208:211], v[94:97]
	v_mfma_f32_16x16x32_bf16 v[14:17], v[98:101], v[208:211], v[14:17]
	v_mfma_f32_16x16x32_bf16 v[66:69], v[82:85], v[216:219], v[66:69]
	v_mfma_f32_16x16x32_bf16 v[6:9], v[98:101], v[216:219], v[6:9]
	v_mfma_f32_16x16x32_bf16 v[118:121], v[90:93], v[170:173], v[114:117]
	v_mfma_f32_16x16x32_bf16 v[30:33], v[102:105], v[170:173], v[30:33]
	v_mfma_f32_16x16x32_bf16 v[106:109], v[90:93], v[204:207], v[106:109]
	v_mfma_f32_16x16x32_bf16 v[22:25], v[102:105], v[204:207], v[22:25]
	v_mfma_f32_16x16x32_bf16 v[94:97], v[90:93], v[212:215], v[94:97]
	v_mfma_f32_16x16x32_bf16 v[14:17], v[102:105], v[212:215], v[14:17]
	v_mfma_f32_16x16x32_bf16 v[82:85], v[90:93], v[220:223], v[66:69]
	v_mfma_f32_16x16x32_bf16 v[6:9], v[102:105], v[220:223], v[6:9]
	v_mfma_f32_16x16x32_bf16 v[66:69], v[110:113], v[166:169], v[70:73]
	v_mfma_f32_16x16x32_bf16 v[114:117], v[122:125], v[170:173], v[66:69]
	v_mfma_f32_16x16x32_bf16 v[66:69], v[110:113], v[200:203], v[74:77]
	v_mfma_f32_16x16x32_bf16 v[102:105], v[122:125], v[204:207], v[66:69]
	v_mfma_f32_16x16x32_bf16 v[66:69], v[110:113], v[208:211], v[86:89]
	v_mfma_f32_16x16x32_bf16 v[26:29], v[158:161], v[166:169], v[26:29]
	v_mfma_f32_16x16x32_bf16 v[18:21], v[158:161], v[200:203], v[18:21]
	v_mfma_f32_16x16x32_bf16 v[90:93], v[122:125], v[212:215], v[66:69]
	v_mfma_f32_16x16x32_bf16 v[10:13], v[158:161], v[208:211], v[10:13]
	v_mfma_f32_16x16x32_bf16 v[66:69], v[110:113], v[216:219], v[78:81]
	v_mfma_f32_16x16x32_bf16 v[2:5], v[158:161], v[216:219], v[2:5]
	v_mfma_f32_16x16x32_bf16 v[26:29], v[162:165], v[170:173], v[26:29]
	v_mfma_f32_16x16x32_bf16 v[18:21], v[162:165], v[204:207], v[18:21]
	v_mfma_f32_16x16x32_bf16 v[10:13], v[162:165], v[212:215], v[10:13]
	v_mfma_f32_16x16x32_bf16 v[78:81], v[122:125], v[220:223], v[66:69]
	v_mfma_f32_16x16x32_bf16 v[2:5], v[162:165], v[220:223], v[2:5]
	s_setprio 0
	s_barrier
	s_add_u32 s80, s80, 0x100
	s_addc_u32 s81, s81, 0
	s_add_u32 s82, s82, 0x100
	s_addc_u32 s83, s83, 0
	s_cmp_ge_i32 s84, s39
	s_mov_b32 s2, s84
	s_cbranch_scc0 .LBB0_998
	v_readlane_b32 s88, v255, 33
	v_readlane_b32 s89, v255, 34
	s_movk_i32 s87, 0x2000
	s_mov_b32 s78, 0x1a000
	s_mov_b32 s79, 0x8000
	s_mov_b32 s80, 0x1e000
	s_mov_b32 s81, 0xc000
	s_mov_b32 s82, 0xe000
	s_mov_b32 s83, 0xb000
	s_mov_b32 s84, 0x4ffff
	s_mov_b32 s85, 0x66666667
	s_mov_b32 s86, 0x1f000

.LBB0_1315:
	s_add_i32 s92, s18, 2
	s_cmp_eq_u32 s81, s18
	s_cselect_b32 s18, s37, vcc_lo
	s_cselect_b32 s19, s1, vcc_hi
	s_cselect_b32 s62, s89, s90
	s_cselect_b32 s63, s55, s91
	s_add_u32 s26, s18, 0x80
	s_addc_u32 s27, s19, 0
	s_add_i32 s93, 0, 0x10000
	v_add_u32_e32 v0, s93, v222
	s_add_i32 s96, 0, 0x14000
	ds_read_b128 v[66:69], v0
	ds_read_b128 v[70:73], v0 offset:1024
	ds_read_b128 v[74:77], v0 offset:2048
	ds_read_b128 v[78:81], v0 offset:3072
	v_add_u32_e32 v0, s96, v222
	ds_read_b128 v[146:149], v0
	ds_read_b128 v[150:153], v0 offset:1024
	ds_read_b128 v[154:157], v0 offset:2048
	ds_read_b128 v[158:161], v0 offset:3072
	s_mov_b64 s[2:3], s[94:95]
	ds_read_b128 v[162:165], v223
	ds_read_b128 v[166:169], v223 offset:1024
	ds_read_b128 v[198:201], v223 offset:2048
	ds_read_b128 v[202:205], v223 offset:3072
	ds_read_b128 v[206:209], v223 offset:4096
	ds_read_b128 v[210:213], v223 offset:5120
	ds_read_b128 v[214:217], v223 offset:6144
	ds_read_b128 v[218:221], v223 offset:7168
	s_add_i32 m0, s67, 0xc000
	v_lshl_add_u64 v[224:225], s[2:3], 0, v[196:197]
	global_load_lds_dwordx4 v[224:225], off
	v_lshl_add_u64 v[224:225], s[2:3], 0, v[172:173]
	s_add_i32 m0, s67, 0xe000
	s_nop 0
	global_load_lds_dwordx4 v[224:225], off
	s_waitcnt vmcnt(8)
	s_waitcnt lgkmcnt(0)
	s_barrier
	s_setprio 1
	s_waitcnt lgkmcnt(0)
	v_mfma_f32_16x16x32_bf16 v[138:141], v[66:69], v[162:165], v[138:141]
	v_mfma_f32_16x16x32_bf16 v[142:145], v[74:77], v[162:165], v[142:145]
	v_mfma_f32_16x16x32_bf16 v[126:129], v[66:69], v[198:201], v[126:129]
	v_mfma_f32_16x16x32_bf16 v[122:125], v[74:77], v[198:201], v[122:125]
	v_mfma_f32_16x16x32_bf16 v[110:113], v[66:69], v[206:209], v[110:113]
	v_mfma_f32_16x16x32_bf16 v[106:109], v[74:77], v[206:209], v[106:109]
	v_mfma_f32_16x16x32_bf16 v[94:97], v[66:69], v[214:217], v[94:97]
	v_mfma_f32_16x16x32_bf16 v[90:93], v[74:77], v[214:217], v[90:93]
	v_mfma_f32_16x16x32_bf16 v[138:141], v[70:73], v[166:169], v[138:141]
	v_mfma_f32_16x16x32_bf16 v[142:145], v[78:81], v[166:169], v[142:145]
	v_mfma_f32_16x16x32_bf16 v[126:129], v[70:73], v[202:205], v[126:129]
	v_mfma_f32_16x16x32_bf16 v[122:125], v[78:81], v[202:205], v[122:125]
	v_mfma_f32_16x16x32_bf16 v[110:113], v[70:73], v[210:213], v[110:113]
	v_mfma_f32_16x16x32_bf16 v[106:109], v[78:81], v[210:213], v[106:109]
	v_mfma_f32_16x16x32_bf16 v[94:97], v[70:73], v[218:221], v[94:97]
	v_mfma_f32_16x16x32_bf16 v[90:93], v[78:81], v[218:221], v[90:93]
	v_mfma_f32_16x16x32_bf16 v[134:137], v[146:149], v[162:165], v[134:137]
	v_mfma_f32_16x16x32_bf16 v[130:133], v[154:157], v[162:165], v[130:133]
	v_mfma_f32_16x16x32_bf16 v[118:121], v[146:149], v[198:201], v[118:121]
	v_mfma_f32_16x16x32_bf16 v[114:117], v[154:157], v[198:201], v[114:117]
	v_mfma_f32_16x16x32_bf16 v[102:105], v[146:149], v[206:209], v[102:105]
	v_mfma_f32_16x16x32_bf16 v[98:101], v[154:157], v[206:209], v[98:101]
	v_mfma_f32_16x16x32_bf16 v[86:89], v[146:149], v[214:217], v[86:89]
	v_mfma_f32_16x16x32_bf16 v[82:85], v[154:157], v[214:217], v[82:85]
	v_mfma_f32_16x16x32_bf16 v[134:137], v[150:153], v[166:169], v[134:137]
	v_mfma_f32_16x16x32_bf16 v[130:133], v[158:161], v[166:169], v[130:133]
	v_mfma_f32_16x16x32_bf16 v[118:121], v[150:153], v[202:205], v[118:121]
	v_mfma_f32_16x16x32_bf16 v[114:117], v[158:161], v[202:205], v[114:117]
	v_mfma_f32_16x16x32_bf16 v[102:105], v[150:153], v[210:213], v[102:105]
	v_mfma_f32_16x16x32_bf16 v[98:101], v[158:161], v[210:213], v[98:101]
	v_mfma_f32_16x16x32_bf16 v[86:89], v[150:153], v[218:221], v[86:89]
	v_mfma_f32_16x16x32_bf16 v[82:85], v[158:161], v[218:221], v[82:85]
	s_setprio 0
	s_barrier
	s_mov_b64 s[2:3], s[62:63]
	s_add_i32 s93, s93, s25
	ds_read_b128 v[162:165], v223 offset:16384
	ds_read_b128 v[166:169], v223 offset:17408
	ds_read_b128 v[198:201], v223 offset:18432
	ds_read_b128 v[202:205], v223 offset:19456
	ds_read_b128 v[206:209], v223 offset:20480
	ds_read_b128 v[210:213], v223 offset:21504
	ds_read_b128 v[214:217], v223 offset:22528
	ds_read_b128 v[218:221], v223 offset:23552
	s_mov_b32 m0, s93
	v_lshl_add_u64 v[224:225], s[2:3], 0, v[194:195]
	global_load_lds_dwordx4 v[224:225], off
	s_add_i32 m0, s93, 0x2000
	v_lshl_add_u64 v[224:225], s[2:3], 0, v[170:171]
	s_add_u32 s2, s62, 0x40000
	s_addc_u32 s3, s63, 0
	s_add_i32 s93, s96, s25
	global_load_lds_dwordx4 v[224:225], off
	s_mov_b32 m0, s93
	v_lshl_add_u64 v[224:225], s[2:3], 0, v[194:195]
	global_load_lds_dwordx4 v[224:225], off
	v_lshl_add_u64 v[224:225], s[2:3], 0, v[170:171]
	s_add_i32 m0, s93, 0x2000
	s_mov_b64 s[2:3], s[18:19]
	global_load_lds_dwordx4 v[224:225], off
	s_mov_b32 m0, s67
	v_lshl_add_u64 v[224:225], s[2:3], 0, v[196:197]
	global_load_lds_dwordx4 v[224:225], off
	v_lshl_add_u64 v[224:225], s[2:3], 0, v[172:173]
	s_mov_b32 m0, s68
	s_nop 0
	global_load_lds_dwordx4 v[224:225], off
	s_waitcnt vmcnt(8)
	s_waitcnt lgkmcnt(0)
	s_barrier
	s_setprio 1
	s_waitcnt lgkmcnt(0)
	v_mfma_f32_16x16x32_bf16 v[62:65], v[66:69], v[162:165], v[62:65]
	v_mfma_f32_16x16x32_bf16 v[58:61], v[74:77], v[162:165], v[58:61]
	v_mfma_f32_16x16x32_bf16 v[46:49], v[66:69], v[198:201], v[46:49]
	v_mfma_f32_16x16x32_bf16 v[42:45], v[74:77], v[198:201], v[42:45]
	v_mfma_f32_16x16x32_bf16 v[30:33], v[66:69], v[206:209], v[30:33]
	v_mfma_f32_16x16x32_bf16 v[26:29], v[74:77], v[206:209], v[26:29]
	v_mfma_f32_16x16x32_bf16 v[14:17], v[66:69], v[214:217], v[14:17]
	v_mfma_f32_16x16x32_bf16 v[10:13], v[74:77], v[214:217], v[10:13]
	v_mfma_f32_16x16x32_bf16 v[62:65], v[70:73], v[166:169], v[62:65]
	v_mfma_f32_16x16x32_bf16 v[58:61], v[78:81], v[166:169], v[58:61]
	v_mfma_f32_16x16x32_bf16 v[46:49], v[70:73], v[202:205], v[46:49]
	v_mfma_f32_16x16x32_bf16 v[42:45], v[78:81], v[202:205], v[42:45]
	v_mfma_f32_16x16x32_bf16 v[30:33], v[70:73], v[210:213], v[30:33]
	v_mfma_f32_16x16x32_bf16 v[26:29], v[78:81], v[210:213], v[26:29]
	v_mfma_f32_16x16x32_bf16 v[14:17], v[70:73], v[218:221], v[14:17]
	v_mfma_f32_16x16x32_bf16 v[10:13], v[78:81], v[218:221], v[10:13]
	v_mfma_f32_16x16x32_bf16 v[54:57], v[146:149], v[162:165], v[54:57]
	v_mfma_f32_16x16x32_bf16 v[50:53], v[154:157], v[162:165], v[50:53]
	v_mfma_f32_16x16x32_bf16 v[38:41], v[146:149], v[198:201], v[38:41]
	v_mfma_f32_16x16x32_bf16 v[34:37], v[154:157], v[198:201], v[34:37]
	v_mfma_f32_16x16x32_bf16 v[22:25], v[146:149], v[206:209], v[22:25]
	v_mfma_f32_16x16x32_bf16 v[18:21], v[154:157], v[206:209], v[18:21]
	v_mfma_f32_16x16x32_bf16 v[6:9], v[146:149], v[214:217], v[6:9]
	v_mfma_f32_16x16x32_bf16 v[2:5], v[154:157], v[214:217], v[2:5]
	v_mfma_f32_16x16x32_bf16 v[54:57], v[150:153], v[166:169], v[54:57]
	v_mfma_f32_16x16x32_bf16 v[50:53], v[158:161], v[166:169], v[50:53]
	v_mfma_f32_16x16x32_bf16 v[38:41], v[150:153], v[202:205], v[38:41]
	v_mfma_f32_16x16x32_bf16 v[34:37], v[158:161], v[202:205], v[34:37]
	v_mfma_f32_16x16x32_bf16 v[22:25], v[150:153], v[210:213], v[22:25]
	v_mfma_f32_16x16x32_bf16 v[18:21], v[158:161], v[210:213], v[18:21]
	v_mfma_f32_16x16x32_bf16 v[6:9], v[150:153], v[218:221], v[6:9]
	v_mfma_f32_16x16x32_bf16 v[2:5], v[158:161], v[218:221], v[2:5]
	s_setprio 0
	s_barrier
	s_add_i32 s93, 0, 0x18000
	v_add_u32_e32 v0, s93, v222
	s_add_i32 s96, 0, 0x1c000
	ds_read_b128 v[66:69], v0
	ds_read_b128 v[70:73], v0 offset:1024
	ds_read_b128 v[74:77], v0 offset:2048
	ds_read_b128 v[78:81], v0 offset:3072
	v_add_u32_e32 v0, s96, v222
	ds_read_b128 v[146:149], v0
	ds_read_b128 v[150:153], v0 offset:1024
	ds_read_b128 v[154:157], v0 offset:2048
	ds_read_b128 v[158:161], v0 offset:3072
	s_add_u32 s2, s18, 0x40000
	s_addc_u32 s3, s19, 0
	s_mov_b32 m0, s69
	ds_read_b128 v[162:165], v223 offset:32768
	ds_read_b128 v[166:169], v223 offset:33792
	ds_read_b128 v[198:201], v223 offset:34816
	ds_read_b128 v[202:205], v223 offset:35840
	ds_read_b128 v[206:209], v223 offset:36864
	ds_read_b128 v[210:213], v223 offset:37888
	ds_read_b128 v[214:217], v223 offset:38912
	ds_read_b128 v[218:221], v223 offset:39936
	s_nop 0
	v_lshl_add_u64 v[224:225], s[2:3], 0, v[196:197]
	global_load_lds_dwordx4 v[224:225], off
	v_lshl_add_u64 v[224:225], s[2:3], 0, v[172:173]
	s_mov_b32 m0, s70
	s_nop 0
	global_load_lds_dwordx4 v[224:225], off
	s_waitcnt vmcnt(8)
	s_waitcnt lgkmcnt(0)
	s_barrier
	s_setprio 1
	s_waitcnt lgkmcnt(0)
	v_mfma_f32_16x16x32_bf16 v[138:141], v[66:69], v[162:165], v[138:141]
	v_mfma_f32_16x16x32_bf16 v[142:145], v[74:77], v[162:165], v[142:145]
	v_mfma_f32_16x16x32_bf16 v[126:129], v[66:69], v[198:201], v[126:129]
	v_mfma_f32_16x16x32_bf16 v[122:125], v[74:77], v[198:201], v[122:125]
	v_mfma_f32_16x16x32_bf16 v[110:113], v[66:69], v[206:209], v[110:113]
	v_mfma_f32_16x16x32_bf16 v[106:109], v[74:77], v[206:209], v[106:109]
	v_mfma_f32_16x16x32_bf16 v[94:97], v[66:69], v[214:217], v[94:97]
	v_mfma_f32_16x16x32_bf16 v[90:93], v[74:77], v[214:217], v[90:93]
	v_mfma_f32_16x16x32_bf16 v[138:141], v[70:73], v[166:169], v[138:141]
	v_mfma_f32_16x16x32_bf16 v[142:145], v[78:81], v[166:169], v[142:145]
	v_mfma_f32_16x16x32_bf16 v[126:129], v[70:73], v[202:205], v[126:129]
	v_mfma_f32_16x16x32_bf16 v[122:125], v[78:81], v[202:205], v[122:125]
	v_mfma_f32_16x16x32_bf16 v[110:113], v[70:73], v[210:213], v[110:113]
	v_mfma_f32_16x16x32_bf16 v[106:109], v[78:81], v[210:213], v[106:109]
	v_mfma_f32_16x16x32_bf16 v[94:97], v[70:73], v[218:221], v[94:97]
	v_mfma_f32_16x16x32_bf16 v[90:93], v[78:81], v[218:221], v[90:93]
	v_mfma_f32_16x16x32_bf16 v[134:137], v[146:149], v[162:165], v[134:137]
	v_mfma_f32_16x16x32_bf16 v[130:133], v[154:157], v[162:165], v[130:133]
	v_mfma_f32_16x16x32_bf16 v[118:121], v[146:149], v[198:201], v[118:121]
	v_mfma_f32_16x16x32_bf16 v[114:117], v[154:157], v[198:201], v[114:117]
	v_mfma_f32_16x16x32_bf16 v[102:105], v[146:149], v[206:209], v[102:105]
	v_mfma_f32_16x16x32_bf16 v[98:101], v[154:157], v[206:209], v[98:101]
	v_mfma_f32_16x16x32_bf16 v[86:89], v[146:149], v[214:217], v[86:89]
	v_mfma_f32_16x16x32_bf16 v[82:85], v[154:157], v[214:217], v[82:85]
	v_mfma_f32_16x16x32_bf16 v[134:137], v[150:153], v[166:169], v[134:137]
	v_mfma_f32_16x16x32_bf16 v[130:133], v[158:161], v[166:169], v[130:133]
	v_mfma_f32_16x16x32_bf16 v[118:121], v[150:153], v[202:205], v[118:121]
	v_mfma_f32_16x16x32_bf16 v[114:117], v[158:161], v[202:205], v[114:117]
	v_mfma_f32_16x16x32_bf16 v[102:105], v[150:153], v[210:213], v[102:105]
	v_mfma_f32_16x16x32_bf16 v[98:101], v[158:161], v[210:213], v[98:101]
	v_mfma_f32_16x16x32_bf16 v[86:89], v[150:153], v[218:221], v[86:89]
	v_mfma_f32_16x16x32_bf16 v[82:85], v[158:161], v[218:221], v[82:85]
	s_setprio 0
	s_barrier
	s_add_u32 s2, s62, 0x80
	s_addc_u32 s3, s63, 0
	s_add_i32 s18, s93, s25
	ds_read_b128 v[162:165], v223 offset:49152
	ds_read_b128 v[166:169], v223 offset:50176
	ds_read_b128 v[198:201], v223 offset:51200
	ds_read_b128 v[202:205], v223 offset:52224
	ds_read_b128 v[206:209], v223 offset:53248
	ds_read_b128 v[210:213], v223 offset:54272
	ds_read_b128 v[214:217], v223 offset:55296
	ds_read_b128 v[218:221], v223 offset:56320
	s_mov_b32 m0, s18
	v_lshl_add_u64 v[224:225], s[2:3], 0, v[194:195]
	global_load_lds_dwordx4 v[224:225], off
	s_add_i32 m0, s18, 0x2000
	v_lshl_add_u64 v[224:225], s[2:3], 0, v[170:171]
	s_add_u32 s2, s62, 0x40080
	s_addc_u32 s3, s63, 0
	s_add_i32 s18, s96, s25
	global_load_lds_dwordx4 v[224:225], off
	s_mov_b32 m0, s18
	v_lshl_add_u64 v[224:225], s[2:3], 0, v[194:195]
	global_load_lds_dwordx4 v[224:225], off
	v_lshl_add_u64 v[224:225], s[2:3], 0, v[170:171]
	s_add_i32 m0, s18, 0x2000
	s_nop 0
	global_load_lds_dwordx4 v[224:225], off
	s_mov_b32 m0, s82
	v_lshl_add_u64 v[224:225], s[26:27], 0, v[196:197]
	global_load_lds_dwordx4 v[224:225], off
	v_lshl_add_u64 v[224:225], s[26:27], 0, v[172:173]
	s_mov_b32 m0, s83
	s_nop 0
	global_load_lds_dwordx4 v[224:225], off
	s_waitcnt vmcnt(8)
	s_waitcnt lgkmcnt(0)
	s_barrier
	s_setprio 1
	s_waitcnt lgkmcnt(0)
	v_mfma_f32_16x16x32_bf16 v[62:65], v[66:69], v[162:165], v[62:65]
	v_mfma_f32_16x16x32_bf16 v[58:61], v[74:77], v[162:165], v[58:61]
	v_mfma_f32_16x16x32_bf16 v[46:49], v[66:69], v[198:201], v[46:49]
	v_mfma_f32_16x16x32_bf16 v[42:45], v[74:77], v[198:201], v[42:45]
	v_mfma_f32_16x16x32_bf16 v[30:33], v[66:69], v[206:209], v[30:33]
	v_mfma_f32_16x16x32_bf16 v[26:29], v[74:77], v[206:209], v[26:29]
	v_mfma_f32_16x16x32_bf16 v[14:17], v[66:69], v[214:217], v[14:17]
	v_mfma_f32_16x16x32_bf16 v[10:13], v[74:77], v[214:217], v[10:13]
	v_mfma_f32_16x16x32_bf16 v[62:65], v[70:73], v[166:169], v[62:65]
	v_mfma_f32_16x16x32_bf16 v[58:61], v[78:81], v[166:169], v[58:61]
	v_mfma_f32_16x16x32_bf16 v[46:49], v[70:73], v[202:205], v[46:49]
	v_mfma_f32_16x16x32_bf16 v[42:45], v[78:81], v[202:205], v[42:45]
	v_mfma_f32_16x16x32_bf16 v[30:33], v[70:73], v[210:213], v[30:33]
	v_mfma_f32_16x16x32_bf16 v[26:29], v[78:81], v[210:213], v[26:29]
	v_mfma_f32_16x16x32_bf16 v[14:17], v[70:73], v[218:221], v[14:17]
	v_mfma_f32_16x16x32_bf16 v[10:13], v[78:81], v[218:221], v[10:13]
	v_mfma_f32_16x16x32_bf16 v[54:57], v[146:149], v[162:165], v[54:57]
	v_mfma_f32_16x16x32_bf16 v[50:53], v[154:157], v[162:165], v[50:53]
	v_mfma_f32_16x16x32_bf16 v[38:41], v[146:149], v[198:201], v[38:41]
	v_mfma_f32_16x16x32_bf16 v[34:37], v[154:157], v[198:201], v[34:37]
	v_mfma_f32_16x16x32_bf16 v[22:25], v[146:149], v[206:209], v[22:25]
	v_mfma_f32_16x16x32_bf16 v[18:21], v[154:157], v[206:209], v[18:21]
	v_mfma_f32_16x16x32_bf16 v[6:9], v[146:149], v[214:217], v[6:9]
	v_mfma_f32_16x16x32_bf16 v[2:5], v[154:157], v[214:217], v[2:5]
	v_mfma_f32_16x16x32_bf16 v[54:57], v[150:153], v[166:169], v[54:57]
	v_mfma_f32_16x16x32_bf16 v[50:53], v[158:161], v[166:169], v[50:53]
	v_mfma_f32_16x16x32_bf16 v[38:41], v[150:153], v[202:205], v[38:41]
	v_mfma_f32_16x16x32_bf16 v[34:37], v[158:161], v[202:205], v[34:37]
	v_mfma_f32_16x16x32_bf16 v[22:25], v[150:153], v[210:213], v[22:25]
	v_mfma_f32_16x16x32_bf16 v[18:21], v[158:161], v[210:213], v[18:21]
	v_mfma_f32_16x16x32_bf16 v[6:9], v[150:153], v[218:221], v[6:9]
	v_mfma_f32_16x16x32_bf16 v[2:5], v[158:161], v[218:221], v[2:5]
	s_setprio 0
	s_barrier
	s_add_u32 vcc_lo, vcc_lo, 0x100
	s_addc_u32 vcc_hi, vcc_hi, 0
	s_add_u32 s90, s90, 0x100
	s_addc_u32 s91, s91, 0
	s_add_u32 s94, s94, 0x100
	s_addc_u32 s95, s95, 0
	s_cmp_ge_i32 s92, s84
	s_mov_b32 s18, s92
	s_cbranch_scc0 .LBB0_1315
	s_movk_i32 s90, 0x80
	s_mov_b32 s91, 0x10000
	s_mov_b32 s92, 0x12000
	s_mov_b32 s93, 0x14000
	s_mov_b32 s94, 0x16000
	s_movk_i32 s95, 0x4000
	s_movk_i32 s96, 0x3000
	s_mov_b32 s63, 0xa000

.LBB0_1405:
	s_add_i32 s83, s18, 2
	s_cmp_eq_u32 s22, s18
	s_cselect_b32 s18, s47, s79
	s_cselect_b32 s19, s45, s80
	s_cselect_b32 s54, s78, s81
	s_cselect_b32 s55, s73, s82
	s_add_u32 s26, s18, 0x80
	s_addc_u32 s27, s19, 0
	s_add_i32 s86, 0, 0x10000
	v_add_u32_e32 v0, s86, v215
	s_add_i32 s87, 0, 0x14000
	ds_read_b128 v[130:133], v0
	ds_read_b128 v[134:137], v0 offset:1024
	ds_read_b128 v[138:141], v0 offset:2048
	ds_read_b128 v[142:145], v0 offset:3072
	v_add_u32_e32 v0, s87, v215
	ds_read_b128 v[146:149], v0
	ds_read_b128 v[150:153], v0 offset:1024
	ds_read_b128 v[154:157], v0 offset:2048
	ds_read_b128 v[158:161], v0 offset:3072
	s_add_u32 s84, s79, 0x3ff80
	s_addc_u32 s85, s80, 0
	ds_read_b128 v[162:165], v218
	ds_read_b128 v[166:169], v218 offset:1024
	ds_read_b128 v[198:201], v218 offset:2048
	ds_read_b128 v[202:205], v218 offset:3072
	ds_read_b128 v[206:209], v218 offset:4096
	ds_read_b128 v[210:213], v218 offset:5120
	ds_read_b128 v[220:223], v218 offset:6144
	ds_read_b128 v[224:227], v218 offset:7168
	s_add_i32 m0, s60, 0xc000
	v_lshl_add_u64 v[216:217], s[84:85], 0, v[196:197]
	global_load_lds_dwordx4 v[216:217], off
	v_lshl_add_u64 v[216:217], s[84:85], 0, v[172:173]
	s_add_i32 m0, s60, 0xe000
	s_nop 0
	global_load_lds_dwordx4 v[216:217], off
	s_waitcnt vmcnt(8)
	s_waitcnt lgkmcnt(0)
	s_barrier
	s_setprio 1
	s_waitcnt lgkmcnt(0)
	v_mfma_f32_16x16x32_bf16 v[122:125], v[130:133], v[162:165], v[122:125]
	v_mfma_f32_16x16x32_bf16 v[126:129], v[138:141], v[162:165], v[126:129]
	v_mfma_f32_16x16x32_bf16 v[106:109], v[130:133], v[198:201], v[106:109]
	v_mfma_f32_16x16x32_bf16 v[110:113], v[138:141], v[198:201], v[110:113]
	v_mfma_f32_16x16x32_bf16 v[90:93], v[130:133], v[206:209], v[90:93]
	v_mfma_f32_16x16x32_bf16 v[94:97], v[138:141], v[206:209], v[94:97]
	v_mfma_f32_16x16x32_bf16 v[74:77], v[130:133], v[220:223], v[74:77]
	v_mfma_f32_16x16x32_bf16 v[78:81], v[138:141], v[220:223], v[78:81]
	v_mfma_f32_16x16x32_bf16 v[122:125], v[134:137], v[166:169], v[122:125]
	v_mfma_f32_16x16x32_bf16 v[126:129], v[142:145], v[166:169], v[126:129]
	v_mfma_f32_16x16x32_bf16 v[106:109], v[134:137], v[202:205], v[106:109]
	v_mfma_f32_16x16x32_bf16 v[110:113], v[142:145], v[202:205], v[110:113]
	v_mfma_f32_16x16x32_bf16 v[90:93], v[134:137], v[210:213], v[90:93]
	v_mfma_f32_16x16x32_bf16 v[94:97], v[142:145], v[210:213], v[94:97]
	v_mfma_f32_16x16x32_bf16 v[74:77], v[134:137], v[224:227], v[74:77]
	v_mfma_f32_16x16x32_bf16 v[78:81], v[142:145], v[224:227], v[78:81]
	v_mfma_f32_16x16x32_bf16 v[114:117], v[146:149], v[162:165], v[114:117]
	v_mfma_f32_16x16x32_bf16 v[118:121], v[154:157], v[162:165], v[118:121]
	v_mfma_f32_16x16x32_bf16 v[98:101], v[146:149], v[198:201], v[98:101]
	v_mfma_f32_16x16x32_bf16 v[102:105], v[154:157], v[198:201], v[102:105]
	v_mfma_f32_16x16x32_bf16 v[82:85], v[146:149], v[206:209], v[82:85]
	v_mfma_f32_16x16x32_bf16 v[86:89], v[154:157], v[206:209], v[86:89]
	v_mfma_f32_16x16x32_bf16 v[66:69], v[146:149], v[220:223], v[66:69]
	v_mfma_f32_16x16x32_bf16 v[70:73], v[154:157], v[220:223], v[70:73]
	v_mfma_f32_16x16x32_bf16 v[114:117], v[150:153], v[166:169], v[114:117]
	v_mfma_f32_16x16x32_bf16 v[118:121], v[158:161], v[166:169], v[118:121]
	v_mfma_f32_16x16x32_bf16 v[98:101], v[150:153], v[202:205], v[98:101]
	v_mfma_f32_16x16x32_bf16 v[102:105], v[158:161], v[202:205], v[102:105]
	v_mfma_f32_16x16x32_bf16 v[82:85], v[150:153], v[210:213], v[82:85]
	v_mfma_f32_16x16x32_bf16 v[86:89], v[158:161], v[210:213], v[86:89]
	v_mfma_f32_16x16x32_bf16 v[66:69], v[150:153], v[224:227], v[66:69]
	v_mfma_f32_16x16x32_bf16 v[70:73], v[158:161], v[224:227], v[70:73]
	s_setprio 0
	s_barrier
	s_mov_b64 s[84:85], s[54:55]
	s_add_i32 s86, s86, s56
	ds_read_b128 v[162:165], v218 offset:16384
	ds_read_b128 v[166:169], v218 offset:17408
	ds_read_b128 v[198:201], v218 offset:18432
	ds_read_b128 v[202:205], v218 offset:19456
	ds_read_b128 v[206:209], v218 offset:20480
	ds_read_b128 v[210:213], v218 offset:21504
	ds_read_b128 v[220:223], v218 offset:22528
	ds_read_b128 v[224:227], v218 offset:23552
	s_mov_b32 m0, s86
	v_lshl_add_u64 v[216:217], s[84:85], 0, v[194:195]
	global_load_lds_dwordx4 v[216:217], off
	s_add_i32 m0, s86, 0x2000
	v_lshl_add_u64 v[216:217], s[84:85], 0, v[170:171]
	s_add_u32 s84, s54, 0x40000
	s_addc_u32 s85, s55, 0
	s_add_i32 s86, s87, s56
	global_load_lds_dwordx4 v[216:217], off
	s_mov_b32 m0, s86
	v_lshl_add_u64 v[216:217], s[84:85], 0, v[194:195]
	global_load_lds_dwordx4 v[216:217], off
	v_lshl_add_u64 v[216:217], s[84:85], 0, v[170:171]
	s_add_i32 m0, s86, 0x2000
	s_mov_b64 s[84:85], s[18:19]
	global_load_lds_dwordx4 v[216:217], off
	s_mov_b32 m0, s60
	v_lshl_add_u64 v[216:217], s[84:85], 0, v[196:197]
	global_load_lds_dwordx4 v[216:217], off
	v_lshl_add_u64 v[216:217], s[84:85], 0, v[172:173]
	s_mov_b32 m0, s61
	s_nop 0
	global_load_lds_dwordx4 v[216:217], off
	s_waitcnt vmcnt(8)
	s_waitcnt lgkmcnt(0)
	s_barrier
	s_setprio 1
	s_waitcnt lgkmcnt(0)
	v_mfma_f32_16x16x32_bf16 v[58:61], v[130:133], v[162:165], v[58:61]
	v_mfma_f32_16x16x32_bf16 v[62:65], v[138:141], v[162:165], v[62:65]
	v_mfma_f32_16x16x32_bf16 v[42:45], v[130:133], v[198:201], v[42:45]
	v_mfma_f32_16x16x32_bf16 v[46:49], v[138:141], v[198:201], v[46:49]
	v_mfma_f32_16x16x32_bf16 v[26:29], v[130:133], v[206:209], v[26:29]
	v_mfma_f32_16x16x32_bf16 v[30:33], v[138:141], v[206:209], v[30:33]
	v_mfma_f32_16x16x32_bf16 v[10:13], v[130:133], v[220:223], v[10:13]
	v_mfma_f32_16x16x32_bf16 v[14:17], v[138:141], v[220:223], v[14:17]
	v_mfma_f32_16x16x32_bf16 v[58:61], v[134:137], v[166:169], v[58:61]
	v_mfma_f32_16x16x32_bf16 v[62:65], v[142:145], v[166:169], v[62:65]
	v_mfma_f32_16x16x32_bf16 v[42:45], v[134:137], v[202:205], v[42:45]
	v_mfma_f32_16x16x32_bf16 v[46:49], v[142:145], v[202:205], v[46:49]
	v_mfma_f32_16x16x32_bf16 v[26:29], v[134:137], v[210:213], v[26:29]
	v_mfma_f32_16x16x32_bf16 v[30:33], v[142:145], v[210:213], v[30:33]
	v_mfma_f32_16x16x32_bf16 v[10:13], v[134:137], v[224:227], v[10:13]
	v_mfma_f32_16x16x32_bf16 v[14:17], v[142:145], v[224:227], v[14:17]
	v_mfma_f32_16x16x32_bf16 v[50:53], v[146:149], v[162:165], v[50:53]
	v_mfma_f32_16x16x32_bf16 v[54:57], v[154:157], v[162:165], v[54:57]
	v_mfma_f32_16x16x32_bf16 v[34:37], v[146:149], v[198:201], v[34:37]
	v_mfma_f32_16x16x32_bf16 v[38:41], v[154:157], v[198:201], v[38:41]
	v_mfma_f32_16x16x32_bf16 v[18:21], v[146:149], v[206:209], v[18:21]
	v_mfma_f32_16x16x32_bf16 v[22:25], v[154:157], v[206:209], v[22:25]
	v_mfma_f32_16x16x32_bf16 v[2:5], v[146:149], v[220:223], v[2:5]
	v_mfma_f32_16x16x32_bf16 v[6:9], v[154:157], v[220:223], v[6:9]
	v_mfma_f32_16x16x32_bf16 v[50:53], v[150:153], v[166:169], v[50:53]
	v_mfma_f32_16x16x32_bf16 v[54:57], v[158:161], v[166:169], v[54:57]
	v_mfma_f32_16x16x32_bf16 v[34:37], v[150:153], v[202:205], v[34:37]
	v_mfma_f32_16x16x32_bf16 v[38:41], v[158:161], v[202:205], v[38:41]
	v_mfma_f32_16x16x32_bf16 v[18:21], v[150:153], v[210:213], v[18:21]
	v_mfma_f32_16x16x32_bf16 v[22:25], v[158:161], v[210:213], v[22:25]
	v_mfma_f32_16x16x32_bf16 v[2:5], v[150:153], v[224:227], v[2:5]
	v_mfma_f32_16x16x32_bf16 v[6:9], v[158:161], v[224:227], v[6:9]
	s_setprio 0
	s_barrier
	s_add_i32 s84, 0, 0x18000
	v_add_u32_e32 v0, s84, v215
	s_add_i32 s85, 0, 0x1c000
	ds_read_b128 v[130:133], v0
	ds_read_b128 v[134:137], v0 offset:1024
	ds_read_b128 v[138:141], v0 offset:2048
	ds_read_b128 v[142:145], v0 offset:3072
	v_add_u32_e32 v0, s85, v215
	ds_read_b128 v[146:149], v0
	ds_read_b128 v[150:153], v0 offset:1024
	ds_read_b128 v[154:157], v0 offset:2048
	ds_read_b128 v[158:161], v0 offset:3072
	s_add_u32 s18, s18, 0x40000
	s_addc_u32 s19, s19, 0
	s_mov_b32 m0, s62
	ds_read_b128 v[162:165], v218 offset:32768
	ds_read_b128 v[166:169], v218 offset:33792
	ds_read_b128 v[198:201], v218 offset:34816
	ds_read_b128 v[202:205], v218 offset:35840
	ds_read_b128 v[206:209], v218 offset:36864
	ds_read_b128 v[210:213], v218 offset:37888
	ds_read_b128 v[220:223], v218 offset:38912
	ds_read_b128 v[224:227], v218 offset:39936
	s_nop 0
	v_lshl_add_u64 v[216:217], s[18:19], 0, v[196:197]
	global_load_lds_dwordx4 v[216:217], off
	v_lshl_add_u64 v[216:217], s[18:19], 0, v[172:173]
	s_mov_b32 m0, s63
	s_nop 0
	global_load_lds_dwordx4 v[216:217], off
	s_waitcnt vmcnt(8)
	s_waitcnt lgkmcnt(0)
	s_barrier
	s_setprio 1
	s_waitcnt lgkmcnt(0)
	v_mfma_f32_16x16x32_bf16 v[122:125], v[130:133], v[162:165], v[122:125]
	v_mfma_f32_16x16x32_bf16 v[126:129], v[138:141], v[162:165], v[126:129]
	v_mfma_f32_16x16x32_bf16 v[106:109], v[130:133], v[198:201], v[106:109]
	v_mfma_f32_16x16x32_bf16 v[110:113], v[138:141], v[198:201], v[110:113]
	v_mfma_f32_16x16x32_bf16 v[90:93], v[130:133], v[206:209], v[90:93]
	v_mfma_f32_16x16x32_bf16 v[94:97], v[138:141], v[206:209], v[94:97]
	v_mfma_f32_16x16x32_bf16 v[74:77], v[130:133], v[220:223], v[74:77]
	v_mfma_f32_16x16x32_bf16 v[78:81], v[138:141], v[220:223], v[78:81]
	v_mfma_f32_16x16x32_bf16 v[122:125], v[134:137], v[166:169], v[122:125]
	v_mfma_f32_16x16x32_bf16 v[126:129], v[142:145], v[166:169], v[126:129]
	v_mfma_f32_16x16x32_bf16 v[106:109], v[134:137], v[202:205], v[106:109]
	v_mfma_f32_16x16x32_bf16 v[110:113], v[142:145], v[202:205], v[110:113]
	v_mfma_f32_16x16x32_bf16 v[90:93], v[134:137], v[210:213], v[90:93]
	v_mfma_f32_16x16x32_bf16 v[94:97], v[142:145], v[210:213], v[94:97]
	v_mfma_f32_16x16x32_bf16 v[74:77], v[134:137], v[224:227], v[74:77]
	v_mfma_f32_16x16x32_bf16 v[78:81], v[142:145], v[224:227], v[78:81]
	v_mfma_f32_16x16x32_bf16 v[114:117], v[146:149], v[162:165], v[114:117]
	v_mfma_f32_16x16x32_bf16 v[118:121], v[154:157], v[162:165], v[118:121]
	v_mfma_f32_16x16x32_bf16 v[98:101], v[146:149], v[198:201], v[98:101]
	v_mfma_f32_16x16x32_bf16 v[102:105], v[154:157], v[198:201], v[102:105]
	v_mfma_f32_16x16x32_bf16 v[82:85], v[146:149], v[206:209], v[82:85]
	v_mfma_f32_16x16x32_bf16 v[86:89], v[154:157], v[206:209], v[86:89]
	v_mfma_f32_16x16x32_bf16 v[66:69], v[146:149], v[220:223], v[66:69]
	v_mfma_f32_16x16x32_bf16 v[70:73], v[154:157], v[220:223], v[70:73]
	v_mfma_f32_16x16x32_bf16 v[114:117], v[150:153], v[166:169], v[114:117]
	v_mfma_f32_16x16x32_bf16 v[118:121], v[158:161], v[166:169], v[118:121]
	v_mfma_f32_16x16x32_bf16 v[98:101], v[150:153], v[202:205], v[98:101]
	v_mfma_f32_16x16x32_bf16 v[102:105], v[158:161], v[202:205], v[102:105]
	v_mfma_f32_16x16x32_bf16 v[82:85], v[150:153], v[210:213], v[82:85]
	v_mfma_f32_16x16x32_bf16 v[86:89], v[158:161], v[210:213], v[86:89]
	v_mfma_f32_16x16x32_bf16 v[66:69], v[150:153], v[224:227], v[66:69]
	v_mfma_f32_16x16x32_bf16 v[70:73], v[158:161], v[224:227], v[70:73]
	s_setprio 0
	s_barrier
	s_add_u32 s18, s54, 0x80
	s_addc_u32 s19, s55, 0
	s_add_i32 s84, s84, s56
	ds_read_b128 v[162:165], v218 offset:49152
	ds_read_b128 v[166:169], v218 offset:50176
	ds_read_b128 v[198:201], v218 offset:51200
	ds_read_b128 v[202:205], v218 offset:52224
	ds_read_b128 v[206:209], v218 offset:53248
	ds_read_b128 v[210:213], v218 offset:54272
	ds_read_b128 v[220:223], v218 offset:55296
	ds_read_b128 v[224:227], v218 offset:56320
	s_mov_b32 m0, s84
	v_lshl_add_u64 v[216:217], s[18:19], 0, v[194:195]
	global_load_lds_dwordx4 v[216:217], off
	s_add_i32 m0, s84, 0x2000
	v_lshl_add_u64 v[216:217], s[18:19], 0, v[170:171]
	s_add_u32 s18, s54, 0x40080
	s_addc_u32 s19, s55, 0
	s_add_i32 s54, s85, s56
	global_load_lds_dwordx4 v[216:217], off
	s_mov_b32 m0, s54
	v_lshl_add_u64 v[216:217], s[18:19], 0, v[194:195]
	global_load_lds_dwordx4 v[216:217], off
	v_lshl_add_u64 v[216:217], s[18:19], 0, v[170:171]
	s_add_i32 m0, s54, 0x2000
	s_nop 0
	global_load_lds_dwordx4 v[216:217], off
	s_mov_b32 m0, s70
	v_lshl_add_u64 v[216:217], s[26:27], 0, v[196:197]
	global_load_lds_dwordx4 v[216:217], off
	v_lshl_add_u64 v[216:217], s[26:27], 0, v[172:173]
	s_mov_b32 m0, s71
	s_nop 0
	global_load_lds_dwordx4 v[216:217], off
	s_waitcnt vmcnt(8)
	s_waitcnt lgkmcnt(0)
	s_barrier
	s_setprio 1
	s_waitcnt lgkmcnt(0)
	v_mfma_f32_16x16x32_bf16 v[58:61], v[130:133], v[162:165], v[58:61]
	v_mfma_f32_16x16x32_bf16 v[62:65], v[138:141], v[162:165], v[62:65]
	v_mfma_f32_16x16x32_bf16 v[42:45], v[130:133], v[198:201], v[42:45]
	v_mfma_f32_16x16x32_bf16 v[46:49], v[138:141], v[198:201], v[46:49]
	v_mfma_f32_16x16x32_bf16 v[26:29], v[130:133], v[206:209], v[26:29]
	v_mfma_f32_16x16x32_bf16 v[30:33], v[138:141], v[206:209], v[30:33]
	v_mfma_f32_16x16x32_bf16 v[10:13], v[130:133], v[220:223], v[10:13]
	v_mfma_f32_16x16x32_bf16 v[14:17], v[138:141], v[220:223], v[14:17]
	v_mfma_f32_16x16x32_bf16 v[58:61], v[134:137], v[166:169], v[58:61]
	v_mfma_f32_16x16x32_bf16 v[62:65], v[142:145], v[166:169], v[62:65]
	v_mfma_f32_16x16x32_bf16 v[42:45], v[134:137], v[202:205], v[42:45]
	v_mfma_f32_16x16x32_bf16 v[46:49], v[142:145], v[202:205], v[46:49]
	v_mfma_f32_16x16x32_bf16 v[26:29], v[134:137], v[210:213], v[26:29]
	v_mfma_f32_16x16x32_bf16 v[30:33], v[142:145], v[210:213], v[30:33]
	v_mfma_f32_16x16x32_bf16 v[10:13], v[134:137], v[224:227], v[10:13]
	v_mfma_f32_16x16x32_bf16 v[14:17], v[142:145], v[224:227], v[14:17]
	v_mfma_f32_16x16x32_bf16 v[50:53], v[146:149], v[162:165], v[50:53]
	v_mfma_f32_16x16x32_bf16 v[54:57], v[154:157], v[162:165], v[54:57]
	v_mfma_f32_16x16x32_bf16 v[34:37], v[146:149], v[198:201], v[34:37]
	v_mfma_f32_16x16x32_bf16 v[38:41], v[154:157], v[198:201], v[38:41]
	v_mfma_f32_16x16x32_bf16 v[18:21], v[146:149], v[206:209], v[18:21]
	v_mfma_f32_16x16x32_bf16 v[22:25], v[154:157], v[206:209], v[22:25]
	v_mfma_f32_16x16x32_bf16 v[2:5], v[146:149], v[220:223], v[2:5]
	v_mfma_f32_16x16x32_bf16 v[6:9], v[154:157], v[220:223], v[6:9]
	v_mfma_f32_16x16x32_bf16 v[50:53], v[150:153], v[166:169], v[50:53]
	v_mfma_f32_16x16x32_bf16 v[54:57], v[158:161], v[166:169], v[54:57]
	v_mfma_f32_16x16x32_bf16 v[34:37], v[150:153], v[202:205], v[34:37]
	v_mfma_f32_16x16x32_bf16 v[38:41], v[158:161], v[202:205], v[38:41]
	v_mfma_f32_16x16x32_bf16 v[18:21], v[150:153], v[210:213], v[18:21]
	v_mfma_f32_16x16x32_bf16 v[22:25], v[158:161], v[210:213], v[22:25]
	v_mfma_f32_16x16x32_bf16 v[2:5], v[150:153], v[224:227], v[2:5]
	v_mfma_f32_16x16x32_bf16 v[6:9], v[158:161], v[224:227], v[6:9]
	s_setprio 0
	s_barrier
	s_add_u32 s79, s79, 0x100
	s_addc_u32 s80, s80, 0
	s_add_u32 s81, s81, 0x100
	s_addc_u32 s82, s82, 0
	s_cmp_ge_i32 s83, s69
	s_mov_b32 s18, s83
	s_cbranch_scc0 .LBB0_1405
	s_movk_i32 s87, 0x2000
	s_mov_b32 s78, 0x1a000
	s_mov_b32 s79, 0x8000
	s_mov_b32 s80, 0x1e000
	s_mov_b32 s81, 0xc000
	s_mov_b32 s82, 0xe000
	s_mov_b32 s83, 0xb000
	s_mov_b32 s84, 0x4ffff
	s_mov_b32 s85, 0x66666667
	s_mov_b32 s86, 0x1f000

.LBB0_1494:
	s_add_i32 s93, s18, 2
	s_cmp_eq_u32 s86, s18
	s_cselect_b32 s70, s73, vcc_hi
	s_cselect_b32 s71, s61, s90
	s_cselect_b32 s18, vcc_lo, s91
	s_cselect_b32 s19, s89, s92
	s_add_u32 s26, s70, 0x80
	s_addc_u32 s27, s71, 0
	s_add_i32 s96, 0, 0x10000
	v_add_u32_e32 v0, s96, v243
	s_add_i32 s97, 0, 0x14000
	ds_read_b128 v[82:85], v0
	ds_read_b128 v[90:93], v0 offset:1024
	ds_read_b128 v[98:101], v0 offset:2048
	ds_read_b128 v[110:113], v0 offset:3072
	v_add_u32_e32 v0, s97, v243
	ds_read_b128 v[146:149], v0
	ds_read_b128 v[150:153], v0 offset:1024
	ds_read_b128 v[154:157], v0 offset:2048
	ds_read_b128 v[158:161], v0 offset:3072
	s_mov_b64 s[94:95], s[42:43]
	ds_read_b128 v[162:165], v244
	ds_read_b128 v[166:169], v244 offset:1024
	ds_read_b128 v[170:173], v244 offset:2048
	ds_read_b128 v[202:205], v244 offset:3072
	ds_read_b128 v[206:209], v244 offset:4096
	ds_read_b128 v[210:213], v244 offset:5120
	ds_read_b128 v[214:217], v244 offset:6144
	ds_read_b128 v[218:221], v244 offset:7168
	s_add_i32 m0, s31, 0xc000
	v_lshl_add_u64 v[222:223], s[94:95], 0, v[194:195]
	global_load_lds_dwordx4 v[222:223], off
	v_lshl_add_u64 v[222:223], s[94:95], 0, v[198:199]
	s_add_i32 m0, s31, 0xe000
	s_nop 0
	global_load_lds_dwordx4 v[222:223], off
	s_waitcnt vmcnt(8)
	s_waitcnt lgkmcnt(0)
	s_barrier
	s_setprio 1
	s_waitcnt lgkmcnt(0)
	v_mfma_f32_16x16x32_bf16 v[138:141], v[82:85], v[162:165], v[138:141]
	v_mfma_f32_16x16x32_bf16 v[142:145], v[98:101], v[162:165], v[142:145]
	v_mfma_f32_16x16x32_bf16 v[126:129], v[82:85], v[170:173], v[126:129]
	v_mfma_f32_16x16x32_bf16 v[122:125], v[98:101], v[170:173], v[122:125]
	v_mfma_f32_16x16x32_bf16 v[106:109], v[82:85], v[206:209], v[106:109]
	v_mfma_f32_16x16x32_bf16 v[102:105], v[98:101], v[206:209], v[102:105]
	v_mfma_f32_16x16x32_bf16 v[78:81], v[82:85], v[214:217], v[78:81]
	v_mfma_f32_16x16x32_bf16 v[74:77], v[98:101], v[214:217], v[74:77]
	v_mfma_f32_16x16x32_bf16 v[138:141], v[90:93], v[166:169], v[138:141]
	v_mfma_f32_16x16x32_bf16 v[142:145], v[110:113], v[166:169], v[142:145]
	v_mfma_f32_16x16x32_bf16 v[126:129], v[90:93], v[202:205], v[126:129]
	v_mfma_f32_16x16x32_bf16 v[122:125], v[110:113], v[202:205], v[122:125]
	v_mfma_f32_16x16x32_bf16 v[106:109], v[90:93], v[210:213], v[106:109]
	v_mfma_f32_16x16x32_bf16 v[102:105], v[110:113], v[210:213], v[102:105]
	v_mfma_f32_16x16x32_bf16 v[78:81], v[90:93], v[218:221], v[78:81]
	v_mfma_f32_16x16x32_bf16 v[74:77], v[110:113], v[218:221], v[74:77]
	v_mfma_f32_16x16x32_bf16 v[134:137], v[146:149], v[162:165], v[134:137]
	v_mfma_f32_16x16x32_bf16 v[130:133], v[154:157], v[162:165], v[130:133]
	v_mfma_f32_16x16x32_bf16 v[118:121], v[146:149], v[170:173], v[118:121]
	v_mfma_f32_16x16x32_bf16 v[114:117], v[154:157], v[170:173], v[114:117]
	v_mfma_f32_16x16x32_bf16 v[94:97], v[146:149], v[206:209], v[94:97]
	v_mfma_f32_16x16x32_bf16 v[86:89], v[154:157], v[206:209], v[86:89]
	v_mfma_f32_16x16x32_bf16 v[70:73], v[146:149], v[214:217], v[70:73]
	v_mfma_f32_16x16x32_bf16 v[66:69], v[154:157], v[214:217], v[66:69]
	v_mfma_f32_16x16x32_bf16 v[134:137], v[150:153], v[166:169], v[134:137]
	v_mfma_f32_16x16x32_bf16 v[130:133], v[158:161], v[166:169], v[130:133]
	v_mfma_f32_16x16x32_bf16 v[118:121], v[150:153], v[202:205], v[118:121]
	v_mfma_f32_16x16x32_bf16 v[114:117], v[158:161], v[202:205], v[114:117]
	v_mfma_f32_16x16x32_bf16 v[94:97], v[150:153], v[210:213], v[94:97]
	v_mfma_f32_16x16x32_bf16 v[86:89], v[158:161], v[210:213], v[86:89]
	v_mfma_f32_16x16x32_bf16 v[70:73], v[150:153], v[218:221], v[70:73]
	v_mfma_f32_16x16x32_bf16 v[66:69], v[158:161], v[218:221], v[66:69]
	s_setprio 0
	s_barrier
	s_mov_b64 s[94:95], s[18:19]
	s_add_i32 s96, s96, s25
	ds_read_b128 v[162:165], v244 offset:16384
	ds_read_b128 v[166:169], v244 offset:17408
	ds_read_b128 v[170:173], v244 offset:18432
	ds_read_b128 v[202:205], v244 offset:19456
	ds_read_b128 v[206:209], v244 offset:20480
	ds_read_b128 v[210:213], v244 offset:21504
	ds_read_b128 v[214:217], v244 offset:22528
	ds_read_b128 v[218:221], v244 offset:23552
	s_mov_b32 m0, s96
	v_lshl_add_u64 v[222:223], s[94:95], 0, v[196:197]
	global_load_lds_dwordx4 v[222:223], off
	s_add_i32 m0, s96, 0x2000
	v_lshl_add_u64 v[222:223], s[94:95], 0, v[200:201]
	s_add_u32 s94, s18, 0x100000
	s_addc_u32 s95, s19, 0
	s_add_i32 s96, s97, s25
	global_load_lds_dwordx4 v[222:223], off
	s_mov_b32 m0, s96
	v_lshl_add_u64 v[222:223], s[94:95], 0, v[196:197]
	global_load_lds_dwordx4 v[222:223], off
	v_lshl_add_u64 v[222:223], s[94:95], 0, v[200:201]
	s_add_i32 m0, s96, 0x2000
	s_mov_b64 s[94:95], s[70:71]
	global_load_lds_dwordx4 v[222:223], off
	s_mov_b32 m0, s31
	v_lshl_add_u64 v[222:223], s[94:95], 0, v[194:195]
	global_load_lds_dwordx4 v[222:223], off
	v_lshl_add_u64 v[222:223], s[94:95], 0, v[198:199]
	s_mov_b32 m0, s63
	s_nop 0
	global_load_lds_dwordx4 v[222:223], off
	s_waitcnt vmcnt(8)
	s_waitcnt lgkmcnt(0)
	s_barrier
	s_setprio 1
	s_waitcnt lgkmcnt(0)
	v_mfma_f32_16x16x32_bf16 v[62:65], v[82:85], v[162:165], v[62:65]
	v_mfma_f32_16x16x32_bf16 v[58:61], v[98:101], v[162:165], v[58:61]
	v_mfma_f32_16x16x32_bf16 v[46:49], v[82:85], v[170:173], v[46:49]
	v_mfma_f32_16x16x32_bf16 v[42:45], v[98:101], v[170:173], v[42:45]
	v_mfma_f32_16x16x32_bf16 v[30:33], v[82:85], v[206:209], v[30:33]
	v_mfma_f32_16x16x32_bf16 v[26:29], v[98:101], v[206:209], v[26:29]
	v_mfma_f32_16x16x32_bf16 v[14:17], v[82:85], v[214:217], v[14:17]
	v_mfma_f32_16x16x32_bf16 v[10:13], v[98:101], v[214:217], v[10:13]
	v_mfma_f32_16x16x32_bf16 v[62:65], v[90:93], v[166:169], v[62:65]
	v_mfma_f32_16x16x32_bf16 v[58:61], v[110:113], v[166:169], v[58:61]
	v_mfma_f32_16x16x32_bf16 v[46:49], v[90:93], v[202:205], v[46:49]
	v_mfma_f32_16x16x32_bf16 v[42:45], v[110:113], v[202:205], v[42:45]
	v_mfma_f32_16x16x32_bf16 v[30:33], v[90:93], v[210:213], v[30:33]
	v_mfma_f32_16x16x32_bf16 v[26:29], v[110:113], v[210:213], v[26:29]
	v_mfma_f32_16x16x32_bf16 v[14:17], v[90:93], v[218:221], v[14:17]
	v_mfma_f32_16x16x32_bf16 v[10:13], v[110:113], v[218:221], v[10:13]
	v_mfma_f32_16x16x32_bf16 v[54:57], v[146:149], v[162:165], v[54:57]
	v_mfma_f32_16x16x32_bf16 v[50:53], v[154:157], v[162:165], v[50:53]
	v_mfma_f32_16x16x32_bf16 v[38:41], v[146:149], v[170:173], v[38:41]
	v_mfma_f32_16x16x32_bf16 v[34:37], v[154:157], v[170:173], v[34:37]
	v_mfma_f32_16x16x32_bf16 v[22:25], v[146:149], v[206:209], v[22:25]
	v_mfma_f32_16x16x32_bf16 v[18:21], v[154:157], v[206:209], v[18:21]
	v_mfma_f32_16x16x32_bf16 v[6:9], v[146:149], v[214:217], v[6:9]
	v_mfma_f32_16x16x32_bf16 v[2:5], v[154:157], v[214:217], v[2:5]
	v_mfma_f32_16x16x32_bf16 v[54:57], v[150:153], v[166:169], v[54:57]
	v_mfma_f32_16x16x32_bf16 v[50:53], v[158:161], v[166:169], v[50:53]
	v_mfma_f32_16x16x32_bf16 v[38:41], v[150:153], v[202:205], v[38:41]
	v_mfma_f32_16x16x32_bf16 v[34:37], v[158:161], v[202:205], v[34:37]
	v_mfma_f32_16x16x32_bf16 v[22:25], v[150:153], v[210:213], v[22:25]
	v_mfma_f32_16x16x32_bf16 v[18:21], v[158:161], v[210:213], v[18:21]
	v_mfma_f32_16x16x32_bf16 v[6:9], v[150:153], v[218:221], v[6:9]
	v_mfma_f32_16x16x32_bf16 v[2:5], v[158:161], v[218:221], v[2:5]
	s_setprio 0
	s_barrier
	s_add_i32 s94, 0, 0x18000
	v_add_u32_e32 v0, s94, v243
	s_add_i32 s95, 0, 0x1c000
	ds_read_b128 v[82:85], v0
	ds_read_b128 v[90:93], v0 offset:1024
	ds_read_b128 v[98:101], v0 offset:2048
	ds_read_b128 v[110:113], v0 offset:3072
	v_add_u32_e32 v0, s95, v243
	ds_read_b128 v[146:149], v0
	ds_read_b128 v[150:153], v0 offset:1024
	ds_read_b128 v[154:157], v0 offset:2048
	ds_read_b128 v[158:161], v0 offset:3072
	s_add_u32 s70, s70, 0x100000
	s_addc_u32 s71, s71, 0
	s_mov_b32 m0, s67
	ds_read_b128 v[162:165], v244 offset:32768
	ds_read_b128 v[166:169], v244 offset:33792
	ds_read_b128 v[170:173], v244 offset:34816
	ds_read_b128 v[202:205], v244 offset:35840
	ds_read_b128 v[206:209], v244 offset:36864
	ds_read_b128 v[210:213], v244 offset:37888
	ds_read_b128 v[214:217], v244 offset:38912
	ds_read_b128 v[218:221], v244 offset:39936
	s_nop 0
	v_lshl_add_u64 v[222:223], s[70:71], 0, v[194:195]
	global_load_lds_dwordx4 v[222:223], off
	v_lshl_add_u64 v[222:223], s[70:71], 0, v[198:199]
	s_mov_b32 m0, s68
	s_nop 0
	global_load_lds_dwordx4 v[222:223], off
	s_waitcnt vmcnt(8)
	s_waitcnt lgkmcnt(0)
	s_barrier
	s_setprio 1
	s_waitcnt lgkmcnt(0)
	v_mfma_f32_16x16x32_bf16 v[138:141], v[82:85], v[162:165], v[138:141]
	v_mfma_f32_16x16x32_bf16 v[142:145], v[98:101], v[162:165], v[142:145]
	v_mfma_f32_16x16x32_bf16 v[126:129], v[82:85], v[170:173], v[126:129]
	v_mfma_f32_16x16x32_bf16 v[122:125], v[98:101], v[170:173], v[122:125]
	v_mfma_f32_16x16x32_bf16 v[106:109], v[82:85], v[206:209], v[106:109]
	v_mfma_f32_16x16x32_bf16 v[102:105], v[98:101], v[206:209], v[102:105]
	v_mfma_f32_16x16x32_bf16 v[78:81], v[82:85], v[214:217], v[78:81]
	v_mfma_f32_16x16x32_bf16 v[74:77], v[98:101], v[214:217], v[74:77]
	v_mfma_f32_16x16x32_bf16 v[138:141], v[90:93], v[166:169], v[138:141]
	v_mfma_f32_16x16x32_bf16 v[142:145], v[110:113], v[166:169], v[142:145]
	v_mfma_f32_16x16x32_bf16 v[126:129], v[90:93], v[202:205], v[126:129]
	v_mfma_f32_16x16x32_bf16 v[122:125], v[110:113], v[202:205], v[122:125]
	v_mfma_f32_16x16x32_bf16 v[106:109], v[90:93], v[210:213], v[106:109]
	v_mfma_f32_16x16x32_bf16 v[102:105], v[110:113], v[210:213], v[102:105]
	v_mfma_f32_16x16x32_bf16 v[78:81], v[90:93], v[218:221], v[78:81]
	v_mfma_f32_16x16x32_bf16 v[74:77], v[110:113], v[218:221], v[74:77]
	v_mfma_f32_16x16x32_bf16 v[134:137], v[146:149], v[162:165], v[134:137]
	v_mfma_f32_16x16x32_bf16 v[130:133], v[154:157], v[162:165], v[130:133]
	v_mfma_f32_16x16x32_bf16 v[118:121], v[146:149], v[170:173], v[118:121]
	v_mfma_f32_16x16x32_bf16 v[114:117], v[154:157], v[170:173], v[114:117]
	v_mfma_f32_16x16x32_bf16 v[94:97], v[146:149], v[206:209], v[94:97]
	v_mfma_f32_16x16x32_bf16 v[86:89], v[154:157], v[206:209], v[86:89]
	v_mfma_f32_16x16x32_bf16 v[70:73], v[146:149], v[214:217], v[70:73]
	v_mfma_f32_16x16x32_bf16 v[66:69], v[154:157], v[214:217], v[66:69]
	v_mfma_f32_16x16x32_bf16 v[134:137], v[150:153], v[166:169], v[134:137]
	v_mfma_f32_16x16x32_bf16 v[130:133], v[158:161], v[166:169], v[130:133]
	v_mfma_f32_16x16x32_bf16 v[118:121], v[150:153], v[202:205], v[118:121]
	v_mfma_f32_16x16x32_bf16 v[114:117], v[158:161], v[202:205], v[114:117]
	v_mfma_f32_16x16x32_bf16 v[94:97], v[150:153], v[210:213], v[94:97]
	v_mfma_f32_16x16x32_bf16 v[86:89], v[158:161], v[210:213], v[86:89]
	v_mfma_f32_16x16x32_bf16 v[70:73], v[150:153], v[218:221], v[70:73]
	v_mfma_f32_16x16x32_bf16 v[66:69], v[158:161], v[218:221], v[66:69]
	s_setprio 0
	s_barrier
	s_add_u32 s70, s18, 0x80
	s_addc_u32 s71, s19, 0
	s_add_i32 s94, s94, s25
	ds_read_b128 v[162:165], v244 offset:49152
	ds_read_b128 v[166:169], v244 offset:50176
	ds_read_b128 v[170:173], v244 offset:51200
	ds_read_b128 v[202:205], v244 offset:52224
	ds_read_b128 v[206:209], v244 offset:53248
	ds_read_b128 v[210:213], v244 offset:54272
	ds_read_b128 v[214:217], v244 offset:55296
	ds_read_b128 v[218:221], v244 offset:56320
	s_mov_b32 m0, s94
	v_lshl_add_u64 v[222:223], s[70:71], 0, v[196:197]
	global_load_lds_dwordx4 v[222:223], off
	s_add_i32 m0, s94, 0x2000
	s_add_u32 s18, s18, 0x100080
	v_lshl_add_u64 v[222:223], s[70:71], 0, v[200:201]
	s_addc_u32 s19, s19, 0
	s_add_i32 s70, s95, s25
	global_load_lds_dwordx4 v[222:223], off
	s_mov_b32 m0, s70
	v_lshl_add_u64 v[222:223], s[18:19], 0, v[196:197]
	global_load_lds_dwordx4 v[222:223], off
	v_lshl_add_u64 v[222:223], s[18:19], 0, v[200:201]
	s_add_i32 m0, s70, 0x2000
	s_nop 0
	global_load_lds_dwordx4 v[222:223], off
	s_mov_b32 m0, s84
	v_lshl_add_u64 v[222:223], s[26:27], 0, v[194:195]
	global_load_lds_dwordx4 v[222:223], off
	v_lshl_add_u64 v[222:223], s[26:27], 0, v[198:199]
	s_mov_b32 m0, s85
	s_nop 0
	global_load_lds_dwordx4 v[222:223], off
	s_waitcnt vmcnt(8)
	s_waitcnt lgkmcnt(0)
	s_barrier
	s_setprio 1
	s_waitcnt lgkmcnt(0)
	v_mfma_f32_16x16x32_bf16 v[62:65], v[82:85], v[162:165], v[62:65]
	v_mfma_f32_16x16x32_bf16 v[58:61], v[98:101], v[162:165], v[58:61]
	v_mfma_f32_16x16x32_bf16 v[46:49], v[82:85], v[170:173], v[46:49]
	v_mfma_f32_16x16x32_bf16 v[42:45], v[98:101], v[170:173], v[42:45]
	v_mfma_f32_16x16x32_bf16 v[30:33], v[82:85], v[206:209], v[30:33]
	v_mfma_f32_16x16x32_bf16 v[26:29], v[98:101], v[206:209], v[26:29]
	v_mfma_f32_16x16x32_bf16 v[14:17], v[82:85], v[214:217], v[14:17]
	v_mfma_f32_16x16x32_bf16 v[10:13], v[98:101], v[214:217], v[10:13]
	v_mfma_f32_16x16x32_bf16 v[62:65], v[90:93], v[166:169], v[62:65]
	v_mfma_f32_16x16x32_bf16 v[58:61], v[110:113], v[166:169], v[58:61]
	v_mfma_f32_16x16x32_bf16 v[46:49], v[90:93], v[202:205], v[46:49]
	v_mfma_f32_16x16x32_bf16 v[42:45], v[110:113], v[202:205], v[42:45]
	v_mfma_f32_16x16x32_bf16 v[30:33], v[90:93], v[210:213], v[30:33]
	v_mfma_f32_16x16x32_bf16 v[26:29], v[110:113], v[210:213], v[26:29]
	v_mfma_f32_16x16x32_bf16 v[14:17], v[90:93], v[218:221], v[14:17]
	v_mfma_f32_16x16x32_bf16 v[10:13], v[110:113], v[218:221], v[10:13]
	v_mfma_f32_16x16x32_bf16 v[54:57], v[146:149], v[162:165], v[54:57]
	v_mfma_f32_16x16x32_bf16 v[50:53], v[154:157], v[162:165], v[50:53]
	v_mfma_f32_16x16x32_bf16 v[38:41], v[146:149], v[170:173], v[38:41]
	v_mfma_f32_16x16x32_bf16 v[34:37], v[154:157], v[170:173], v[34:37]
	v_mfma_f32_16x16x32_bf16 v[22:25], v[146:149], v[206:209], v[22:25]
	v_mfma_f32_16x16x32_bf16 v[18:21], v[154:157], v[206:209], v[18:21]
	v_mfma_f32_16x16x32_bf16 v[6:9], v[146:149], v[214:217], v[6:9]
	v_mfma_f32_16x16x32_bf16 v[2:5], v[154:157], v[214:217], v[2:5]
	v_mfma_f32_16x16x32_bf16 v[54:57], v[150:153], v[166:169], v[54:57]
	v_mfma_f32_16x16x32_bf16 v[50:53], v[158:161], v[166:169], v[50:53]
	v_mfma_f32_16x16x32_bf16 v[38:41], v[150:153], v[202:205], v[38:41]
	v_mfma_f32_16x16x32_bf16 v[34:37], v[158:161], v[202:205], v[34:37]
	v_mfma_f32_16x16x32_bf16 v[22:25], v[150:153], v[210:213], v[22:25]
	v_mfma_f32_16x16x32_bf16 v[18:21], v[158:161], v[210:213], v[18:21]
	v_mfma_f32_16x16x32_bf16 v[6:9], v[150:153], v[218:221], v[6:9]
	v_mfma_f32_16x16x32_bf16 v[2:5], v[158:161], v[218:221], v[2:5]
	s_setprio 0
	s_barrier
	s_add_u32 vcc_hi, vcc_hi, 0x100
	s_addc_u32 s90, s90, 0
	s_add_u32 s91, s91, 0x100
	s_addc_u32 s92, s92, 0
	s_add_u32 s42, s42, 0x100
	s_addc_u32 s43, s43, 0
	s_cmp_ge_i32 s93, s83
	s_mov_b32 s18, s93
	s_cbranch_scc0 .LBB0_1494
	s_mov_b32 s97, s66
	s_mov_b32 s66, s24
	s_movk_i32 s24, 0x1000
	s_movk_i32 s90, 0x80
	s_mov_b32 s91, 0x10000
	s_mov_b32 s92, 0x12000
	s_mov_b32 s93, 0x14000
	s_mov_b32 s94, 0x16000
	s_movk_i32 s95, 0x4000
	s_movk_i32 s96, 0x3000

.LBB0_1550:
	s_add_i32 s44, s18, 2
	s_add_u32 s19, s30, 0xf7800080
	s_addc_u32 s26, s31, -1
	s_cmp_lg_u32 s41, s18
	s_cselect_b32 s18, s19, 0
	s_cselect_b32 s45, s26, 0
	s_add_u32 s34, s2, s18
	s_addc_u32 s35, s3, s45
	s_add_u32 s26, s34, 0x80
	s_addc_u32 s27, s35, 0
	s_add_i32 s50, 0, 0x10000
	s_add_u32 s18, s0, s18
	s_addc_u32 s19, s1, s45
	s_add_i32 s45, 0, 0x14000
	v_add_u32_e32 v146, s50, v132
	v_add_u32_e32 v162, s45, v132
	ds_read_b128 v[134:137], v146
	ds_read_b128 v[138:141], v146 offset:1024
	ds_read_b128 v[142:145], v146 offset:2048
	ds_read_b128 v[146:149], v146 offset:3072
	ds_read_b128 v[150:153], v162
	ds_read_b128 v[154:157], v162 offset:1024
	ds_read_b128 v[158:161], v162 offset:2048
	ds_read_b128 v[162:165], v162 offset:3072
	s_add_u32 s48, s42, s30
	s_addc_u32 s49, s43, s31
	s_add_u32 s48, s48, 0x100000
	s_addc_u32 s49, s49, 0
	ds_read_b128 v[166:169], v133
	ds_read_b128 v[170:173], v133 offset:1024
	ds_read_b128 v[194:197], v133 offset:2048
	ds_read_b128 v[198:201], v133 offset:3072
	ds_read_b128 v[202:205], v133 offset:4096
	ds_read_b128 v[206:209], v133 offset:5120
	ds_read_b128 v[210:213], v133 offset:6144
	ds_read_b128 v[214:217], v133 offset:7168
	s_add_i32 m0, s16, 0xc000
	v_lshl_add_u64 v[218:219], s[48:49], 0, v[0:1]
	global_load_lds_dwordx4 v[218:219], off
	v_lshl_add_u64 v[218:219], s[48:49], 0, v[130:131]
	s_add_i32 m0, s16, 0xe000
	s_nop 0
	global_load_lds_dwordx4 v[218:219], off
	s_waitcnt vmcnt(8)
	s_waitcnt lgkmcnt(0)
	s_barrier
	s_setprio 1
	s_waitcnt lgkmcnt(0)
	v_mfma_f32_16x16x32_bf16 v[126:129], v[134:137], v[166:169], v[126:129]
	v_mfma_f32_16x16x32_bf16 v[122:125], v[142:145], v[166:169], v[122:125]
	v_mfma_f32_16x16x32_bf16 v[110:113], v[134:137], v[194:197], v[110:113]
	v_mfma_f32_16x16x32_bf16 v[106:109], v[142:145], v[194:197], v[106:109]
	v_mfma_f32_16x16x32_bf16 v[94:97], v[134:137], v[202:205], v[94:97]
	v_mfma_f32_16x16x32_bf16 v[90:93], v[142:145], v[202:205], v[90:93]
	v_mfma_f32_16x16x32_bf16 v[78:81], v[134:137], v[210:213], v[78:81]
	v_mfma_f32_16x16x32_bf16 v[74:77], v[142:145], v[210:213], v[74:77]
	v_mfma_f32_16x16x32_bf16 v[126:129], v[138:141], v[170:173], v[126:129]
	v_mfma_f32_16x16x32_bf16 v[122:125], v[146:149], v[170:173], v[122:125]
	v_mfma_f32_16x16x32_bf16 v[110:113], v[138:141], v[198:201], v[110:113]
	v_mfma_f32_16x16x32_bf16 v[106:109], v[146:149], v[198:201], v[106:109]
	v_mfma_f32_16x16x32_bf16 v[94:97], v[138:141], v[206:209], v[94:97]
	v_mfma_f32_16x16x32_bf16 v[90:93], v[146:149], v[206:209], v[90:93]
	v_mfma_f32_16x16x32_bf16 v[78:81], v[138:141], v[214:217], v[78:81]
	v_mfma_f32_16x16x32_bf16 v[74:77], v[146:149], v[214:217], v[74:77]
	v_mfma_f32_16x16x32_bf16 v[118:121], v[150:153], v[166:169], v[118:121]
	v_mfma_f32_16x16x32_bf16 v[114:117], v[158:161], v[166:169], v[114:117]
	v_mfma_f32_16x16x32_bf16 v[102:105], v[150:153], v[194:197], v[102:105]
	v_mfma_f32_16x16x32_bf16 v[98:101], v[158:161], v[194:197], v[98:101]
	v_mfma_f32_16x16x32_bf16 v[86:89], v[150:153], v[202:205], v[86:89]
	v_mfma_f32_16x16x32_bf16 v[82:85], v[158:161], v[202:205], v[82:85]
	v_mfma_f32_16x16x32_bf16 v[70:73], v[150:153], v[210:213], v[70:73]
	v_mfma_f32_16x16x32_bf16 v[66:69], v[158:161], v[210:213], v[66:69]
	v_mfma_f32_16x16x32_bf16 v[118:121], v[154:157], v[170:173], v[118:121]
	v_mfma_f32_16x16x32_bf16 v[114:117], v[162:165], v[170:173], v[114:117]
	v_mfma_f32_16x16x32_bf16 v[102:105], v[154:157], v[198:201], v[102:105]
	v_mfma_f32_16x16x32_bf16 v[98:101], v[162:165], v[198:201], v[98:101]
	v_mfma_f32_16x16x32_bf16 v[86:89], v[154:157], v[206:209], v[86:89]
	v_mfma_f32_16x16x32_bf16 v[82:85], v[162:165], v[206:209], v[82:85]
	v_mfma_f32_16x16x32_bf16 v[70:73], v[154:157], v[214:217], v[70:73]
	v_mfma_f32_16x16x32_bf16 v[66:69], v[162:165], v[214:217], v[66:69]
	s_setprio 0
	s_barrier
	s_mov_b64 s[48:49], s[18:19]
	s_add_i32 s50, s50, s36
	ds_read_b128 v[166:169], v133 offset:16384
	ds_read_b128 v[170:173], v133 offset:17408
	ds_read_b128 v[194:197], v133 offset:18432
	ds_read_b128 v[198:201], v133 offset:19456
	ds_read_b128 v[202:205], v133 offset:20480
	ds_read_b128 v[206:209], v133 offset:21504
	ds_read_b128 v[210:213], v133 offset:22528
	ds_read_b128 v[214:217], v133 offset:23552
	s_mov_b32 m0, s50
	v_lshl_add_u64 v[218:219], s[48:49], 0, v[0:1]
	global_load_lds_dwordx4 v[218:219], off
	s_add_i32 m0, s50, 0x2000
	v_lshl_add_u64 v[218:219], s[48:49], 0, v[130:131]
	s_add_u32 s48, s18, 0x100000
	s_addc_u32 s49, s19, 0
	s_add_i32 s45, s45, s36
	global_load_lds_dwordx4 v[218:219], off
	s_mov_b32 m0, s45
	v_lshl_add_u64 v[218:219], s[48:49], 0, v[0:1]
	global_load_lds_dwordx4 v[218:219], off
	v_lshl_add_u64 v[218:219], s[48:49], 0, v[130:131]
	s_add_i32 m0, s45, 0x2000
	s_mov_b64 s[48:49], s[34:35]
	global_load_lds_dwordx4 v[218:219], off
	s_mov_b32 m0, s16
	v_lshl_add_u64 v[218:219], s[48:49], 0, v[0:1]
	global_load_lds_dwordx4 v[218:219], off
	v_lshl_add_u64 v[218:219], s[48:49], 0, v[130:131]
	s_mov_b32 m0, s17
	s_nop 0
	global_load_lds_dwordx4 v[218:219], off
	s_waitcnt vmcnt(8)
	s_waitcnt lgkmcnt(0)
	s_barrier
	s_setprio 1
	s_waitcnt lgkmcnt(0)
	v_mfma_f32_16x16x32_bf16 v[62:65], v[134:137], v[166:169], v[62:65]
	v_mfma_f32_16x16x32_bf16 v[58:61], v[142:145], v[166:169], v[58:61]
	v_mfma_f32_16x16x32_bf16 v[46:49], v[134:137], v[194:197], v[46:49]
	v_mfma_f32_16x16x32_bf16 v[42:45], v[142:145], v[194:197], v[42:45]
	v_mfma_f32_16x16x32_bf16 v[30:33], v[134:137], v[202:205], v[30:33]
	v_mfma_f32_16x16x32_bf16 v[26:29], v[142:145], v[202:205], v[26:29]
	v_mfma_f32_16x16x32_bf16 v[14:17], v[134:137], v[210:213], v[14:17]
	v_mfma_f32_16x16x32_bf16 v[10:13], v[142:145], v[210:213], v[10:13]
	v_mfma_f32_16x16x32_bf16 v[62:65], v[138:141], v[170:173], v[62:65]
	v_mfma_f32_16x16x32_bf16 v[58:61], v[146:149], v[170:173], v[58:61]
	v_mfma_f32_16x16x32_bf16 v[46:49], v[138:141], v[198:201], v[46:49]
	v_mfma_f32_16x16x32_bf16 v[42:45], v[146:149], v[198:201], v[42:45]
	v_mfma_f32_16x16x32_bf16 v[30:33], v[138:141], v[206:209], v[30:33]
	v_mfma_f32_16x16x32_bf16 v[26:29], v[146:149], v[206:209], v[26:29]
	v_mfma_f32_16x16x32_bf16 v[14:17], v[138:141], v[214:217], v[14:17]
	v_mfma_f32_16x16x32_bf16 v[10:13], v[146:149], v[214:217], v[10:13]
	v_mfma_f32_16x16x32_bf16 v[54:57], v[150:153], v[166:169], v[54:57]
	v_mfma_f32_16x16x32_bf16 v[50:53], v[158:161], v[166:169], v[50:53]
	v_mfma_f32_16x16x32_bf16 v[38:41], v[150:153], v[194:197], v[38:41]
	v_mfma_f32_16x16x32_bf16 v[34:37], v[158:161], v[194:197], v[34:37]
	v_mfma_f32_16x16x32_bf16 v[22:25], v[150:153], v[202:205], v[22:25]
	v_mfma_f32_16x16x32_bf16 v[18:21], v[158:161], v[202:205], v[18:21]
	v_mfma_f32_16x16x32_bf16 v[6:9], v[150:153], v[210:213], v[6:9]
	v_mfma_f32_16x16x32_bf16 v[2:5], v[158:161], v[210:213], v[2:5]
	v_mfma_f32_16x16x32_bf16 v[54:57], v[154:157], v[170:173], v[54:57]
	v_mfma_f32_16x16x32_bf16 v[50:53], v[162:165], v[170:173], v[50:53]
	v_mfma_f32_16x16x32_bf16 v[38:41], v[154:157], v[198:201], v[38:41]
	v_mfma_f32_16x16x32_bf16 v[34:37], v[162:165], v[198:201], v[34:37]
	v_mfma_f32_16x16x32_bf16 v[22:25], v[154:157], v[206:209], v[22:25]
	v_mfma_f32_16x16x32_bf16 v[18:21], v[162:165], v[206:209], v[18:21]
	v_mfma_f32_16x16x32_bf16 v[6:9], v[154:157], v[214:217], v[6:9]
	v_mfma_f32_16x16x32_bf16 v[2:5], v[162:165], v[214:217], v[2:5]
	s_setprio 0
	s_barrier
	s_add_i32 s45, 0, 0x18000
	s_add_i32 s48, 0, 0x1c000
	v_add_u32_e32 v146, s45, v132
	v_add_u32_e32 v162, s48, v132
	ds_read_b128 v[134:137], v146
	ds_read_b128 v[138:141], v146 offset:1024
	ds_read_b128 v[142:145], v146 offset:2048
	ds_read_b128 v[146:149], v146 offset:3072
	ds_read_b128 v[150:153], v162
	ds_read_b128 v[154:157], v162 offset:1024
	ds_read_b128 v[158:161], v162 offset:2048
	ds_read_b128 v[162:165], v162 offset:3072
	s_add_u32 s34, s34, 0x100000
	s_addc_u32 s35, s35, 0
	s_mov_b32 m0, s21
	ds_read_b128 v[166:169], v133 offset:32768
	ds_read_b128 v[170:173], v133 offset:33792
	ds_read_b128 v[194:197], v133 offset:34816
	ds_read_b128 v[198:201], v133 offset:35840
	ds_read_b128 v[202:205], v133 offset:36864
	ds_read_b128 v[206:209], v133 offset:37888
	ds_read_b128 v[210:213], v133 offset:38912
	ds_read_b128 v[214:217], v133 offset:39936
	s_nop 0
	v_lshl_add_u64 v[218:219], s[34:35], 0, v[0:1]
	global_load_lds_dwordx4 v[218:219], off
	v_lshl_add_u64 v[218:219], s[34:35], 0, v[130:131]
	s_mov_b32 m0, s22
	s_nop 0
	global_load_lds_dwordx4 v[218:219], off
	s_waitcnt vmcnt(8)
	s_waitcnt lgkmcnt(0)
	s_barrier
	s_setprio 1
	s_waitcnt lgkmcnt(0)
	v_mfma_f32_16x16x32_bf16 v[126:129], v[134:137], v[166:169], v[126:129]
	v_mfma_f32_16x16x32_bf16 v[122:125], v[142:145], v[166:169], v[122:125]
	v_mfma_f32_16x16x32_bf16 v[110:113], v[134:137], v[194:197], v[110:113]
	v_mfma_f32_16x16x32_bf16 v[106:109], v[142:145], v[194:197], v[106:109]
	v_mfma_f32_16x16x32_bf16 v[94:97], v[134:137], v[202:205], v[94:97]
	v_mfma_f32_16x16x32_bf16 v[90:93], v[142:145], v[202:205], v[90:93]
	v_mfma_f32_16x16x32_bf16 v[78:81], v[134:137], v[210:213], v[78:81]
	v_mfma_f32_16x16x32_bf16 v[74:77], v[142:145], v[210:213], v[74:77]
	v_mfma_f32_16x16x32_bf16 v[126:129], v[138:141], v[170:173], v[126:129]
	v_mfma_f32_16x16x32_bf16 v[122:125], v[146:149], v[170:173], v[122:125]
	v_mfma_f32_16x16x32_bf16 v[110:113], v[138:141], v[198:201], v[110:113]
	v_mfma_f32_16x16x32_bf16 v[106:109], v[146:149], v[198:201], v[106:109]
	v_mfma_f32_16x16x32_bf16 v[94:97], v[138:141], v[206:209], v[94:97]
	v_mfma_f32_16x16x32_bf16 v[90:93], v[146:149], v[206:209], v[90:93]
	v_mfma_f32_16x16x32_bf16 v[78:81], v[138:141], v[214:217], v[78:81]
	v_mfma_f32_16x16x32_bf16 v[74:77], v[146:149], v[214:217], v[74:77]
	v_mfma_f32_16x16x32_bf16 v[118:121], v[150:153], v[166:169], v[118:121]
	v_mfma_f32_16x16x32_bf16 v[114:117], v[158:161], v[166:169], v[114:117]
	v_mfma_f32_16x16x32_bf16 v[102:105], v[150:153], v[194:197], v[102:105]
	v_mfma_f32_16x16x32_bf16 v[98:101], v[158:161], v[194:197], v[98:101]
	v_mfma_f32_16x16x32_bf16 v[86:89], v[150:153], v[202:205], v[86:89]
	v_mfma_f32_16x16x32_bf16 v[82:85], v[158:161], v[202:205], v[82:85]
	v_mfma_f32_16x16x32_bf16 v[70:73], v[150:153], v[210:213], v[70:73]
	v_mfma_f32_16x16x32_bf16 v[66:69], v[158:161], v[210:213], v[66:69]
	v_mfma_f32_16x16x32_bf16 v[118:121], v[154:157], v[170:173], v[118:121]
	v_mfma_f32_16x16x32_bf16 v[114:117], v[162:165], v[170:173], v[114:117]
	v_mfma_f32_16x16x32_bf16 v[102:105], v[154:157], v[198:201], v[102:105]
	v_mfma_f32_16x16x32_bf16 v[98:101], v[162:165], v[198:201], v[98:101]
	v_mfma_f32_16x16x32_bf16 v[86:89], v[154:157], v[206:209], v[86:89]
	v_mfma_f32_16x16x32_bf16 v[82:85], v[162:165], v[206:209], v[82:85]
	v_mfma_f32_16x16x32_bf16 v[70:73], v[154:157], v[214:217], v[70:73]
	v_mfma_f32_16x16x32_bf16 v[66:69], v[162:165], v[214:217], v[66:69]
	s_setprio 0
	s_barrier
	s_add_u32 s34, s18, 0x80
	s_addc_u32 s35, s19, 0
	s_add_i32 s45, s45, s36
	ds_read_b128 v[166:169], v133 offset:49152
	ds_read_b128 v[170:173], v133 offset:50176
	ds_read_b128 v[194:197], v133 offset:51200
	ds_read_b128 v[198:201], v133 offset:52224
	ds_read_b128 v[202:205], v133 offset:53248
	ds_read_b128 v[206:209], v133 offset:54272
	ds_read_b128 v[210:213], v133 offset:55296
	ds_read_b128 v[214:217], v133 offset:56320
	s_mov_b32 m0, s45
	v_lshl_add_u64 v[218:219], s[34:35], 0, v[0:1]
	global_load_lds_dwordx4 v[218:219], off
	s_add_i32 m0, s45, 0x2000
	s_add_u32 s18, s18, 0x100080
	v_lshl_add_u64 v[218:219], s[34:35], 0, v[130:131]
	s_addc_u32 s19, s19, 0
	s_add_i32 s34, s48, s36
	global_load_lds_dwordx4 v[218:219], off
	s_mov_b32 m0, s34
	v_lshl_add_u64 v[218:219], s[18:19], 0, v[0:1]
	global_load_lds_dwordx4 v[218:219], off
	v_lshl_add_u64 v[218:219], s[18:19], 0, v[130:131]
	s_add_i32 m0, s34, 0x2000
	s_nop 0
	global_load_lds_dwordx4 v[218:219], off
	s_mov_b32 m0, s37
	v_lshl_add_u64 v[218:219], s[26:27], 0, v[0:1]
	global_load_lds_dwordx4 v[218:219], off
	v_lshl_add_u64 v[218:219], s[26:27], 0, v[130:131]
	s_mov_b32 m0, s39
	s_nop 0
	global_load_lds_dwordx4 v[218:219], off
	s_waitcnt vmcnt(8)
	s_waitcnt lgkmcnt(0)
	s_barrier
	s_setprio 1
	s_waitcnt lgkmcnt(0)
	v_mfma_f32_16x16x32_bf16 v[62:65], v[134:137], v[166:169], v[62:65]
	v_mfma_f32_16x16x32_bf16 v[58:61], v[142:145], v[166:169], v[58:61]
	v_mfma_f32_16x16x32_bf16 v[46:49], v[134:137], v[194:197], v[46:49]
	v_mfma_f32_16x16x32_bf16 v[42:45], v[142:145], v[194:197], v[42:45]
	v_mfma_f32_16x16x32_bf16 v[30:33], v[134:137], v[202:205], v[30:33]
	v_mfma_f32_16x16x32_bf16 v[26:29], v[142:145], v[202:205], v[26:29]
	v_mfma_f32_16x16x32_bf16 v[14:17], v[134:137], v[210:213], v[14:17]
	v_mfma_f32_16x16x32_bf16 v[10:13], v[142:145], v[210:213], v[10:13]
	v_mfma_f32_16x16x32_bf16 v[62:65], v[138:141], v[170:173], v[62:65]
	v_mfma_f32_16x16x32_bf16 v[58:61], v[146:149], v[170:173], v[58:61]
	v_mfma_f32_16x16x32_bf16 v[46:49], v[138:141], v[198:201], v[46:49]
	v_mfma_f32_16x16x32_bf16 v[42:45], v[146:149], v[198:201], v[42:45]
	v_mfma_f32_16x16x32_bf16 v[30:33], v[138:141], v[206:209], v[30:33]
	v_mfma_f32_16x16x32_bf16 v[26:29], v[146:149], v[206:209], v[26:29]
	v_mfma_f32_16x16x32_bf16 v[14:17], v[138:141], v[214:217], v[14:17]
	v_mfma_f32_16x16x32_bf16 v[10:13], v[146:149], v[214:217], v[10:13]
	v_mfma_f32_16x16x32_bf16 v[54:57], v[150:153], v[166:169], v[54:57]
	v_mfma_f32_16x16x32_bf16 v[50:53], v[158:161], v[166:169], v[50:53]
	v_mfma_f32_16x16x32_bf16 v[38:41], v[150:153], v[194:197], v[38:41]
	v_mfma_f32_16x16x32_bf16 v[34:37], v[158:161], v[194:197], v[34:37]
	v_mfma_f32_16x16x32_bf16 v[22:25], v[150:153], v[202:205], v[22:25]
	v_mfma_f32_16x16x32_bf16 v[18:21], v[158:161], v[202:205], v[18:21]
	v_mfma_f32_16x16x32_bf16 v[6:9], v[150:153], v[210:213], v[6:9]
	v_mfma_f32_16x16x32_bf16 v[2:5], v[158:161], v[210:213], v[2:5]
	v_mfma_f32_16x16x32_bf16 v[54:57], v[154:157], v[170:173], v[54:57]
	v_mfma_f32_16x16x32_bf16 v[50:53], v[162:165], v[170:173], v[50:53]
	v_mfma_f32_16x16x32_bf16 v[38:41], v[154:157], v[198:201], v[38:41]
	v_mfma_f32_16x16x32_bf16 v[34:37], v[162:165], v[198:201], v[34:37]
	v_mfma_f32_16x16x32_bf16 v[22:25], v[154:157], v[206:209], v[22:25]
	v_mfma_f32_16x16x32_bf16 v[18:21], v[162:165], v[206:209], v[18:21]
	v_mfma_f32_16x16x32_bf16 v[6:9], v[154:157], v[214:217], v[6:9]
	v_mfma_f32_16x16x32_bf16 v[2:5], v[162:165], v[214:217], v[2:5]
	s_setprio 0
	s_barrier
	s_add_u32 s30, s30, 0x100
	s_addc_u32 s31, s31, 0
	s_cmp_ge_i32 s44, s40
	s_mov_b32 s18, s44
	s_cbranch_scc0 .LBB0_1550
